# m_comb chunk scan software-pipelined: groups of 16 loads kept two groups ahead of the group being processed (fully unrolled)
# baseline (speedup 1.0000x reference)
; DI unsigned pk2(float lo, float hi) { f32x2 v = {lo, hi}; bf16x2_t b = __builtin_convertvector(v, bf16x2_t); return __builtin_bit_cast(unsigned, b); }
; DI float bflo(unsigned u) { return __uint_as_float(u << 16); }
; DI float bfhi(unsigned u) { return __uint_as_float(u & 0xffff0000u); }
; DI void phase_m_comb(int wv, const ArgP a, LAS unsigned char* lds, int dry) {
;     ...
;     for (int eb = blockIdx.x; eb < 129; eb += gridDim.x) {
;         if (eb < 128) { const int h = eb >> 5; unsigned* p = (unsigned*)(CST + (size_t)h * 32768 + (size_t)(eb & 31) * 1024 + 2 * tid); float C0 = 0.f, C1 = 0.f;
;             for (int c = 0; c < 256; c += 64) { unsigned d[64];
; #pragma unroll
;                 for (int k = 0; k < 64; ++k) d[k] = p[(size_t)(c + k) * 65536];
; #pragma unroll
;                 for (int k = 0; k < 64; ++k) { if (!dry) p[(size_t)(c + k) * 65536] = pk2(C0, C1); const float a_ = ga[(c + k) * 4 + h], b_ = gb[(c + k) * 4 + h]; C0 = a_ * C0 + b_ * bflo(d[k]); C1 = a_ * C1 + b_ * bfhi(d[k]); } }
.LBB0_1543:
	s_cmpk_lg_i32 s13, 0x80
	s_mov_b64 s[0:1], -1
	s_cbranch_scc0 .LBB0_1547
	s_ashr_i32 s8, s13, 5
	s_ashr_i32 s9, s8, 31
	s_lshl_b64 s[0:1], s[8:9], 16
	s_add_u32 s0, s10, s0
	s_addc_u32 s1, s11, s1
	s_lshl_b32 s2, s13, 11
	s_and_b32 s2, s2, 0xf800
	s_add_u32 s0, s0, s2
	s_addc_u32 s1, s1, 0
	v_lshlrev_b32_e32 v116, 1, v0
	s_mov_b64 s[14:15], s[0:1]
	s_mov_b64 s[16:17], s[0:1]
	s_lshl_b32 s2, s8, 2
	s_add_i32 s18, s2, 0x2000
	s_add_i32 s19, s2, 0x3000
	v_mov_b32_e32 v8, 0
	v_mov_b32_e32 v9, 0
	v_mov_b32_e32 v118, s18
	v_mov_b32_e32 v119, s19
	global_load_dword v140, v116, s[14:15]
	s_add_u32 s14, s14, 0x40000
	s_addc_u32 s15, s15, 0
	global_load_dword v141, v116, s[14:15]
	s_add_u32 s14, s14, 0x40000
	s_addc_u32 s15, s15, 0
	global_load_dword v142, v116, s[14:15]
	s_add_u32 s14, s14, 0x40000
	s_addc_u32 s15, s15, 0
	global_load_dword v143, v116, s[14:15]
	s_add_u32 s14, s14, 0x40000
	s_addc_u32 s15, s15, 0
	global_load_dword v144, v116, s[14:15]
	s_add_u32 s14, s14, 0x40000
	s_addc_u32 s15, s15, 0
	global_load_dword v145, v116, s[14:15]
	s_add_u32 s14, s14, 0x40000
	s_addc_u32 s15, s15, 0
	global_load_dword v146, v116, s[14:15]
	s_add_u32 s14, s14, 0x40000
	s_addc_u32 s15, s15, 0
	global_load_dword v147, v116, s[14:15]
	s_add_u32 s14, s14, 0x40000
	s_addc_u32 s15, s15, 0
	global_load_dword v148, v116, s[14:15]
	s_add_u32 s14, s14, 0x40000
	s_addc_u32 s15, s15, 0
	global_load_dword v149, v116, s[14:15]
	s_add_u32 s14, s14, 0x40000
	s_addc_u32 s15, s15, 0
	global_load_dword v150, v116, s[14:15]
	s_add_u32 s14, s14, 0x40000
	s_addc_u32 s15, s15, 0
	global_load_dword v151, v116, s[14:15]
	s_add_u32 s14, s14, 0x40000
	s_addc_u32 s15, s15, 0
	global_load_dword v152, v116, s[14:15]
	s_add_u32 s14, s14, 0x40000
	s_addc_u32 s15, s15, 0
	global_load_dword v153, v116, s[14:15]
	s_add_u32 s14, s14, 0x40000
	s_addc_u32 s15, s15, 0
	global_load_dword v154, v116, s[14:15]
	s_add_u32 s14, s14, 0x40000
	s_addc_u32 s15, s15, 0
	global_load_dword v155, v116, s[14:15]
	s_add_u32 s14, s14, 0x40000
	s_addc_u32 s15, s15, 0
	global_load_dword v156, v116, s[14:15]
	s_add_u32 s14, s14, 0x40000
	s_addc_u32 s15, s15, 0
	global_load_dword v157, v116, s[14:15]
	s_add_u32 s14, s14, 0x40000
	s_addc_u32 s15, s15, 0
	global_load_dword v158, v116, s[14:15]
	s_add_u32 s14, s14, 0x40000
	s_addc_u32 s15, s15, 0
	global_load_dword v159, v116, s[14:15]
	s_add_u32 s14, s14, 0x40000
	s_addc_u32 s15, s15, 0
	global_load_dword v160, v116, s[14:15]
	s_add_u32 s14, s14, 0x40000
	s_addc_u32 s15, s15, 0
	global_load_dword v161, v116, s[14:15]
	s_add_u32 s14, s14, 0x40000
	s_addc_u32 s15, s15, 0
	global_load_dword v162, v116, s[14:15]
	s_add_u32 s14, s14, 0x40000
	s_addc_u32 s15, s15, 0
	global_load_dword v163, v116, s[14:15]
	s_add_u32 s14, s14, 0x40000
	s_addc_u32 s15, s15, 0
	global_load_dword v164, v116, s[14:15]
	s_add_u32 s14, s14, 0x40000
	s_addc_u32 s15, s15, 0
	global_load_dword v165, v116, s[14:15]
	s_add_u32 s14, s14, 0x40000
	s_addc_u32 s15, s15, 0
	global_load_dword v166, v116, s[14:15]
	s_add_u32 s14, s14, 0x40000
	s_addc_u32 s15, s15, 0
	global_load_dword v167, v116, s[14:15]
	s_add_u32 s14, s14, 0x40000
	s_addc_u32 s15, s15, 0
	global_load_dword v168, v116, s[14:15]
	s_add_u32 s14, s14, 0x40000
	s_addc_u32 s15, s15, 0
	global_load_dword v169, v116, s[14:15]
	s_add_u32 s14, s14, 0x40000
	s_addc_u32 s15, s15, 0
	global_load_dword v170, v116, s[14:15]
	s_add_u32 s14, s14, 0x40000
	s_addc_u32 s15, s15, 0
	global_load_dword v171, v116, s[14:15]
	s_add_u32 s14, s14, 0x40000
	s_addc_u32 s15, s15, 0
	ds_read2_b32 v[12:13], v118 offset0:0 offset1:4
	ds_read2_b32 v[76:77], v119 offset0:0 offset1:4
	ds_read2_b32 v[14:15], v118 offset0:8 offset1:12
	ds_read2_b32 v[78:79], v119 offset0:8 offset1:12
	ds_read2_b32 v[16:17], v118 offset0:16 offset1:20
	ds_read2_b32 v[80:81], v119 offset0:16 offset1:20
	ds_read2_b32 v[18:19], v118 offset0:24 offset1:28
	ds_read2_b32 v[82:83], v119 offset0:24 offset1:28
	s_waitcnt lgkmcnt(0)
	ds_read2_b32 v[20:21], v118 offset0:32 offset1:36
	ds_read2_b32 v[84:85], v119 offset0:32 offset1:36
	ds_read2_b32 v[22:23], v118 offset0:40 offset1:44
	ds_read2_b32 v[86:87], v119 offset0:40 offset1:44
	ds_read2_b32 v[24:25], v118 offset0:48 offset1:52
	ds_read2_b32 v[88:89], v119 offset0:48 offset1:52
	ds_read2_b32 v[26:27], v118 offset0:56 offset1:60
	ds_read2_b32 v[90:91], v119 offset0:56 offset1:60
	s_waitcnt lgkmcnt(0)
	ds_read2_b32 v[28:29], v118 offset0:64 offset1:68
	ds_read2_b32 v[92:93], v119 offset0:64 offset1:68
	ds_read2_b32 v[30:31], v118 offset0:72 offset1:76
	ds_read2_b32 v[94:95], v119 offset0:72 offset1:76
	ds_read2_b32 v[32:33], v118 offset0:80 offset1:84
	ds_read2_b32 v[96:97], v119 offset0:80 offset1:84
	ds_read2_b32 v[34:35], v118 offset0:88 offset1:92
	ds_read2_b32 v[98:99], v119 offset0:88 offset1:92
	s_waitcnt lgkmcnt(0)
	ds_read2_b32 v[36:37], v118 offset0:96 offset1:100
	ds_read2_b32 v[100:101], v119 offset0:96 offset1:100
	ds_read2_b32 v[38:39], v118 offset0:104 offset1:108
	ds_read2_b32 v[102:103], v119 offset0:104 offset1:108
	ds_read2_b32 v[40:41], v118 offset0:112 offset1:116
	ds_read2_b32 v[104:105], v119 offset0:112 offset1:116
	ds_read2_b32 v[42:43], v118 offset0:120 offset1:124
	ds_read2_b32 v[106:107], v119 offset0:120 offset1:124
	s_waitcnt lgkmcnt(0)
	ds_read2_b32 v[44:45], v118 offset0:128 offset1:132
	ds_read2_b32 v[108:109], v119 offset0:128 offset1:132
	ds_read2_b32 v[46:47], v118 offset0:136 offset1:140
	ds_read2_b32 v[110:111], v119 offset0:136 offset1:140
	ds_read2_b32 v[48:49], v118 offset0:144 offset1:148
	ds_read2_b32 v[112:113], v119 offset0:144 offset1:148
	ds_read2_b32 v[50:51], v118 offset0:152 offset1:156
	ds_read2_b32 v[114:115], v119 offset0:152 offset1:156
	s_waitcnt lgkmcnt(0)
; DI unsigned pk2(float lo, float hi) { f32x2 v = {lo, hi}; bf16x2_t b = __builtin_convertvector(v, bf16x2_t); return __builtin_bit_cast(unsigned, b); }
; DI float bflo(unsigned u) { return __uint_as_float(u << 16); }
; DI float bfhi(unsigned u) { return __uint_as_float(u & 0xffff0000u); }
; DI void phase_m_comb(int wv, const ArgP a, LAS unsigned char* lds, int dry) {
;     ...
;             for (int c = 0; c < 256; c += 64) { unsigned d[64];
; #pragma unroll
;                 for (int k = 0; k < 64; ++k) d[k] = p[(size_t)(c + k) * 65536];
; #pragma unroll
;                 for (int k = 0; k < 64; ++k) { if (!dry) p[(size_t)(c + k) * 65536] = pk2(C0, C1); const float a_ = ga[(c + k) * 4 + h], b_ = gb[(c + k) * 4 + h]; C0 = a_ * C0 + b_ * bflo(d[k]); C1 = a_ * C1 + b_ * bfhi(d[k]); } }
	ds_read2_b32 v[52:53], v118 offset0:160 offset1:164
	ds_read2_b32 v[208:209], v119 offset0:160 offset1:164
	ds_read2_b32 v[54:55], v118 offset0:168 offset1:172
	ds_read2_b32 v[210:211], v119 offset0:168 offset1:172
	ds_read2_b32 v[56:57], v118 offset0:176 offset1:180
	ds_read2_b32 v[212:213], v119 offset0:176 offset1:180
	ds_read2_b32 v[58:59], v118 offset0:184 offset1:188
	ds_read2_b32 v[214:215], v119 offset0:184 offset1:188
	s_waitcnt lgkmcnt(0)
	ds_read2_b32 v[60:61], v118 offset0:192 offset1:196
	ds_read2_b32 v[216:217], v119 offset0:192 offset1:196
	ds_read2_b32 v[62:63], v118 offset0:200 offset1:204
	ds_read2_b32 v[218:219], v119 offset0:200 offset1:204
	ds_read2_b32 v[64:65], v118 offset0:208 offset1:212
	ds_read2_b32 v[220:221], v119 offset0:208 offset1:212
	ds_read2_b32 v[66:67], v118 offset0:216 offset1:220
	ds_read2_b32 v[222:223], v119 offset0:216 offset1:220
	s_waitcnt lgkmcnt(0)
	ds_read2_b32 v[68:69], v118 offset0:224 offset1:228
	ds_read2_b32 v[224:225], v119 offset0:224 offset1:228
	ds_read2_b32 v[70:71], v118 offset0:232 offset1:236
	ds_read2_b32 v[226:227], v119 offset0:232 offset1:236
	ds_read2_b32 v[72:73], v118 offset0:240 offset1:244
	ds_read2_b32 v[228:229], v119 offset0:240 offset1:244
	ds_read2_b32 v[74:75], v118 offset0:248 offset1:252
	ds_read2_b32 v[230:231], v119 offset0:248 offset1:252
	s_waitcnt lgkmcnt(0)
	s_waitcnt vmcnt(31)
	v_cvt_pk_bf16_f32 v122, v8, v9
	v_lshlrev_b32_e32 v120, 16, v140
	v_and_b32_e32 v121, 0xffff0000, v140
	global_store_dword v116, v122, s[16:17]
	s_add_u32 s16, s16, 0x40000
	s_addc_u32 s17, s17, 0
	v_pk_mul_f32 v[120:121], v[76:77], v[120:121] op_sel_hi:[0,1]
	v_pk_fma_f32 v[8:9], v[8:9], v[12:13], v[120:121] op_sel_hi:[1,0,1]
	s_waitcnt vmcnt(31)
	v_cvt_pk_bf16_f32 v123, v8, v9
	v_lshlrev_b32_e32 v120, 16, v141
	v_and_b32_e32 v121, 0xffff0000, v141
	global_store_dword v116, v123, s[16:17]
	s_add_u32 s16, s16, 0x40000
	s_addc_u32 s17, s17, 0
	v_pk_mul_f32 v[120:121], v[76:77], v[120:121] op_sel:[1,0] op_sel_hi:[1,1]
	v_pk_fma_f32 v[8:9], v[8:9], v[12:13], v[120:121] op_sel:[0,1,0] op_sel_hi:[1,1,1]
	s_waitcnt vmcnt(31)
	v_cvt_pk_bf16_f32 v122, v8, v9
	v_lshlrev_b32_e32 v120, 16, v142
	v_and_b32_e32 v121, 0xffff0000, v142
	global_store_dword v116, v122, s[16:17]
	s_add_u32 s16, s16, 0x40000
	s_addc_u32 s17, s17, 0
	v_pk_mul_f32 v[120:121], v[78:79], v[120:121] op_sel_hi:[0,1]
	v_pk_fma_f32 v[8:9], v[8:9], v[14:15], v[120:121] op_sel_hi:[1,0,1]
	s_waitcnt vmcnt(31)
	v_cvt_pk_bf16_f32 v123, v8, v9
	v_lshlrev_b32_e32 v120, 16, v143
	v_and_b32_e32 v121, 0xffff0000, v143
	global_store_dword v116, v123, s[16:17]
	s_add_u32 s16, s16, 0x40000
	s_addc_u32 s17, s17, 0
	v_pk_mul_f32 v[120:121], v[78:79], v[120:121] op_sel:[1,0] op_sel_hi:[1,1]
	v_pk_fma_f32 v[8:9], v[8:9], v[14:15], v[120:121] op_sel:[0,1,0] op_sel_hi:[1,1,1]
	s_waitcnt vmcnt(31)
	v_cvt_pk_bf16_f32 v122, v8, v9
	v_lshlrev_b32_e32 v120, 16, v144
	v_and_b32_e32 v121, 0xffff0000, v144
	global_store_dword v116, v122, s[16:17]
	s_add_u32 s16, s16, 0x40000
	s_addc_u32 s17, s17, 0
	v_pk_mul_f32 v[120:121], v[80:81], v[120:121] op_sel_hi:[0,1]
	v_pk_fma_f32 v[8:9], v[8:9], v[16:17], v[120:121] op_sel_hi:[1,0,1]
	s_waitcnt vmcnt(31)
	v_cvt_pk_bf16_f32 v123, v8, v9
	v_lshlrev_b32_e32 v120, 16, v145
	v_and_b32_e32 v121, 0xffff0000, v145
	global_store_dword v116, v123, s[16:17]
	s_add_u32 s16, s16, 0x40000
	s_addc_u32 s17, s17, 0
	v_pk_mul_f32 v[120:121], v[80:81], v[120:121] op_sel:[1,0] op_sel_hi:[1,1]
	v_pk_fma_f32 v[8:9], v[8:9], v[16:17], v[120:121] op_sel:[0,1,0] op_sel_hi:[1,1,1]
	s_waitcnt vmcnt(31)
	v_cvt_pk_bf16_f32 v122, v8, v9
	v_lshlrev_b32_e32 v120, 16, v146
	v_and_b32_e32 v121, 0xffff0000, v146
	global_store_dword v116, v122, s[16:17]
	s_add_u32 s16, s16, 0x40000
	s_addc_u32 s17, s17, 0
	v_pk_mul_f32 v[120:121], v[82:83], v[120:121] op_sel_hi:[0,1]
	v_pk_fma_f32 v[8:9], v[8:9], v[18:19], v[120:121] op_sel_hi:[1,0,1]
	s_waitcnt vmcnt(31)
	v_cvt_pk_bf16_f32 v123, v8, v9
	v_lshlrev_b32_e32 v120, 16, v147
	v_and_b32_e32 v121, 0xffff0000, v147
	global_store_dword v116, v123, s[16:17]
	s_add_u32 s16, s16, 0x40000
	s_addc_u32 s17, s17, 0
	v_pk_mul_f32 v[120:121], v[82:83], v[120:121] op_sel:[1,0] op_sel_hi:[1,1]
	v_pk_fma_f32 v[8:9], v[8:9], v[18:19], v[120:121] op_sel:[0,1,0] op_sel_hi:[1,1,1]
	s_waitcnt vmcnt(31)
	v_cvt_pk_bf16_f32 v122, v8, v9
	v_lshlrev_b32_e32 v120, 16, v148
	v_and_b32_e32 v121, 0xffff0000, v148
	global_store_dword v116, v122, s[16:17]
	s_add_u32 s16, s16, 0x40000
	s_addc_u32 s17, s17, 0
	v_pk_mul_f32 v[120:121], v[84:85], v[120:121] op_sel_hi:[0,1]
	v_pk_fma_f32 v[8:9], v[8:9], v[20:21], v[120:121] op_sel_hi:[1,0,1]
	s_waitcnt vmcnt(31)
	v_cvt_pk_bf16_f32 v123, v8, v9
	v_lshlrev_b32_e32 v120, 16, v149
	v_and_b32_e32 v121, 0xffff0000, v149
	global_store_dword v116, v123, s[16:17]
	s_add_u32 s16, s16, 0x40000
	s_addc_u32 s17, s17, 0
	v_pk_mul_f32 v[120:121], v[84:85], v[120:121] op_sel:[1,0] op_sel_hi:[1,1]
	v_pk_fma_f32 v[8:9], v[8:9], v[20:21], v[120:121] op_sel:[0,1,0] op_sel_hi:[1,1,1]
	s_waitcnt vmcnt(31)
	v_cvt_pk_bf16_f32 v122, v8, v9
	v_lshlrev_b32_e32 v120, 16, v150
	v_and_b32_e32 v121, 0xffff0000, v150
	global_store_dword v116, v122, s[16:17]
	s_add_u32 s16, s16, 0x40000
	s_addc_u32 s17, s17, 0
	v_pk_mul_f32 v[120:121], v[86:87], v[120:121] op_sel_hi:[0,1]
	v_pk_fma_f32 v[8:9], v[8:9], v[22:23], v[120:121] op_sel_hi:[1,0,1]
	s_waitcnt vmcnt(31)
	v_cvt_pk_bf16_f32 v123, v8, v9
	v_lshlrev_b32_e32 v120, 16, v151
	v_and_b32_e32 v121, 0xffff0000, v151
	global_store_dword v116, v123, s[16:17]
	s_add_u32 s16, s16, 0x40000
	s_addc_u32 s17, s17, 0
	v_pk_mul_f32 v[120:121], v[86:87], v[120:121] op_sel:[1,0] op_sel_hi:[1,1]
	v_pk_fma_f32 v[8:9], v[8:9], v[22:23], v[120:121] op_sel:[0,1,0] op_sel_hi:[1,1,1]
	s_waitcnt vmcnt(31)
; DI unsigned pk2(float lo, float hi) { f32x2 v = {lo, hi}; bf16x2_t b = __builtin_convertvector(v, bf16x2_t); return __builtin_bit_cast(unsigned, b); }
; DI float bflo(unsigned u) { return __uint_as_float(u << 16); }
; DI float bfhi(unsigned u) { return __uint_as_float(u & 0xffff0000u); }
; DI void phase_m_comb(int wv, const ArgP a, LAS unsigned char* lds, int dry) {
;     ...
;             for (int c = 0; c < 256; c += 64) { unsigned d[64];
; #pragma unroll
;                 for (int k = 0; k < 64; ++k) d[k] = p[(size_t)(c + k) * 65536];
; #pragma unroll
;                 for (int k = 0; k < 64; ++k) { if (!dry) p[(size_t)(c + k) * 65536] = pk2(C0, C1); const float a_ = ga[(c + k) * 4 + h], b_ = gb[(c + k) * 4 + h]; C0 = a_ * C0 + b_ * bflo(d[k]); C1 = a_ * C1 + b_ * bfhi(d[k]); } }
	v_cvt_pk_bf16_f32 v122, v8, v9
	v_lshlrev_b32_e32 v120, 16, v152
	v_and_b32_e32 v121, 0xffff0000, v152
	global_store_dword v116, v122, s[16:17]
	s_add_u32 s16, s16, 0x40000
	s_addc_u32 s17, s17, 0
	v_pk_mul_f32 v[120:121], v[88:89], v[120:121] op_sel_hi:[0,1]
	v_pk_fma_f32 v[8:9], v[8:9], v[24:25], v[120:121] op_sel_hi:[1,0,1]
	s_waitcnt vmcnt(31)
	v_cvt_pk_bf16_f32 v123, v8, v9
	v_lshlrev_b32_e32 v120, 16, v153
	v_and_b32_e32 v121, 0xffff0000, v153
	global_store_dword v116, v123, s[16:17]
	s_add_u32 s16, s16, 0x40000
	s_addc_u32 s17, s17, 0
	v_pk_mul_f32 v[120:121], v[88:89], v[120:121] op_sel:[1,0] op_sel_hi:[1,1]
	v_pk_fma_f32 v[8:9], v[8:9], v[24:25], v[120:121] op_sel:[0,1,0] op_sel_hi:[1,1,1]
	s_waitcnt vmcnt(31)
	v_cvt_pk_bf16_f32 v122, v8, v9
	v_lshlrev_b32_e32 v120, 16, v154
	v_and_b32_e32 v121, 0xffff0000, v154
	global_store_dword v116, v122, s[16:17]
	s_add_u32 s16, s16, 0x40000
	s_addc_u32 s17, s17, 0
	v_pk_mul_f32 v[120:121], v[90:91], v[120:121] op_sel_hi:[0,1]
	v_pk_fma_f32 v[8:9], v[8:9], v[26:27], v[120:121] op_sel_hi:[1,0,1]
	s_waitcnt vmcnt(31)
	v_cvt_pk_bf16_f32 v123, v8, v9
	v_lshlrev_b32_e32 v120, 16, v155
	v_and_b32_e32 v121, 0xffff0000, v155
	global_store_dword v116, v123, s[16:17]
	s_add_u32 s16, s16, 0x40000
	s_addc_u32 s17, s17, 0
	v_pk_mul_f32 v[120:121], v[90:91], v[120:121] op_sel:[1,0] op_sel_hi:[1,1]
	v_pk_fma_f32 v[8:9], v[8:9], v[26:27], v[120:121] op_sel:[0,1,0] op_sel_hi:[1,1,1]
	global_load_dword v172, v116, s[14:15]
	s_add_u32 s14, s14, 0x40000
	s_addc_u32 s15, s15, 0
	global_load_dword v173, v116, s[14:15]
	s_add_u32 s14, s14, 0x40000
	s_addc_u32 s15, s15, 0
	global_load_dword v174, v116, s[14:15]
	s_add_u32 s14, s14, 0x40000
	s_addc_u32 s15, s15, 0
	global_load_dword v175, v116, s[14:15]
	s_add_u32 s14, s14, 0x40000
	s_addc_u32 s15, s15, 0
	global_load_dword v176, v116, s[14:15]
	s_add_u32 s14, s14, 0x40000
	s_addc_u32 s15, s15, 0
	global_load_dword v177, v116, s[14:15]
	s_add_u32 s14, s14, 0x40000
	s_addc_u32 s15, s15, 0
	global_load_dword v178, v116, s[14:15]
	s_add_u32 s14, s14, 0x40000
	s_addc_u32 s15, s15, 0
	global_load_dword v179, v116, s[14:15]
	s_add_u32 s14, s14, 0x40000
	s_addc_u32 s15, s15, 0
	global_load_dword v180, v116, s[14:15]
	s_add_u32 s14, s14, 0x40000
	s_addc_u32 s15, s15, 0
	global_load_dword v181, v116, s[14:15]
	s_add_u32 s14, s14, 0x40000
	s_addc_u32 s15, s15, 0
	global_load_dword v182, v116, s[14:15]
	s_add_u32 s14, s14, 0x40000
	s_addc_u32 s15, s15, 0
	global_load_dword v183, v116, s[14:15]
	s_add_u32 s14, s14, 0x40000
	s_addc_u32 s15, s15, 0
	global_load_dword v184, v116, s[14:15]
	s_add_u32 s14, s14, 0x40000
	s_addc_u32 s15, s15, 0
	global_load_dword v185, v116, s[14:15]
	s_add_u32 s14, s14, 0x40000
	s_addc_u32 s15, s15, 0
	global_load_dword v186, v116, s[14:15]
	s_add_u32 s14, s14, 0x40000
	s_addc_u32 s15, s15, 0
	global_load_dword v187, v116, s[14:15]
	s_add_u32 s14, s14, 0x40000
	s_addc_u32 s15, s15, 0
	s_waitcnt vmcnt(47)
	v_cvt_pk_bf16_f32 v122, v8, v9
	v_lshlrev_b32_e32 v120, 16, v156
	v_and_b32_e32 v121, 0xffff0000, v156
	global_store_dword v116, v122, s[16:17]
	s_add_u32 s16, s16, 0x40000
	s_addc_u32 s17, s17, 0
	v_pk_mul_f32 v[120:121], v[92:93], v[120:121] op_sel_hi:[0,1]
	v_pk_fma_f32 v[8:9], v[8:9], v[28:29], v[120:121] op_sel_hi:[1,0,1]
	s_waitcnt vmcnt(47)
	v_cvt_pk_bf16_f32 v123, v8, v9
	v_lshlrev_b32_e32 v120, 16, v157
	v_and_b32_e32 v121, 0xffff0000, v157
	global_store_dword v116, v123, s[16:17]
	s_add_u32 s16, s16, 0x40000
	s_addc_u32 s17, s17, 0
	v_pk_mul_f32 v[120:121], v[92:93], v[120:121] op_sel:[1,0] op_sel_hi:[1,1]
	v_pk_fma_f32 v[8:9], v[8:9], v[28:29], v[120:121] op_sel:[0,1,0] op_sel_hi:[1,1,1]
	s_waitcnt vmcnt(47)
	v_cvt_pk_bf16_f32 v122, v8, v9
	v_lshlrev_b32_e32 v120, 16, v158
	v_and_b32_e32 v121, 0xffff0000, v158
	global_store_dword v116, v122, s[16:17]
	s_add_u32 s16, s16, 0x40000
	s_addc_u32 s17, s17, 0
	v_pk_mul_f32 v[120:121], v[94:95], v[120:121] op_sel_hi:[0,1]
	v_pk_fma_f32 v[8:9], v[8:9], v[30:31], v[120:121] op_sel_hi:[1,0,1]
	s_waitcnt vmcnt(47)
	v_cvt_pk_bf16_f32 v123, v8, v9
	v_lshlrev_b32_e32 v120, 16, v159
	v_and_b32_e32 v121, 0xffff0000, v159
	global_store_dword v116, v123, s[16:17]
	s_add_u32 s16, s16, 0x40000
	s_addc_u32 s17, s17, 0
	v_pk_mul_f32 v[120:121], v[94:95], v[120:121] op_sel:[1,0] op_sel_hi:[1,1]
	v_pk_fma_f32 v[8:9], v[8:9], v[30:31], v[120:121] op_sel:[0,1,0] op_sel_hi:[1,1,1]
	s_waitcnt vmcnt(47)
	v_cvt_pk_bf16_f32 v122, v8, v9
	v_lshlrev_b32_e32 v120, 16, v160
	v_and_b32_e32 v121, 0xffff0000, v160
	global_store_dword v116, v122, s[16:17]
	s_add_u32 s16, s16, 0x40000
	s_addc_u32 s17, s17, 0
	v_pk_mul_f32 v[120:121], v[96:97], v[120:121] op_sel_hi:[0,1]
	v_pk_fma_f32 v[8:9], v[8:9], v[32:33], v[120:121] op_sel_hi:[1,0,1]
	s_waitcnt vmcnt(47)
	v_cvt_pk_bf16_f32 v123, v8, v9
	v_lshlrev_b32_e32 v120, 16, v161
	v_and_b32_e32 v121, 0xffff0000, v161
	global_store_dword v116, v123, s[16:17]
	s_add_u32 s16, s16, 0x40000
	s_addc_u32 s17, s17, 0
	v_pk_mul_f32 v[120:121], v[96:97], v[120:121] op_sel:[1,0] op_sel_hi:[1,1]
	v_pk_fma_f32 v[8:9], v[8:9], v[32:33], v[120:121] op_sel:[0,1,0] op_sel_hi:[1,1,1]
	s_waitcnt vmcnt(47)
	v_cvt_pk_bf16_f32 v122, v8, v9
	v_lshlrev_b32_e32 v120, 16, v162
	v_and_b32_e32 v121, 0xffff0000, v162
	global_store_dword v116, v122, s[16:17]
	s_add_u32 s16, s16, 0x40000
	s_addc_u32 s17, s17, 0
	v_pk_mul_f32 v[120:121], v[98:99], v[120:121] op_sel_hi:[0,1]
	v_pk_fma_f32 v[8:9], v[8:9], v[34:35], v[120:121] op_sel_hi:[1,0,1]
	s_waitcnt vmcnt(47)
; DI unsigned pk2(float lo, float hi) { f32x2 v = {lo, hi}; bf16x2_t b = __builtin_convertvector(v, bf16x2_t); return __builtin_bit_cast(unsigned, b); }
; DI float bflo(unsigned u) { return __uint_as_float(u << 16); }
; DI float bfhi(unsigned u) { return __uint_as_float(u & 0xffff0000u); }
; DI void phase_m_comb(int wv, const ArgP a, LAS unsigned char* lds, int dry) {
;     ...
;             for (int c = 0; c < 256; c += 64) { unsigned d[64];
; #pragma unroll
;                 for (int k = 0; k < 64; ++k) d[k] = p[(size_t)(c + k) * 65536];
; #pragma unroll
;                 for (int k = 0; k < 64; ++k) { if (!dry) p[(size_t)(c + k) * 65536] = pk2(C0, C1); const float a_ = ga[(c + k) * 4 + h], b_ = gb[(c + k) * 4 + h]; C0 = a_ * C0 + b_ * bflo(d[k]); C1 = a_ * C1 + b_ * bfhi(d[k]); } }
	v_cvt_pk_bf16_f32 v123, v8, v9
	v_lshlrev_b32_e32 v120, 16, v163
	v_and_b32_e32 v121, 0xffff0000, v163
	global_store_dword v116, v123, s[16:17]
	s_add_u32 s16, s16, 0x40000
	s_addc_u32 s17, s17, 0
	v_pk_mul_f32 v[120:121], v[98:99], v[120:121] op_sel:[1,0] op_sel_hi:[1,1]
	v_pk_fma_f32 v[8:9], v[8:9], v[34:35], v[120:121] op_sel:[0,1,0] op_sel_hi:[1,1,1]
	s_waitcnt vmcnt(47)
	v_cvt_pk_bf16_f32 v122, v8, v9
	v_lshlrev_b32_e32 v120, 16, v164
	v_and_b32_e32 v121, 0xffff0000, v164
	global_store_dword v116, v122, s[16:17]
	s_add_u32 s16, s16, 0x40000
	s_addc_u32 s17, s17, 0
	v_pk_mul_f32 v[120:121], v[100:101], v[120:121] op_sel_hi:[0,1]
	v_pk_fma_f32 v[8:9], v[8:9], v[36:37], v[120:121] op_sel_hi:[1,0,1]
	s_waitcnt vmcnt(47)
	v_cvt_pk_bf16_f32 v123, v8, v9
	v_lshlrev_b32_e32 v120, 16, v165
	v_and_b32_e32 v121, 0xffff0000, v165
	global_store_dword v116, v123, s[16:17]
	s_add_u32 s16, s16, 0x40000
	s_addc_u32 s17, s17, 0
	v_pk_mul_f32 v[120:121], v[100:101], v[120:121] op_sel:[1,0] op_sel_hi:[1,1]
	v_pk_fma_f32 v[8:9], v[8:9], v[36:37], v[120:121] op_sel:[0,1,0] op_sel_hi:[1,1,1]
	s_waitcnt vmcnt(47)
	v_cvt_pk_bf16_f32 v122, v8, v9
	v_lshlrev_b32_e32 v120, 16, v166
	v_and_b32_e32 v121, 0xffff0000, v166
	global_store_dword v116, v122, s[16:17]
	s_add_u32 s16, s16, 0x40000
	s_addc_u32 s17, s17, 0
	v_pk_mul_f32 v[120:121], v[102:103], v[120:121] op_sel_hi:[0,1]
	v_pk_fma_f32 v[8:9], v[8:9], v[38:39], v[120:121] op_sel_hi:[1,0,1]
	s_waitcnt vmcnt(47)
	v_cvt_pk_bf16_f32 v123, v8, v9
	v_lshlrev_b32_e32 v120, 16, v167
	v_and_b32_e32 v121, 0xffff0000, v167
	global_store_dword v116, v123, s[16:17]
	s_add_u32 s16, s16, 0x40000
	s_addc_u32 s17, s17, 0
	v_pk_mul_f32 v[120:121], v[102:103], v[120:121] op_sel:[1,0] op_sel_hi:[1,1]
	v_pk_fma_f32 v[8:9], v[8:9], v[38:39], v[120:121] op_sel:[0,1,0] op_sel_hi:[1,1,1]
	s_waitcnt vmcnt(47)
	v_cvt_pk_bf16_f32 v122, v8, v9
	v_lshlrev_b32_e32 v120, 16, v168
	v_and_b32_e32 v121, 0xffff0000, v168
	global_store_dword v116, v122, s[16:17]
	s_add_u32 s16, s16, 0x40000
	s_addc_u32 s17, s17, 0
	v_pk_mul_f32 v[120:121], v[104:105], v[120:121] op_sel_hi:[0,1]
	v_pk_fma_f32 v[8:9], v[8:9], v[40:41], v[120:121] op_sel_hi:[1,0,1]
	s_waitcnt vmcnt(47)
	v_cvt_pk_bf16_f32 v123, v8, v9
	v_lshlrev_b32_e32 v120, 16, v169
	v_and_b32_e32 v121, 0xffff0000, v169
	global_store_dword v116, v123, s[16:17]
	s_add_u32 s16, s16, 0x40000
	s_addc_u32 s17, s17, 0
	v_pk_mul_f32 v[120:121], v[104:105], v[120:121] op_sel:[1,0] op_sel_hi:[1,1]
	v_pk_fma_f32 v[8:9], v[8:9], v[40:41], v[120:121] op_sel:[0,1,0] op_sel_hi:[1,1,1]
	s_waitcnt vmcnt(47)
	v_cvt_pk_bf16_f32 v122, v8, v9
	v_lshlrev_b32_e32 v120, 16, v170
	v_and_b32_e32 v121, 0xffff0000, v170
	global_store_dword v116, v122, s[16:17]
	s_add_u32 s16, s16, 0x40000
	s_addc_u32 s17, s17, 0
	v_pk_mul_f32 v[120:121], v[106:107], v[120:121] op_sel_hi:[0,1]
	v_pk_fma_f32 v[8:9], v[8:9], v[42:43], v[120:121] op_sel_hi:[1,0,1]
	s_waitcnt vmcnt(47)
	v_cvt_pk_bf16_f32 v123, v8, v9
	v_lshlrev_b32_e32 v120, 16, v171
	v_and_b32_e32 v121, 0xffff0000, v171
	global_store_dword v116, v123, s[16:17]
	s_add_u32 s16, s16, 0x40000
	s_addc_u32 s17, s17, 0
	v_pk_mul_f32 v[120:121], v[106:107], v[120:121] op_sel:[1,0] op_sel_hi:[1,1]
	v_pk_fma_f32 v[8:9], v[8:9], v[42:43], v[120:121] op_sel:[0,1,0] op_sel_hi:[1,1,1]
	global_load_dword v140, v116, s[14:15]
	s_add_u32 s14, s14, 0x40000
	s_addc_u32 s15, s15, 0
	global_load_dword v141, v116, s[14:15]
	s_add_u32 s14, s14, 0x40000
	s_addc_u32 s15, s15, 0
	global_load_dword v142, v116, s[14:15]
	s_add_u32 s14, s14, 0x40000
	s_addc_u32 s15, s15, 0
	global_load_dword v143, v116, s[14:15]
	s_add_u32 s14, s14, 0x40000
	s_addc_u32 s15, s15, 0
	global_load_dword v144, v116, s[14:15]
	s_add_u32 s14, s14, 0x40000
	s_addc_u32 s15, s15, 0
	global_load_dword v145, v116, s[14:15]
	s_add_u32 s14, s14, 0x40000
	s_addc_u32 s15, s15, 0
	global_load_dword v146, v116, s[14:15]
	s_add_u32 s14, s14, 0x40000
	s_addc_u32 s15, s15, 0
	global_load_dword v147, v116, s[14:15]
	s_add_u32 s14, s14, 0x40000
	s_addc_u32 s15, s15, 0
	global_load_dword v148, v116, s[14:15]
	s_add_u32 s14, s14, 0x40000
	s_addc_u32 s15, s15, 0
	global_load_dword v149, v116, s[14:15]
	s_add_u32 s14, s14, 0x40000
	s_addc_u32 s15, s15, 0
	global_load_dword v150, v116, s[14:15]
	s_add_u32 s14, s14, 0x40000
	s_addc_u32 s15, s15, 0
	global_load_dword v151, v116, s[14:15]
	s_add_u32 s14, s14, 0x40000
	s_addc_u32 s15, s15, 0
	global_load_dword v152, v116, s[14:15]
	s_add_u32 s14, s14, 0x40000
	s_addc_u32 s15, s15, 0
	global_load_dword v153, v116, s[14:15]
	s_add_u32 s14, s14, 0x40000
	s_addc_u32 s15, s15, 0
	global_load_dword v154, v116, s[14:15]
	s_add_u32 s14, s14, 0x40000
	s_addc_u32 s15, s15, 0
	global_load_dword v155, v116, s[14:15]
	s_add_u32 s14, s14, 0x40000
	s_addc_u32 s15, s15, 0
	s_waitcnt vmcnt(47)
	v_cvt_pk_bf16_f32 v122, v8, v9
	v_lshlrev_b32_e32 v120, 16, v172
	v_and_b32_e32 v121, 0xffff0000, v172
	global_store_dword v116, v122, s[16:17]
	s_add_u32 s16, s16, 0x40000
	s_addc_u32 s17, s17, 0
	v_pk_mul_f32 v[120:121], v[108:109], v[120:121] op_sel_hi:[0,1]
	v_pk_fma_f32 v[8:9], v[8:9], v[44:45], v[120:121] op_sel_hi:[1,0,1]
	s_waitcnt vmcnt(47)
	v_cvt_pk_bf16_f32 v123, v8, v9
	v_lshlrev_b32_e32 v120, 16, v173
	v_and_b32_e32 v121, 0xffff0000, v173
	global_store_dword v116, v123, s[16:17]
	s_add_u32 s16, s16, 0x40000
	s_addc_u32 s17, s17, 0
	v_pk_mul_f32 v[120:121], v[108:109], v[120:121] op_sel:[1,0] op_sel_hi:[1,1]
	v_pk_fma_f32 v[8:9], v[8:9], v[44:45], v[120:121] op_sel:[0,1,0] op_sel_hi:[1,1,1]
	s_waitcnt vmcnt(47)
; DI unsigned pk2(float lo, float hi) { f32x2 v = {lo, hi}; bf16x2_t b = __builtin_convertvector(v, bf16x2_t); return __builtin_bit_cast(unsigned, b); }
; DI float bflo(unsigned u) { return __uint_as_float(u << 16); }
; DI float bfhi(unsigned u) { return __uint_as_float(u & 0xffff0000u); }
; DI void phase_m_comb(int wv, const ArgP a, LAS unsigned char* lds, int dry) {
;     ...
;             for (int c = 0; c < 256; c += 64) { unsigned d[64];
; #pragma unroll
;                 for (int k = 0; k < 64; ++k) d[k] = p[(size_t)(c + k) * 65536];
; #pragma unroll
;                 for (int k = 0; k < 64; ++k) { if (!dry) p[(size_t)(c + k) * 65536] = pk2(C0, C1); const float a_ = ga[(c + k) * 4 + h], b_ = gb[(c + k) * 4 + h]; C0 = a_ * C0 + b_ * bflo(d[k]); C1 = a_ * C1 + b_ * bfhi(d[k]); } }
	v_cvt_pk_bf16_f32 v122, v8, v9
	v_lshlrev_b32_e32 v120, 16, v174
	v_and_b32_e32 v121, 0xffff0000, v174
	global_store_dword v116, v122, s[16:17]
	s_add_u32 s16, s16, 0x40000
	s_addc_u32 s17, s17, 0
	v_pk_mul_f32 v[120:121], v[110:111], v[120:121] op_sel_hi:[0,1]
	v_pk_fma_f32 v[8:9], v[8:9], v[46:47], v[120:121] op_sel_hi:[1,0,1]
	s_waitcnt vmcnt(47)
	v_cvt_pk_bf16_f32 v123, v8, v9
	v_lshlrev_b32_e32 v120, 16, v175
	v_and_b32_e32 v121, 0xffff0000, v175
	global_store_dword v116, v123, s[16:17]
	s_add_u32 s16, s16, 0x40000
	s_addc_u32 s17, s17, 0
	v_pk_mul_f32 v[120:121], v[110:111], v[120:121] op_sel:[1,0] op_sel_hi:[1,1]
	v_pk_fma_f32 v[8:9], v[8:9], v[46:47], v[120:121] op_sel:[0,1,0] op_sel_hi:[1,1,1]
	s_waitcnt vmcnt(47)
	v_cvt_pk_bf16_f32 v122, v8, v9
	v_lshlrev_b32_e32 v120, 16, v176
	v_and_b32_e32 v121, 0xffff0000, v176
	global_store_dword v116, v122, s[16:17]
	s_add_u32 s16, s16, 0x40000
	s_addc_u32 s17, s17, 0
	v_pk_mul_f32 v[120:121], v[112:113], v[120:121] op_sel_hi:[0,1]
	v_pk_fma_f32 v[8:9], v[8:9], v[48:49], v[120:121] op_sel_hi:[1,0,1]
	s_waitcnt vmcnt(47)
	v_cvt_pk_bf16_f32 v123, v8, v9
	v_lshlrev_b32_e32 v120, 16, v177
	v_and_b32_e32 v121, 0xffff0000, v177
	global_store_dword v116, v123, s[16:17]
	s_add_u32 s16, s16, 0x40000
	s_addc_u32 s17, s17, 0
	v_pk_mul_f32 v[120:121], v[112:113], v[120:121] op_sel:[1,0] op_sel_hi:[1,1]
	v_pk_fma_f32 v[8:9], v[8:9], v[48:49], v[120:121] op_sel:[0,1,0] op_sel_hi:[1,1,1]
	s_waitcnt vmcnt(47)
	v_cvt_pk_bf16_f32 v122, v8, v9
	v_lshlrev_b32_e32 v120, 16, v178
	v_and_b32_e32 v121, 0xffff0000, v178
	global_store_dword v116, v122, s[16:17]
	s_add_u32 s16, s16, 0x40000
	s_addc_u32 s17, s17, 0
	v_pk_mul_f32 v[120:121], v[114:115], v[120:121] op_sel_hi:[0,1]
	v_pk_fma_f32 v[8:9], v[8:9], v[50:51], v[120:121] op_sel_hi:[1,0,1]
	s_waitcnt vmcnt(47)
	v_cvt_pk_bf16_f32 v123, v8, v9
	v_lshlrev_b32_e32 v120, 16, v179
	v_and_b32_e32 v121, 0xffff0000, v179
	global_store_dword v116, v123, s[16:17]
	s_add_u32 s16, s16, 0x40000
	s_addc_u32 s17, s17, 0
	v_pk_mul_f32 v[120:121], v[114:115], v[120:121] op_sel:[1,0] op_sel_hi:[1,1]
	v_pk_fma_f32 v[8:9], v[8:9], v[50:51], v[120:121] op_sel:[0,1,0] op_sel_hi:[1,1,1]
	s_waitcnt vmcnt(47)
	v_cvt_pk_bf16_f32 v122, v8, v9
	v_lshlrev_b32_e32 v120, 16, v180
	v_and_b32_e32 v121, 0xffff0000, v180
	global_store_dword v116, v122, s[16:17]
	s_add_u32 s16, s16, 0x40000
	s_addc_u32 s17, s17, 0
	v_pk_mul_f32 v[120:121], v[208:209], v[120:121] op_sel_hi:[0,1]
	v_pk_fma_f32 v[8:9], v[8:9], v[52:53], v[120:121] op_sel_hi:[1,0,1]
	s_waitcnt vmcnt(47)
	v_cvt_pk_bf16_f32 v123, v8, v9
	v_lshlrev_b32_e32 v120, 16, v181
	v_and_b32_e32 v121, 0xffff0000, v181
	global_store_dword v116, v123, s[16:17]
	s_add_u32 s16, s16, 0x40000
	s_addc_u32 s17, s17, 0
	v_pk_mul_f32 v[120:121], v[208:209], v[120:121] op_sel:[1,0] op_sel_hi:[1,1]
	v_pk_fma_f32 v[8:9], v[8:9], v[52:53], v[120:121] op_sel:[0,1,0] op_sel_hi:[1,1,1]
	s_waitcnt vmcnt(47)
	v_cvt_pk_bf16_f32 v122, v8, v9
	v_lshlrev_b32_e32 v120, 16, v182
	v_and_b32_e32 v121, 0xffff0000, v182
	global_store_dword v116, v122, s[16:17]
	s_add_u32 s16, s16, 0x40000
	s_addc_u32 s17, s17, 0
	v_pk_mul_f32 v[120:121], v[210:211], v[120:121] op_sel_hi:[0,1]
	v_pk_fma_f32 v[8:9], v[8:9], v[54:55], v[120:121] op_sel_hi:[1,0,1]
	s_waitcnt vmcnt(47)
	v_cvt_pk_bf16_f32 v123, v8, v9
	v_lshlrev_b32_e32 v120, 16, v183
	v_and_b32_e32 v121, 0xffff0000, v183
	global_store_dword v116, v123, s[16:17]
	s_add_u32 s16, s16, 0x40000
	s_addc_u32 s17, s17, 0
	v_pk_mul_f32 v[120:121], v[210:211], v[120:121] op_sel:[1,0] op_sel_hi:[1,1]
	v_pk_fma_f32 v[8:9], v[8:9], v[54:55], v[120:121] op_sel:[0,1,0] op_sel_hi:[1,1,1]
	s_waitcnt vmcnt(47)
	v_cvt_pk_bf16_f32 v122, v8, v9
	v_lshlrev_b32_e32 v120, 16, v184
	v_and_b32_e32 v121, 0xffff0000, v184
	global_store_dword v116, v122, s[16:17]
	s_add_u32 s16, s16, 0x40000
	s_addc_u32 s17, s17, 0
	v_pk_mul_f32 v[120:121], v[212:213], v[120:121] op_sel_hi:[0,1]
	v_pk_fma_f32 v[8:9], v[8:9], v[56:57], v[120:121] op_sel_hi:[1,0,1]
	s_waitcnt vmcnt(47)
	v_cvt_pk_bf16_f32 v123, v8, v9
	v_lshlrev_b32_e32 v120, 16, v185
	v_and_b32_e32 v121, 0xffff0000, v185
	global_store_dword v116, v123, s[16:17]
	s_add_u32 s16, s16, 0x40000
	s_addc_u32 s17, s17, 0
	v_pk_mul_f32 v[120:121], v[212:213], v[120:121] op_sel:[1,0] op_sel_hi:[1,1]
	v_pk_fma_f32 v[8:9], v[8:9], v[56:57], v[120:121] op_sel:[0,1,0] op_sel_hi:[1,1,1]
	s_waitcnt vmcnt(47)
	v_cvt_pk_bf16_f32 v122, v8, v9
	v_lshlrev_b32_e32 v120, 16, v186
	v_and_b32_e32 v121, 0xffff0000, v186
	global_store_dword v116, v122, s[16:17]
	s_add_u32 s16, s16, 0x40000
	s_addc_u32 s17, s17, 0
	v_pk_mul_f32 v[120:121], v[214:215], v[120:121] op_sel_hi:[0,1]
	v_pk_fma_f32 v[8:9], v[8:9], v[58:59], v[120:121] op_sel_hi:[1,0,1]
	s_waitcnt vmcnt(47)
; DI unsigned pk2(float lo, float hi) { f32x2 v = {lo, hi}; bf16x2_t b = __builtin_convertvector(v, bf16x2_t); return __builtin_bit_cast(unsigned, b); }
; DI float bflo(unsigned u) { return __uint_as_float(u << 16); }
; DI float bfhi(unsigned u) { return __uint_as_float(u & 0xffff0000u); }
; DI void phase_m_comb(int wv, const ArgP a, LAS unsigned char* lds, int dry) {
;     ...
;             for (int c = 0; c < 256; c += 64) { unsigned d[64];
; #pragma unroll
;                 for (int k = 0; k < 64; ++k) d[k] = p[(size_t)(c + k) * 65536];
; #pragma unroll
;                 for (int k = 0; k < 64; ++k) { if (!dry) p[(size_t)(c + k) * 65536] = pk2(C0, C1); const float a_ = ga[(c + k) * 4 + h], b_ = gb[(c + k) * 4 + h]; C0 = a_ * C0 + b_ * bflo(d[k]); C1 = a_ * C1 + b_ * bfhi(d[k]); } }
	v_cvt_pk_bf16_f32 v123, v8, v9
	v_lshlrev_b32_e32 v120, 16, v187
	v_and_b32_e32 v121, 0xffff0000, v187
	global_store_dword v116, v123, s[16:17]
	s_add_u32 s16, s16, 0x40000
	s_addc_u32 s17, s17, 0
	v_pk_mul_f32 v[120:121], v[214:215], v[120:121] op_sel:[1,0] op_sel_hi:[1,1]
	v_pk_fma_f32 v[8:9], v[8:9], v[58:59], v[120:121] op_sel:[0,1,0] op_sel_hi:[1,1,1]
	global_load_dword v156, v116, s[14:15]
	s_add_u32 s14, s14, 0x40000
	s_addc_u32 s15, s15, 0
	global_load_dword v157, v116, s[14:15]
	s_add_u32 s14, s14, 0x40000
	s_addc_u32 s15, s15, 0
	global_load_dword v158, v116, s[14:15]
	s_add_u32 s14, s14, 0x40000
	s_addc_u32 s15, s15, 0
	global_load_dword v159, v116, s[14:15]
	s_add_u32 s14, s14, 0x40000
	s_addc_u32 s15, s15, 0
	global_load_dword v160, v116, s[14:15]
	s_add_u32 s14, s14, 0x40000
	s_addc_u32 s15, s15, 0
	global_load_dword v161, v116, s[14:15]
	s_add_u32 s14, s14, 0x40000
	s_addc_u32 s15, s15, 0
	global_load_dword v162, v116, s[14:15]
	s_add_u32 s14, s14, 0x40000
	s_addc_u32 s15, s15, 0
	global_load_dword v163, v116, s[14:15]
	s_add_u32 s14, s14, 0x40000
	s_addc_u32 s15, s15, 0
	global_load_dword v164, v116, s[14:15]
	s_add_u32 s14, s14, 0x40000
	s_addc_u32 s15, s15, 0
	global_load_dword v165, v116, s[14:15]
	s_add_u32 s14, s14, 0x40000
	s_addc_u32 s15, s15, 0
	global_load_dword v166, v116, s[14:15]
	s_add_u32 s14, s14, 0x40000
	s_addc_u32 s15, s15, 0
	global_load_dword v167, v116, s[14:15]
	s_add_u32 s14, s14, 0x40000
	s_addc_u32 s15, s15, 0
	global_load_dword v168, v116, s[14:15]
	s_add_u32 s14, s14, 0x40000
	s_addc_u32 s15, s15, 0
	global_load_dword v169, v116, s[14:15]
	s_add_u32 s14, s14, 0x40000
	s_addc_u32 s15, s15, 0
	global_load_dword v170, v116, s[14:15]
	s_add_u32 s14, s14, 0x40000
	s_addc_u32 s15, s15, 0
	global_load_dword v171, v116, s[14:15]
	s_add_u32 s14, s14, 0x40000
	s_addc_u32 s15, s15, 0
	s_waitcnt vmcnt(47)
	v_cvt_pk_bf16_f32 v122, v8, v9
	v_lshlrev_b32_e32 v120, 16, v140
	v_and_b32_e32 v121, 0xffff0000, v140
	global_store_dword v116, v122, s[16:17]
	s_add_u32 s16, s16, 0x40000
	s_addc_u32 s17, s17, 0
	v_pk_mul_f32 v[120:121], v[216:217], v[120:121] op_sel_hi:[0,1]
	v_pk_fma_f32 v[8:9], v[8:9], v[60:61], v[120:121] op_sel_hi:[1,0,1]
	s_waitcnt vmcnt(47)
	v_cvt_pk_bf16_f32 v123, v8, v9
	v_lshlrev_b32_e32 v120, 16, v141
	v_and_b32_e32 v121, 0xffff0000, v141
	global_store_dword v116, v123, s[16:17]
	s_add_u32 s16, s16, 0x40000
	s_addc_u32 s17, s17, 0
	v_pk_mul_f32 v[120:121], v[216:217], v[120:121] op_sel:[1,0] op_sel_hi:[1,1]
	v_pk_fma_f32 v[8:9], v[8:9], v[60:61], v[120:121] op_sel:[0,1,0] op_sel_hi:[1,1,1]
	s_waitcnt vmcnt(47)
	v_cvt_pk_bf16_f32 v122, v8, v9
	v_lshlrev_b32_e32 v120, 16, v142
	v_and_b32_e32 v121, 0xffff0000, v142
	global_store_dword v116, v122, s[16:17]
	s_add_u32 s16, s16, 0x40000
	s_addc_u32 s17, s17, 0
	v_pk_mul_f32 v[120:121], v[218:219], v[120:121] op_sel_hi:[0,1]
	v_pk_fma_f32 v[8:9], v[8:9], v[62:63], v[120:121] op_sel_hi:[1,0,1]
	s_waitcnt vmcnt(47)
	v_cvt_pk_bf16_f32 v123, v8, v9
	v_lshlrev_b32_e32 v120, 16, v143
	v_and_b32_e32 v121, 0xffff0000, v143
	global_store_dword v116, v123, s[16:17]
	s_add_u32 s16, s16, 0x40000
	s_addc_u32 s17, s17, 0
	v_pk_mul_f32 v[120:121], v[218:219], v[120:121] op_sel:[1,0] op_sel_hi:[1,1]
	v_pk_fma_f32 v[8:9], v[8:9], v[62:63], v[120:121] op_sel:[0,1,0] op_sel_hi:[1,1,1]
	s_waitcnt vmcnt(47)
	v_cvt_pk_bf16_f32 v122, v8, v9
	v_lshlrev_b32_e32 v120, 16, v144
	v_and_b32_e32 v121, 0xffff0000, v144
	global_store_dword v116, v122, s[16:17]
	s_add_u32 s16, s16, 0x40000
	s_addc_u32 s17, s17, 0
	v_pk_mul_f32 v[120:121], v[220:221], v[120:121] op_sel_hi:[0,1]
	v_pk_fma_f32 v[8:9], v[8:9], v[64:65], v[120:121] op_sel_hi:[1,0,1]
	s_waitcnt vmcnt(47)
	v_cvt_pk_bf16_f32 v123, v8, v9
	v_lshlrev_b32_e32 v120, 16, v145
	v_and_b32_e32 v121, 0xffff0000, v145
	global_store_dword v116, v123, s[16:17]
	s_add_u32 s16, s16, 0x40000
	s_addc_u32 s17, s17, 0
	v_pk_mul_f32 v[120:121], v[220:221], v[120:121] op_sel:[1,0] op_sel_hi:[1,1]
	v_pk_fma_f32 v[8:9], v[8:9], v[64:65], v[120:121] op_sel:[0,1,0] op_sel_hi:[1,1,1]
	s_waitcnt vmcnt(47)
	v_cvt_pk_bf16_f32 v122, v8, v9
	v_lshlrev_b32_e32 v120, 16, v146
	v_and_b32_e32 v121, 0xffff0000, v146
	global_store_dword v116, v122, s[16:17]
	s_add_u32 s16, s16, 0x40000
	s_addc_u32 s17, s17, 0
	v_pk_mul_f32 v[120:121], v[222:223], v[120:121] op_sel_hi:[0,1]
	v_pk_fma_f32 v[8:9], v[8:9], v[66:67], v[120:121] op_sel_hi:[1,0,1]
	s_waitcnt vmcnt(47)
	v_cvt_pk_bf16_f32 v123, v8, v9
	v_lshlrev_b32_e32 v120, 16, v147
	v_and_b32_e32 v121, 0xffff0000, v147
	global_store_dword v116, v123, s[16:17]
	s_add_u32 s16, s16, 0x40000
	s_addc_u32 s17, s17, 0
	v_pk_mul_f32 v[120:121], v[222:223], v[120:121] op_sel:[1,0] op_sel_hi:[1,1]
	v_pk_fma_f32 v[8:9], v[8:9], v[66:67], v[120:121] op_sel:[0,1,0] op_sel_hi:[1,1,1]
	s_waitcnt vmcnt(47)
	v_cvt_pk_bf16_f32 v122, v8, v9
	v_lshlrev_b32_e32 v120, 16, v148
	v_and_b32_e32 v121, 0xffff0000, v148
	global_store_dword v116, v122, s[16:17]
	s_add_u32 s16, s16, 0x40000
	s_addc_u32 s17, s17, 0
	v_pk_mul_f32 v[120:121], v[224:225], v[120:121] op_sel_hi:[0,1]
	v_pk_fma_f32 v[8:9], v[8:9], v[68:69], v[120:121] op_sel_hi:[1,0,1]
	s_waitcnt vmcnt(47)
	v_cvt_pk_bf16_f32 v123, v8, v9
	v_lshlrev_b32_e32 v120, 16, v149
	v_and_b32_e32 v121, 0xffff0000, v149
	global_store_dword v116, v123, s[16:17]
	s_add_u32 s16, s16, 0x40000
	s_addc_u32 s17, s17, 0
	v_pk_mul_f32 v[120:121], v[224:225], v[120:121] op_sel:[1,0] op_sel_hi:[1,1]
	v_pk_fma_f32 v[8:9], v[8:9], v[68:69], v[120:121] op_sel:[0,1,0] op_sel_hi:[1,1,1]
	s_waitcnt vmcnt(47)
; DI unsigned pk2(float lo, float hi) { f32x2 v = {lo, hi}; bf16x2_t b = __builtin_convertvector(v, bf16x2_t); return __builtin_bit_cast(unsigned, b); }
; DI float bflo(unsigned u) { return __uint_as_float(u << 16); }
; DI float bfhi(unsigned u) { return __uint_as_float(u & 0xffff0000u); }
; DI void phase_m_comb(int wv, const ArgP a, LAS unsigned char* lds, int dry) {
;     ...
;             for (int c = 0; c < 256; c += 64) { unsigned d[64];
; #pragma unroll
;                 for (int k = 0; k < 64; ++k) d[k] = p[(size_t)(c + k) * 65536];
; #pragma unroll
;                 for (int k = 0; k < 64; ++k) { if (!dry) p[(size_t)(c + k) * 65536] = pk2(C0, C1); const float a_ = ga[(c + k) * 4 + h], b_ = gb[(c + k) * 4 + h]; C0 = a_ * C0 + b_ * bflo(d[k]); C1 = a_ * C1 + b_ * bfhi(d[k]); } }
	v_cvt_pk_bf16_f32 v122, v8, v9
	v_lshlrev_b32_e32 v120, 16, v150
	v_and_b32_e32 v121, 0xffff0000, v150
	global_store_dword v116, v122, s[16:17]
	s_add_u32 s16, s16, 0x40000
	s_addc_u32 s17, s17, 0
	v_pk_mul_f32 v[120:121], v[226:227], v[120:121] op_sel_hi:[0,1]
	v_pk_fma_f32 v[8:9], v[8:9], v[70:71], v[120:121] op_sel_hi:[1,0,1]
	s_waitcnt vmcnt(47)
	v_cvt_pk_bf16_f32 v123, v8, v9
	v_lshlrev_b32_e32 v120, 16, v151
	v_and_b32_e32 v121, 0xffff0000, v151
	global_store_dword v116, v123, s[16:17]
	s_add_u32 s16, s16, 0x40000
	s_addc_u32 s17, s17, 0
	v_pk_mul_f32 v[120:121], v[226:227], v[120:121] op_sel:[1,0] op_sel_hi:[1,1]
	v_pk_fma_f32 v[8:9], v[8:9], v[70:71], v[120:121] op_sel:[0,1,0] op_sel_hi:[1,1,1]
	s_waitcnt vmcnt(47)
	v_cvt_pk_bf16_f32 v122, v8, v9
	v_lshlrev_b32_e32 v120, 16, v152
	v_and_b32_e32 v121, 0xffff0000, v152
	global_store_dword v116, v122, s[16:17]
	s_add_u32 s16, s16, 0x40000
	s_addc_u32 s17, s17, 0
	v_pk_mul_f32 v[120:121], v[228:229], v[120:121] op_sel_hi:[0,1]
	v_pk_fma_f32 v[8:9], v[8:9], v[72:73], v[120:121] op_sel_hi:[1,0,1]
	s_waitcnt vmcnt(47)
	v_cvt_pk_bf16_f32 v123, v8, v9
	v_lshlrev_b32_e32 v120, 16, v153
	v_and_b32_e32 v121, 0xffff0000, v153
	global_store_dword v116, v123, s[16:17]
	s_add_u32 s16, s16, 0x40000
	s_addc_u32 s17, s17, 0
	v_pk_mul_f32 v[120:121], v[228:229], v[120:121] op_sel:[1,0] op_sel_hi:[1,1]
	v_pk_fma_f32 v[8:9], v[8:9], v[72:73], v[120:121] op_sel:[0,1,0] op_sel_hi:[1,1,1]
	s_waitcnt vmcnt(47)
	v_cvt_pk_bf16_f32 v122, v8, v9
	v_lshlrev_b32_e32 v120, 16, v154
	v_and_b32_e32 v121, 0xffff0000, v154
	global_store_dword v116, v122, s[16:17]
	s_add_u32 s16, s16, 0x40000
	s_addc_u32 s17, s17, 0
	v_pk_mul_f32 v[120:121], v[230:231], v[120:121] op_sel_hi:[0,1]
	v_pk_fma_f32 v[8:9], v[8:9], v[74:75], v[120:121] op_sel_hi:[1,0,1]
	s_waitcnt vmcnt(47)
	v_cvt_pk_bf16_f32 v123, v8, v9
	v_lshlrev_b32_e32 v120, 16, v155
	v_and_b32_e32 v121, 0xffff0000, v155
	global_store_dword v116, v123, s[16:17]
	s_add_u32 s16, s16, 0x40000
	s_addc_u32 s17, s17, 0
	v_pk_mul_f32 v[120:121], v[230:231], v[120:121] op_sel:[1,0] op_sel_hi:[1,1]
	v_pk_fma_f32 v[8:9], v[8:9], v[74:75], v[120:121] op_sel:[0,1,0] op_sel_hi:[1,1,1]
	global_load_dword v172, v116, s[14:15]
	s_add_u32 s14, s14, 0x40000
	s_addc_u32 s15, s15, 0
	global_load_dword v173, v116, s[14:15]
	s_add_u32 s14, s14, 0x40000
	s_addc_u32 s15, s15, 0
	global_load_dword v174, v116, s[14:15]
	s_add_u32 s14, s14, 0x40000
	s_addc_u32 s15, s15, 0
	global_load_dword v175, v116, s[14:15]
	s_add_u32 s14, s14, 0x40000
	s_addc_u32 s15, s15, 0
	global_load_dword v176, v116, s[14:15]
	s_add_u32 s14, s14, 0x40000
	s_addc_u32 s15, s15, 0
	global_load_dword v177, v116, s[14:15]
	s_add_u32 s14, s14, 0x40000
	s_addc_u32 s15, s15, 0
	global_load_dword v178, v116, s[14:15]
	s_add_u32 s14, s14, 0x40000
	s_addc_u32 s15, s15, 0
	global_load_dword v179, v116, s[14:15]
	s_add_u32 s14, s14, 0x40000
	s_addc_u32 s15, s15, 0
	global_load_dword v180, v116, s[14:15]
	s_add_u32 s14, s14, 0x40000
	s_addc_u32 s15, s15, 0
	global_load_dword v181, v116, s[14:15]
	s_add_u32 s14, s14, 0x40000
	s_addc_u32 s15, s15, 0
	global_load_dword v182, v116, s[14:15]
	s_add_u32 s14, s14, 0x40000
	s_addc_u32 s15, s15, 0
	global_load_dword v183, v116, s[14:15]
	s_add_u32 s14, s14, 0x40000
	s_addc_u32 s15, s15, 0
	global_load_dword v184, v116, s[14:15]
	s_add_u32 s14, s14, 0x40000
	s_addc_u32 s15, s15, 0
	global_load_dword v185, v116, s[14:15]
	s_add_u32 s14, s14, 0x40000
	s_addc_u32 s15, s15, 0
	global_load_dword v186, v116, s[14:15]
	s_add_u32 s14, s14, 0x40000
	s_addc_u32 s15, s15, 0
	global_load_dword v187, v116, s[14:15]
	s_add_u32 s14, s14, 0x40000
	s_addc_u32 s15, s15, 0
	v_add_u32_e32 v118, 0x400, v118
	v_add_u32_e32 v119, 0x400, v119
	ds_read2_b32 v[12:13], v118 offset0:0 offset1:4
	ds_read2_b32 v[76:77], v119 offset0:0 offset1:4
	ds_read2_b32 v[14:15], v118 offset0:8 offset1:12
	ds_read2_b32 v[78:79], v119 offset0:8 offset1:12
	ds_read2_b32 v[16:17], v118 offset0:16 offset1:20
	ds_read2_b32 v[80:81], v119 offset0:16 offset1:20
	ds_read2_b32 v[18:19], v118 offset0:24 offset1:28
	ds_read2_b32 v[82:83], v119 offset0:24 offset1:28
	s_waitcnt lgkmcnt(0)
	ds_read2_b32 v[20:21], v118 offset0:32 offset1:36
	ds_read2_b32 v[84:85], v119 offset0:32 offset1:36
	ds_read2_b32 v[22:23], v118 offset0:40 offset1:44
	ds_read2_b32 v[86:87], v119 offset0:40 offset1:44
	ds_read2_b32 v[24:25], v118 offset0:48 offset1:52
	ds_read2_b32 v[88:89], v119 offset0:48 offset1:52
	ds_read2_b32 v[26:27], v118 offset0:56 offset1:60
	ds_read2_b32 v[90:91], v119 offset0:56 offset1:60
	s_waitcnt lgkmcnt(0)
	ds_read2_b32 v[28:29], v118 offset0:64 offset1:68
	ds_read2_b32 v[92:93], v119 offset0:64 offset1:68
	ds_read2_b32 v[30:31], v118 offset0:72 offset1:76
	ds_read2_b32 v[94:95], v119 offset0:72 offset1:76
	ds_read2_b32 v[32:33], v118 offset0:80 offset1:84
	ds_read2_b32 v[96:97], v119 offset0:80 offset1:84
	ds_read2_b32 v[34:35], v118 offset0:88 offset1:92
	ds_read2_b32 v[98:99], v119 offset0:88 offset1:92
	s_waitcnt lgkmcnt(0)
	ds_read2_b32 v[36:37], v118 offset0:96 offset1:100
	ds_read2_b32 v[100:101], v119 offset0:96 offset1:100
	ds_read2_b32 v[38:39], v118 offset0:104 offset1:108
	ds_read2_b32 v[102:103], v119 offset0:104 offset1:108
	ds_read2_b32 v[40:41], v118 offset0:112 offset1:116
	ds_read2_b32 v[104:105], v119 offset0:112 offset1:116
	ds_read2_b32 v[42:43], v118 offset0:120 offset1:124
	ds_read2_b32 v[106:107], v119 offset0:120 offset1:124
	s_waitcnt lgkmcnt(0)
; DI unsigned pk2(float lo, float hi) { f32x2 v = {lo, hi}; bf16x2_t b = __builtin_convertvector(v, bf16x2_t); return __builtin_bit_cast(unsigned, b); }
; DI float bflo(unsigned u) { return __uint_as_float(u << 16); }
; DI float bfhi(unsigned u) { return __uint_as_float(u & 0xffff0000u); }
; DI void phase_m_comb(int wv, const ArgP a, LAS unsigned char* lds, int dry) {
;     ...
;             for (int c = 0; c < 256; c += 64) { unsigned d[64];
; #pragma unroll
;                 for (int k = 0; k < 64; ++k) d[k] = p[(size_t)(c + k) * 65536];
; #pragma unroll
;                 for (int k = 0; k < 64; ++k) { if (!dry) p[(size_t)(c + k) * 65536] = pk2(C0, C1); const float a_ = ga[(c + k) * 4 + h], b_ = gb[(c + k) * 4 + h]; C0 = a_ * C0 + b_ * bflo(d[k]); C1 = a_ * C1 + b_ * bfhi(d[k]); } }
	ds_read2_b32 v[44:45], v118 offset0:128 offset1:132
	ds_read2_b32 v[108:109], v119 offset0:128 offset1:132
	ds_read2_b32 v[46:47], v118 offset0:136 offset1:140
	ds_read2_b32 v[110:111], v119 offset0:136 offset1:140
	ds_read2_b32 v[48:49], v118 offset0:144 offset1:148
	ds_read2_b32 v[112:113], v119 offset0:144 offset1:148
	ds_read2_b32 v[50:51], v118 offset0:152 offset1:156
	ds_read2_b32 v[114:115], v119 offset0:152 offset1:156
	s_waitcnt lgkmcnt(0)
	ds_read2_b32 v[52:53], v118 offset0:160 offset1:164
	ds_read2_b32 v[208:209], v119 offset0:160 offset1:164
	ds_read2_b32 v[54:55], v118 offset0:168 offset1:172
	ds_read2_b32 v[210:211], v119 offset0:168 offset1:172
	ds_read2_b32 v[56:57], v118 offset0:176 offset1:180
	ds_read2_b32 v[212:213], v119 offset0:176 offset1:180
	ds_read2_b32 v[58:59], v118 offset0:184 offset1:188
	ds_read2_b32 v[214:215], v119 offset0:184 offset1:188
	s_waitcnt lgkmcnt(0)
	ds_read2_b32 v[60:61], v118 offset0:192 offset1:196
	ds_read2_b32 v[216:217], v119 offset0:192 offset1:196
	ds_read2_b32 v[62:63], v118 offset0:200 offset1:204
	ds_read2_b32 v[218:219], v119 offset0:200 offset1:204
	ds_read2_b32 v[64:65], v118 offset0:208 offset1:212
	ds_read2_b32 v[220:221], v119 offset0:208 offset1:212
	ds_read2_b32 v[66:67], v118 offset0:216 offset1:220
	ds_read2_b32 v[222:223], v119 offset0:216 offset1:220
	s_waitcnt lgkmcnt(0)
	ds_read2_b32 v[68:69], v118 offset0:224 offset1:228
	ds_read2_b32 v[224:225], v119 offset0:224 offset1:228
	ds_read2_b32 v[70:71], v118 offset0:232 offset1:236
	ds_read2_b32 v[226:227], v119 offset0:232 offset1:236
	ds_read2_b32 v[72:73], v118 offset0:240 offset1:244
	ds_read2_b32 v[228:229], v119 offset0:240 offset1:244
	ds_read2_b32 v[74:75], v118 offset0:248 offset1:252
	ds_read2_b32 v[230:231], v119 offset0:248 offset1:252
	s_waitcnt lgkmcnt(0)
	s_waitcnt vmcnt(47)
	v_cvt_pk_bf16_f32 v122, v8, v9
	v_lshlrev_b32_e32 v120, 16, v156
	v_and_b32_e32 v121, 0xffff0000, v156
	global_store_dword v116, v122, s[16:17]
	s_add_u32 s16, s16, 0x40000
	s_addc_u32 s17, s17, 0
	v_pk_mul_f32 v[120:121], v[76:77], v[120:121] op_sel_hi:[0,1]
	v_pk_fma_f32 v[8:9], v[8:9], v[12:13], v[120:121] op_sel_hi:[1,0,1]
	s_waitcnt vmcnt(47)
	v_cvt_pk_bf16_f32 v123, v8, v9
	v_lshlrev_b32_e32 v120, 16, v157
	v_and_b32_e32 v121, 0xffff0000, v157
	global_store_dword v116, v123, s[16:17]
	s_add_u32 s16, s16, 0x40000
	s_addc_u32 s17, s17, 0
	v_pk_mul_f32 v[120:121], v[76:77], v[120:121] op_sel:[1,0] op_sel_hi:[1,1]
	v_pk_fma_f32 v[8:9], v[8:9], v[12:13], v[120:121] op_sel:[0,1,0] op_sel_hi:[1,1,1]
	s_waitcnt vmcnt(47)
	v_cvt_pk_bf16_f32 v122, v8, v9
	v_lshlrev_b32_e32 v120, 16, v158
	v_and_b32_e32 v121, 0xffff0000, v158
	global_store_dword v116, v122, s[16:17]
	s_add_u32 s16, s16, 0x40000
	s_addc_u32 s17, s17, 0
	v_pk_mul_f32 v[120:121], v[78:79], v[120:121] op_sel_hi:[0,1]
	v_pk_fma_f32 v[8:9], v[8:9], v[14:15], v[120:121] op_sel_hi:[1,0,1]
	s_waitcnt vmcnt(47)
	v_cvt_pk_bf16_f32 v123, v8, v9
	v_lshlrev_b32_e32 v120, 16, v159
	v_and_b32_e32 v121, 0xffff0000, v159
	global_store_dword v116, v123, s[16:17]
	s_add_u32 s16, s16, 0x40000
	s_addc_u32 s17, s17, 0
	v_pk_mul_f32 v[120:121], v[78:79], v[120:121] op_sel:[1,0] op_sel_hi:[1,1]
	v_pk_fma_f32 v[8:9], v[8:9], v[14:15], v[120:121] op_sel:[0,1,0] op_sel_hi:[1,1,1]
	s_waitcnt vmcnt(47)
	v_cvt_pk_bf16_f32 v122, v8, v9
	v_lshlrev_b32_e32 v120, 16, v160
	v_and_b32_e32 v121, 0xffff0000, v160
	global_store_dword v116, v122, s[16:17]
	s_add_u32 s16, s16, 0x40000
	s_addc_u32 s17, s17, 0
	v_pk_mul_f32 v[120:121], v[80:81], v[120:121] op_sel_hi:[0,1]
	v_pk_fma_f32 v[8:9], v[8:9], v[16:17], v[120:121] op_sel_hi:[1,0,1]
	s_waitcnt vmcnt(47)
	v_cvt_pk_bf16_f32 v123, v8, v9
	v_lshlrev_b32_e32 v120, 16, v161
	v_and_b32_e32 v121, 0xffff0000, v161
	global_store_dword v116, v123, s[16:17]
	s_add_u32 s16, s16, 0x40000
	s_addc_u32 s17, s17, 0
	v_pk_mul_f32 v[120:121], v[80:81], v[120:121] op_sel:[1,0] op_sel_hi:[1,1]
	v_pk_fma_f32 v[8:9], v[8:9], v[16:17], v[120:121] op_sel:[0,1,0] op_sel_hi:[1,1,1]
	s_waitcnt vmcnt(47)
	v_cvt_pk_bf16_f32 v122, v8, v9
	v_lshlrev_b32_e32 v120, 16, v162
	v_and_b32_e32 v121, 0xffff0000, v162
	global_store_dword v116, v122, s[16:17]
	s_add_u32 s16, s16, 0x40000
	s_addc_u32 s17, s17, 0
	v_pk_mul_f32 v[120:121], v[82:83], v[120:121] op_sel_hi:[0,1]
	v_pk_fma_f32 v[8:9], v[8:9], v[18:19], v[120:121] op_sel_hi:[1,0,1]
	s_waitcnt vmcnt(47)
	v_cvt_pk_bf16_f32 v123, v8, v9
	v_lshlrev_b32_e32 v120, 16, v163
	v_and_b32_e32 v121, 0xffff0000, v163
	global_store_dword v116, v123, s[16:17]
	s_add_u32 s16, s16, 0x40000
	s_addc_u32 s17, s17, 0
	v_pk_mul_f32 v[120:121], v[82:83], v[120:121] op_sel:[1,0] op_sel_hi:[1,1]
	v_pk_fma_f32 v[8:9], v[8:9], v[18:19], v[120:121] op_sel:[0,1,0] op_sel_hi:[1,1,1]
	s_waitcnt vmcnt(47)
	v_cvt_pk_bf16_f32 v122, v8, v9
	v_lshlrev_b32_e32 v120, 16, v164
	v_and_b32_e32 v121, 0xffff0000, v164
	global_store_dword v116, v122, s[16:17]
	s_add_u32 s16, s16, 0x40000
	s_addc_u32 s17, s17, 0
	v_pk_mul_f32 v[120:121], v[84:85], v[120:121] op_sel_hi:[0,1]
	v_pk_fma_f32 v[8:9], v[8:9], v[20:21], v[120:121] op_sel_hi:[1,0,1]
	s_waitcnt vmcnt(47)
	v_cvt_pk_bf16_f32 v123, v8, v9
	v_lshlrev_b32_e32 v120, 16, v165
	v_and_b32_e32 v121, 0xffff0000, v165
	global_store_dword v116, v123, s[16:17]
	s_add_u32 s16, s16, 0x40000
	s_addc_u32 s17, s17, 0
	v_pk_mul_f32 v[120:121], v[84:85], v[120:121] op_sel:[1,0] op_sel_hi:[1,1]
	v_pk_fma_f32 v[8:9], v[8:9], v[20:21], v[120:121] op_sel:[0,1,0] op_sel_hi:[1,1,1]
	s_waitcnt vmcnt(47)
; DI unsigned pk2(float lo, float hi) { f32x2 v = {lo, hi}; bf16x2_t b = __builtin_convertvector(v, bf16x2_t); return __builtin_bit_cast(unsigned, b); }
; DI float bflo(unsigned u) { return __uint_as_float(u << 16); }
; DI float bfhi(unsigned u) { return __uint_as_float(u & 0xffff0000u); }
; DI void phase_m_comb(int wv, const ArgP a, LAS unsigned char* lds, int dry) {
;     ...
;             for (int c = 0; c < 256; c += 64) { unsigned d[64];
; #pragma unroll
;                 for (int k = 0; k < 64; ++k) d[k] = p[(size_t)(c + k) * 65536];
; #pragma unroll
;                 for (int k = 0; k < 64; ++k) { if (!dry) p[(size_t)(c + k) * 65536] = pk2(C0, C1); const float a_ = ga[(c + k) * 4 + h], b_ = gb[(c + k) * 4 + h]; C0 = a_ * C0 + b_ * bflo(d[k]); C1 = a_ * C1 + b_ * bfhi(d[k]); } }
	v_cvt_pk_bf16_f32 v122, v8, v9
	v_lshlrev_b32_e32 v120, 16, v166
	v_and_b32_e32 v121, 0xffff0000, v166
	global_store_dword v116, v122, s[16:17]
	s_add_u32 s16, s16, 0x40000
	s_addc_u32 s17, s17, 0
	v_pk_mul_f32 v[120:121], v[86:87], v[120:121] op_sel_hi:[0,1]
	v_pk_fma_f32 v[8:9], v[8:9], v[22:23], v[120:121] op_sel_hi:[1,0,1]
	s_waitcnt vmcnt(47)
	v_cvt_pk_bf16_f32 v123, v8, v9
	v_lshlrev_b32_e32 v120, 16, v167
	v_and_b32_e32 v121, 0xffff0000, v167
	global_store_dword v116, v123, s[16:17]
	s_add_u32 s16, s16, 0x40000
	s_addc_u32 s17, s17, 0
	v_pk_mul_f32 v[120:121], v[86:87], v[120:121] op_sel:[1,0] op_sel_hi:[1,1]
	v_pk_fma_f32 v[8:9], v[8:9], v[22:23], v[120:121] op_sel:[0,1,0] op_sel_hi:[1,1,1]
	s_waitcnt vmcnt(47)
	v_cvt_pk_bf16_f32 v122, v8, v9
	v_lshlrev_b32_e32 v120, 16, v168
	v_and_b32_e32 v121, 0xffff0000, v168
	global_store_dword v116, v122, s[16:17]
	s_add_u32 s16, s16, 0x40000
	s_addc_u32 s17, s17, 0
	v_pk_mul_f32 v[120:121], v[88:89], v[120:121] op_sel_hi:[0,1]
	v_pk_fma_f32 v[8:9], v[8:9], v[24:25], v[120:121] op_sel_hi:[1,0,1]
	s_waitcnt vmcnt(47)
	v_cvt_pk_bf16_f32 v123, v8, v9
	v_lshlrev_b32_e32 v120, 16, v169
	v_and_b32_e32 v121, 0xffff0000, v169
	global_store_dword v116, v123, s[16:17]
	s_add_u32 s16, s16, 0x40000
	s_addc_u32 s17, s17, 0
	v_pk_mul_f32 v[120:121], v[88:89], v[120:121] op_sel:[1,0] op_sel_hi:[1,1]
	v_pk_fma_f32 v[8:9], v[8:9], v[24:25], v[120:121] op_sel:[0,1,0] op_sel_hi:[1,1,1]
	s_waitcnt vmcnt(47)
	v_cvt_pk_bf16_f32 v122, v8, v9
	v_lshlrev_b32_e32 v120, 16, v170
	v_and_b32_e32 v121, 0xffff0000, v170
	global_store_dword v116, v122, s[16:17]
	s_add_u32 s16, s16, 0x40000
	s_addc_u32 s17, s17, 0
	v_pk_mul_f32 v[120:121], v[90:91], v[120:121] op_sel_hi:[0,1]
	v_pk_fma_f32 v[8:9], v[8:9], v[26:27], v[120:121] op_sel_hi:[1,0,1]
	s_waitcnt vmcnt(47)
	v_cvt_pk_bf16_f32 v123, v8, v9
	v_lshlrev_b32_e32 v120, 16, v171
	v_and_b32_e32 v121, 0xffff0000, v171
	global_store_dword v116, v123, s[16:17]
	s_add_u32 s16, s16, 0x40000
	s_addc_u32 s17, s17, 0
	v_pk_mul_f32 v[120:121], v[90:91], v[120:121] op_sel:[1,0] op_sel_hi:[1,1]
	v_pk_fma_f32 v[8:9], v[8:9], v[26:27], v[120:121] op_sel:[0,1,0] op_sel_hi:[1,1,1]
	global_load_dword v140, v116, s[14:15]
	s_add_u32 s14, s14, 0x40000
	s_addc_u32 s15, s15, 0
	global_load_dword v141, v116, s[14:15]
	s_add_u32 s14, s14, 0x40000
	s_addc_u32 s15, s15, 0
	global_load_dword v142, v116, s[14:15]
	s_add_u32 s14, s14, 0x40000
	s_addc_u32 s15, s15, 0
	global_load_dword v143, v116, s[14:15]
	s_add_u32 s14, s14, 0x40000
	s_addc_u32 s15, s15, 0
	global_load_dword v144, v116, s[14:15]
	s_add_u32 s14, s14, 0x40000
	s_addc_u32 s15, s15, 0
	global_load_dword v145, v116, s[14:15]
	s_add_u32 s14, s14, 0x40000
	s_addc_u32 s15, s15, 0
	global_load_dword v146, v116, s[14:15]
	s_add_u32 s14, s14, 0x40000
	s_addc_u32 s15, s15, 0
	global_load_dword v147, v116, s[14:15]
	s_add_u32 s14, s14, 0x40000
	s_addc_u32 s15, s15, 0
	global_load_dword v148, v116, s[14:15]
	s_add_u32 s14, s14, 0x40000
	s_addc_u32 s15, s15, 0
	global_load_dword v149, v116, s[14:15]
	s_add_u32 s14, s14, 0x40000
	s_addc_u32 s15, s15, 0
	global_load_dword v150, v116, s[14:15]
	s_add_u32 s14, s14, 0x40000
	s_addc_u32 s15, s15, 0
	global_load_dword v151, v116, s[14:15]
	s_add_u32 s14, s14, 0x40000
	s_addc_u32 s15, s15, 0
	global_load_dword v152, v116, s[14:15]
	s_add_u32 s14, s14, 0x40000
	s_addc_u32 s15, s15, 0
	global_load_dword v153, v116, s[14:15]
	s_add_u32 s14, s14, 0x40000
	s_addc_u32 s15, s15, 0
	global_load_dword v154, v116, s[14:15]
	s_add_u32 s14, s14, 0x40000
	s_addc_u32 s15, s15, 0
	global_load_dword v155, v116, s[14:15]
	s_add_u32 s14, s14, 0x40000
	s_addc_u32 s15, s15, 0
	s_waitcnt vmcnt(47)
	v_cvt_pk_bf16_f32 v122, v8, v9
	v_lshlrev_b32_e32 v120, 16, v172
	v_and_b32_e32 v121, 0xffff0000, v172
	global_store_dword v116, v122, s[16:17]
	s_add_u32 s16, s16, 0x40000
	s_addc_u32 s17, s17, 0
	v_pk_mul_f32 v[120:121], v[92:93], v[120:121] op_sel_hi:[0,1]
	v_pk_fma_f32 v[8:9], v[8:9], v[28:29], v[120:121] op_sel_hi:[1,0,1]
	s_waitcnt vmcnt(47)
	v_cvt_pk_bf16_f32 v123, v8, v9
	v_lshlrev_b32_e32 v120, 16, v173
	v_and_b32_e32 v121, 0xffff0000, v173
	global_store_dword v116, v123, s[16:17]
	s_add_u32 s16, s16, 0x40000
	s_addc_u32 s17, s17, 0
	v_pk_mul_f32 v[120:121], v[92:93], v[120:121] op_sel:[1,0] op_sel_hi:[1,1]
	v_pk_fma_f32 v[8:9], v[8:9], v[28:29], v[120:121] op_sel:[0,1,0] op_sel_hi:[1,1,1]
	s_waitcnt vmcnt(47)
	v_cvt_pk_bf16_f32 v122, v8, v9
	v_lshlrev_b32_e32 v120, 16, v174
	v_and_b32_e32 v121, 0xffff0000, v174
	global_store_dword v116, v122, s[16:17]
	s_add_u32 s16, s16, 0x40000
	s_addc_u32 s17, s17, 0
	v_pk_mul_f32 v[120:121], v[94:95], v[120:121] op_sel_hi:[0,1]
	v_pk_fma_f32 v[8:9], v[8:9], v[30:31], v[120:121] op_sel_hi:[1,0,1]
	s_waitcnt vmcnt(47)
	v_cvt_pk_bf16_f32 v123, v8, v9
	v_lshlrev_b32_e32 v120, 16, v175
	v_and_b32_e32 v121, 0xffff0000, v175
	global_store_dword v116, v123, s[16:17]
	s_add_u32 s16, s16, 0x40000
	s_addc_u32 s17, s17, 0
	v_pk_mul_f32 v[120:121], v[94:95], v[120:121] op_sel:[1,0] op_sel_hi:[1,1]
	v_pk_fma_f32 v[8:9], v[8:9], v[30:31], v[120:121] op_sel:[0,1,0] op_sel_hi:[1,1,1]
	s_waitcnt vmcnt(47)
	v_cvt_pk_bf16_f32 v122, v8, v9
	v_lshlrev_b32_e32 v120, 16, v176
	v_and_b32_e32 v121, 0xffff0000, v176
	global_store_dword v116, v122, s[16:17]
	s_add_u32 s16, s16, 0x40000
	s_addc_u32 s17, s17, 0
	v_pk_mul_f32 v[120:121], v[96:97], v[120:121] op_sel_hi:[0,1]
	v_pk_fma_f32 v[8:9], v[8:9], v[32:33], v[120:121] op_sel_hi:[1,0,1]
	s_waitcnt vmcnt(47)
; DI unsigned pk2(float lo, float hi) { f32x2 v = {lo, hi}; bf16x2_t b = __builtin_convertvector(v, bf16x2_t); return __builtin_bit_cast(unsigned, b); }
; DI float bflo(unsigned u) { return __uint_as_float(u << 16); }
; DI float bfhi(unsigned u) { return __uint_as_float(u & 0xffff0000u); }
; DI void phase_m_comb(int wv, const ArgP a, LAS unsigned char* lds, int dry) {
;     ...
;             for (int c = 0; c < 256; c += 64) { unsigned d[64];
; #pragma unroll
;                 for (int k = 0; k < 64; ++k) d[k] = p[(size_t)(c + k) * 65536];
; #pragma unroll
;                 for (int k = 0; k < 64; ++k) { if (!dry) p[(size_t)(c + k) * 65536] = pk2(C0, C1); const float a_ = ga[(c + k) * 4 + h], b_ = gb[(c + k) * 4 + h]; C0 = a_ * C0 + b_ * bflo(d[k]); C1 = a_ * C1 + b_ * bfhi(d[k]); } }
	v_cvt_pk_bf16_f32 v123, v8, v9
	v_lshlrev_b32_e32 v120, 16, v177
	v_and_b32_e32 v121, 0xffff0000, v177
	global_store_dword v116, v123, s[16:17]
	s_add_u32 s16, s16, 0x40000
	s_addc_u32 s17, s17, 0
	v_pk_mul_f32 v[120:121], v[96:97], v[120:121] op_sel:[1,0] op_sel_hi:[1,1]
	v_pk_fma_f32 v[8:9], v[8:9], v[32:33], v[120:121] op_sel:[0,1,0] op_sel_hi:[1,1,1]
	s_waitcnt vmcnt(47)
	v_cvt_pk_bf16_f32 v122, v8, v9
	v_lshlrev_b32_e32 v120, 16, v178
	v_and_b32_e32 v121, 0xffff0000, v178
	global_store_dword v116, v122, s[16:17]
	s_add_u32 s16, s16, 0x40000
	s_addc_u32 s17, s17, 0
	v_pk_mul_f32 v[120:121], v[98:99], v[120:121] op_sel_hi:[0,1]
	v_pk_fma_f32 v[8:9], v[8:9], v[34:35], v[120:121] op_sel_hi:[1,0,1]
	s_waitcnt vmcnt(47)
	v_cvt_pk_bf16_f32 v123, v8, v9
	v_lshlrev_b32_e32 v120, 16, v179
	v_and_b32_e32 v121, 0xffff0000, v179
	global_store_dword v116, v123, s[16:17]
	s_add_u32 s16, s16, 0x40000
	s_addc_u32 s17, s17, 0
	v_pk_mul_f32 v[120:121], v[98:99], v[120:121] op_sel:[1,0] op_sel_hi:[1,1]
	v_pk_fma_f32 v[8:9], v[8:9], v[34:35], v[120:121] op_sel:[0,1,0] op_sel_hi:[1,1,1]
	s_waitcnt vmcnt(47)
	v_cvt_pk_bf16_f32 v122, v8, v9
	v_lshlrev_b32_e32 v120, 16, v180
	v_and_b32_e32 v121, 0xffff0000, v180
	global_store_dword v116, v122, s[16:17]
	s_add_u32 s16, s16, 0x40000
	s_addc_u32 s17, s17, 0
	v_pk_mul_f32 v[120:121], v[100:101], v[120:121] op_sel_hi:[0,1]
	v_pk_fma_f32 v[8:9], v[8:9], v[36:37], v[120:121] op_sel_hi:[1,0,1]
	s_waitcnt vmcnt(47)
	v_cvt_pk_bf16_f32 v123, v8, v9
	v_lshlrev_b32_e32 v120, 16, v181
	v_and_b32_e32 v121, 0xffff0000, v181
	global_store_dword v116, v123, s[16:17]
	s_add_u32 s16, s16, 0x40000
	s_addc_u32 s17, s17, 0
	v_pk_mul_f32 v[120:121], v[100:101], v[120:121] op_sel:[1,0] op_sel_hi:[1,1]
	v_pk_fma_f32 v[8:9], v[8:9], v[36:37], v[120:121] op_sel:[0,1,0] op_sel_hi:[1,1,1]
	s_waitcnt vmcnt(47)
	v_cvt_pk_bf16_f32 v122, v8, v9
	v_lshlrev_b32_e32 v120, 16, v182
	v_and_b32_e32 v121, 0xffff0000, v182
	global_store_dword v116, v122, s[16:17]
	s_add_u32 s16, s16, 0x40000
	s_addc_u32 s17, s17, 0
	v_pk_mul_f32 v[120:121], v[102:103], v[120:121] op_sel_hi:[0,1]
	v_pk_fma_f32 v[8:9], v[8:9], v[38:39], v[120:121] op_sel_hi:[1,0,1]
	s_waitcnt vmcnt(47)
	v_cvt_pk_bf16_f32 v123, v8, v9
	v_lshlrev_b32_e32 v120, 16, v183
	v_and_b32_e32 v121, 0xffff0000, v183
	global_store_dword v116, v123, s[16:17]
	s_add_u32 s16, s16, 0x40000
	s_addc_u32 s17, s17, 0
	v_pk_mul_f32 v[120:121], v[102:103], v[120:121] op_sel:[1,0] op_sel_hi:[1,1]
	v_pk_fma_f32 v[8:9], v[8:9], v[38:39], v[120:121] op_sel:[0,1,0] op_sel_hi:[1,1,1]
	s_waitcnt vmcnt(47)
	v_cvt_pk_bf16_f32 v122, v8, v9
	v_lshlrev_b32_e32 v120, 16, v184
	v_and_b32_e32 v121, 0xffff0000, v184
	global_store_dword v116, v122, s[16:17]
	s_add_u32 s16, s16, 0x40000
	s_addc_u32 s17, s17, 0
	v_pk_mul_f32 v[120:121], v[104:105], v[120:121] op_sel_hi:[0,1]
	v_pk_fma_f32 v[8:9], v[8:9], v[40:41], v[120:121] op_sel_hi:[1,0,1]
	s_waitcnt vmcnt(47)
	v_cvt_pk_bf16_f32 v123, v8, v9
	v_lshlrev_b32_e32 v120, 16, v185
	v_and_b32_e32 v121, 0xffff0000, v185
	global_store_dword v116, v123, s[16:17]
	s_add_u32 s16, s16, 0x40000
	s_addc_u32 s17, s17, 0
	v_pk_mul_f32 v[120:121], v[104:105], v[120:121] op_sel:[1,0] op_sel_hi:[1,1]
	v_pk_fma_f32 v[8:9], v[8:9], v[40:41], v[120:121] op_sel:[0,1,0] op_sel_hi:[1,1,1]
	s_waitcnt vmcnt(47)
	v_cvt_pk_bf16_f32 v122, v8, v9
	v_lshlrev_b32_e32 v120, 16, v186
	v_and_b32_e32 v121, 0xffff0000, v186
	global_store_dword v116, v122, s[16:17]
	s_add_u32 s16, s16, 0x40000
	s_addc_u32 s17, s17, 0
	v_pk_mul_f32 v[120:121], v[106:107], v[120:121] op_sel_hi:[0,1]
	v_pk_fma_f32 v[8:9], v[8:9], v[42:43], v[120:121] op_sel_hi:[1,0,1]
	s_waitcnt vmcnt(47)
	v_cvt_pk_bf16_f32 v123, v8, v9
	v_lshlrev_b32_e32 v120, 16, v187
	v_and_b32_e32 v121, 0xffff0000, v187
	global_store_dword v116, v123, s[16:17]
	s_add_u32 s16, s16, 0x40000
	s_addc_u32 s17, s17, 0
	v_pk_mul_f32 v[120:121], v[106:107], v[120:121] op_sel:[1,0] op_sel_hi:[1,1]
	v_pk_fma_f32 v[8:9], v[8:9], v[42:43], v[120:121] op_sel:[0,1,0] op_sel_hi:[1,1,1]
	global_load_dword v156, v116, s[14:15]
	s_add_u32 s14, s14, 0x40000
	s_addc_u32 s15, s15, 0
	global_load_dword v157, v116, s[14:15]
	s_add_u32 s14, s14, 0x40000
	s_addc_u32 s15, s15, 0
	global_load_dword v158, v116, s[14:15]
	s_add_u32 s14, s14, 0x40000
	s_addc_u32 s15, s15, 0
	global_load_dword v159, v116, s[14:15]
	s_add_u32 s14, s14, 0x40000
	s_addc_u32 s15, s15, 0
	global_load_dword v160, v116, s[14:15]
	s_add_u32 s14, s14, 0x40000
	s_addc_u32 s15, s15, 0
	global_load_dword v161, v116, s[14:15]
	s_add_u32 s14, s14, 0x40000
	s_addc_u32 s15, s15, 0
	global_load_dword v162, v116, s[14:15]
	s_add_u32 s14, s14, 0x40000
	s_addc_u32 s15, s15, 0
	global_load_dword v163, v116, s[14:15]
	s_add_u32 s14, s14, 0x40000
	s_addc_u32 s15, s15, 0
	global_load_dword v164, v116, s[14:15]
	s_add_u32 s14, s14, 0x40000
	s_addc_u32 s15, s15, 0
	global_load_dword v165, v116, s[14:15]
	s_add_u32 s14, s14, 0x40000
	s_addc_u32 s15, s15, 0
	global_load_dword v166, v116, s[14:15]
	s_add_u32 s14, s14, 0x40000
	s_addc_u32 s15, s15, 0
	global_load_dword v167, v116, s[14:15]
	s_add_u32 s14, s14, 0x40000
	s_addc_u32 s15, s15, 0
	global_load_dword v168, v116, s[14:15]
	s_add_u32 s14, s14, 0x40000
	s_addc_u32 s15, s15, 0
	global_load_dword v169, v116, s[14:15]
	s_add_u32 s14, s14, 0x40000
	s_addc_u32 s15, s15, 0
	global_load_dword v170, v116, s[14:15]
	s_add_u32 s14, s14, 0x40000
	s_addc_u32 s15, s15, 0
	global_load_dword v171, v116, s[14:15]
	s_add_u32 s14, s14, 0x40000
	s_addc_u32 s15, s15, 0
	s_waitcnt vmcnt(47)
; DI unsigned pk2(float lo, float hi) { f32x2 v = {lo, hi}; bf16x2_t b = __builtin_convertvector(v, bf16x2_t); return __builtin_bit_cast(unsigned, b); }
; DI float bflo(unsigned u) { return __uint_as_float(u << 16); }
; DI float bfhi(unsigned u) { return __uint_as_float(u & 0xffff0000u); }
; DI void phase_m_comb(int wv, const ArgP a, LAS unsigned char* lds, int dry) {
;     ...
;             for (int c = 0; c < 256; c += 64) { unsigned d[64];
; #pragma unroll
;                 for (int k = 0; k < 64; ++k) d[k] = p[(size_t)(c + k) * 65536];
; #pragma unroll
;                 for (int k = 0; k < 64; ++k) { if (!dry) p[(size_t)(c + k) * 65536] = pk2(C0, C1); const float a_ = ga[(c + k) * 4 + h], b_ = gb[(c + k) * 4 + h]; C0 = a_ * C0 + b_ * bflo(d[k]); C1 = a_ * C1 + b_ * bfhi(d[k]); } }
	v_cvt_pk_bf16_f32 v122, v8, v9
	v_lshlrev_b32_e32 v120, 16, v140
	v_and_b32_e32 v121, 0xffff0000, v140
	global_store_dword v116, v122, s[16:17]
	s_add_u32 s16, s16, 0x40000
	s_addc_u32 s17, s17, 0
	v_pk_mul_f32 v[120:121], v[108:109], v[120:121] op_sel_hi:[0,1]
	v_pk_fma_f32 v[8:9], v[8:9], v[44:45], v[120:121] op_sel_hi:[1,0,1]
	s_waitcnt vmcnt(47)
	v_cvt_pk_bf16_f32 v123, v8, v9
	v_lshlrev_b32_e32 v120, 16, v141
	v_and_b32_e32 v121, 0xffff0000, v141
	global_store_dword v116, v123, s[16:17]
	s_add_u32 s16, s16, 0x40000
	s_addc_u32 s17, s17, 0
	v_pk_mul_f32 v[120:121], v[108:109], v[120:121] op_sel:[1,0] op_sel_hi:[1,1]
	v_pk_fma_f32 v[8:9], v[8:9], v[44:45], v[120:121] op_sel:[0,1,0] op_sel_hi:[1,1,1]
	s_waitcnt vmcnt(47)
	v_cvt_pk_bf16_f32 v122, v8, v9
	v_lshlrev_b32_e32 v120, 16, v142
	v_and_b32_e32 v121, 0xffff0000, v142
	global_store_dword v116, v122, s[16:17]
	s_add_u32 s16, s16, 0x40000
	s_addc_u32 s17, s17, 0
	v_pk_mul_f32 v[120:121], v[110:111], v[120:121] op_sel_hi:[0,1]
	v_pk_fma_f32 v[8:9], v[8:9], v[46:47], v[120:121] op_sel_hi:[1,0,1]
	s_waitcnt vmcnt(47)
	v_cvt_pk_bf16_f32 v123, v8, v9
	v_lshlrev_b32_e32 v120, 16, v143
	v_and_b32_e32 v121, 0xffff0000, v143
	global_store_dword v116, v123, s[16:17]
	s_add_u32 s16, s16, 0x40000
	s_addc_u32 s17, s17, 0
	v_pk_mul_f32 v[120:121], v[110:111], v[120:121] op_sel:[1,0] op_sel_hi:[1,1]
	v_pk_fma_f32 v[8:9], v[8:9], v[46:47], v[120:121] op_sel:[0,1,0] op_sel_hi:[1,1,1]
	s_waitcnt vmcnt(47)
	v_cvt_pk_bf16_f32 v122, v8, v9
	v_lshlrev_b32_e32 v120, 16, v144
	v_and_b32_e32 v121, 0xffff0000, v144
	global_store_dword v116, v122, s[16:17]
	s_add_u32 s16, s16, 0x40000
	s_addc_u32 s17, s17, 0
	v_pk_mul_f32 v[120:121], v[112:113], v[120:121] op_sel_hi:[0,1]
	v_pk_fma_f32 v[8:9], v[8:9], v[48:49], v[120:121] op_sel_hi:[1,0,1]
	s_waitcnt vmcnt(47)
	v_cvt_pk_bf16_f32 v123, v8, v9
	v_lshlrev_b32_e32 v120, 16, v145
	v_and_b32_e32 v121, 0xffff0000, v145
	global_store_dword v116, v123, s[16:17]
	s_add_u32 s16, s16, 0x40000
	s_addc_u32 s17, s17, 0
	v_pk_mul_f32 v[120:121], v[112:113], v[120:121] op_sel:[1,0] op_sel_hi:[1,1]
	v_pk_fma_f32 v[8:9], v[8:9], v[48:49], v[120:121] op_sel:[0,1,0] op_sel_hi:[1,1,1]
	s_waitcnt vmcnt(47)
	v_cvt_pk_bf16_f32 v122, v8, v9
	v_lshlrev_b32_e32 v120, 16, v146
	v_and_b32_e32 v121, 0xffff0000, v146
	global_store_dword v116, v122, s[16:17]
	s_add_u32 s16, s16, 0x40000
	s_addc_u32 s17, s17, 0
	v_pk_mul_f32 v[120:121], v[114:115], v[120:121] op_sel_hi:[0,1]
	v_pk_fma_f32 v[8:9], v[8:9], v[50:51], v[120:121] op_sel_hi:[1,0,1]
	s_waitcnt vmcnt(47)
	v_cvt_pk_bf16_f32 v123, v8, v9
	v_lshlrev_b32_e32 v120, 16, v147
	v_and_b32_e32 v121, 0xffff0000, v147
	global_store_dword v116, v123, s[16:17]
	s_add_u32 s16, s16, 0x40000
	s_addc_u32 s17, s17, 0
	v_pk_mul_f32 v[120:121], v[114:115], v[120:121] op_sel:[1,0] op_sel_hi:[1,1]
	v_pk_fma_f32 v[8:9], v[8:9], v[50:51], v[120:121] op_sel:[0,1,0] op_sel_hi:[1,1,1]
	s_waitcnt vmcnt(47)
	v_cvt_pk_bf16_f32 v122, v8, v9
	v_lshlrev_b32_e32 v120, 16, v148
	v_and_b32_e32 v121, 0xffff0000, v148
	global_store_dword v116, v122, s[16:17]
	s_add_u32 s16, s16, 0x40000
	s_addc_u32 s17, s17, 0
	v_pk_mul_f32 v[120:121], v[208:209], v[120:121] op_sel_hi:[0,1]
	v_pk_fma_f32 v[8:9], v[8:9], v[52:53], v[120:121] op_sel_hi:[1,0,1]
	s_waitcnt vmcnt(47)
	v_cvt_pk_bf16_f32 v123, v8, v9
	v_lshlrev_b32_e32 v120, 16, v149
	v_and_b32_e32 v121, 0xffff0000, v149
	global_store_dword v116, v123, s[16:17]
	s_add_u32 s16, s16, 0x40000
	s_addc_u32 s17, s17, 0
	v_pk_mul_f32 v[120:121], v[208:209], v[120:121] op_sel:[1,0] op_sel_hi:[1,1]
	v_pk_fma_f32 v[8:9], v[8:9], v[52:53], v[120:121] op_sel:[0,1,0] op_sel_hi:[1,1,1]
	s_waitcnt vmcnt(47)
	v_cvt_pk_bf16_f32 v122, v8, v9
	v_lshlrev_b32_e32 v120, 16, v150
	v_and_b32_e32 v121, 0xffff0000, v150
	global_store_dword v116, v122, s[16:17]
	s_add_u32 s16, s16, 0x40000
	s_addc_u32 s17, s17, 0
	v_pk_mul_f32 v[120:121], v[210:211], v[120:121] op_sel_hi:[0,1]
	v_pk_fma_f32 v[8:9], v[8:9], v[54:55], v[120:121] op_sel_hi:[1,0,1]
	s_waitcnt vmcnt(47)
	v_cvt_pk_bf16_f32 v123, v8, v9
	v_lshlrev_b32_e32 v120, 16, v151
	v_and_b32_e32 v121, 0xffff0000, v151
	global_store_dword v116, v123, s[16:17]
	s_add_u32 s16, s16, 0x40000
	s_addc_u32 s17, s17, 0
	v_pk_mul_f32 v[120:121], v[210:211], v[120:121] op_sel:[1,0] op_sel_hi:[1,1]
	v_pk_fma_f32 v[8:9], v[8:9], v[54:55], v[120:121] op_sel:[0,1,0] op_sel_hi:[1,1,1]
	s_waitcnt vmcnt(47)
	v_cvt_pk_bf16_f32 v122, v8, v9
	v_lshlrev_b32_e32 v120, 16, v152
	v_and_b32_e32 v121, 0xffff0000, v152
	global_store_dword v116, v122, s[16:17]
	s_add_u32 s16, s16, 0x40000
	s_addc_u32 s17, s17, 0
	v_pk_mul_f32 v[120:121], v[212:213], v[120:121] op_sel_hi:[0,1]
	v_pk_fma_f32 v[8:9], v[8:9], v[56:57], v[120:121] op_sel_hi:[1,0,1]
	s_waitcnt vmcnt(47)
	v_cvt_pk_bf16_f32 v123, v8, v9
	v_lshlrev_b32_e32 v120, 16, v153
	v_and_b32_e32 v121, 0xffff0000, v153
	global_store_dword v116, v123, s[16:17]
	s_add_u32 s16, s16, 0x40000
	s_addc_u32 s17, s17, 0
	v_pk_mul_f32 v[120:121], v[212:213], v[120:121] op_sel:[1,0] op_sel_hi:[1,1]
	v_pk_fma_f32 v[8:9], v[8:9], v[56:57], v[120:121] op_sel:[0,1,0] op_sel_hi:[1,1,1]
	s_waitcnt vmcnt(47)
	v_cvt_pk_bf16_f32 v122, v8, v9
	v_lshlrev_b32_e32 v120, 16, v154
	v_and_b32_e32 v121, 0xffff0000, v154
	global_store_dword v116, v122, s[16:17]
	s_add_u32 s16, s16, 0x40000
	s_addc_u32 s17, s17, 0
	v_pk_mul_f32 v[120:121], v[214:215], v[120:121] op_sel_hi:[0,1]
	v_pk_fma_f32 v[8:9], v[8:9], v[58:59], v[120:121] op_sel_hi:[1,0,1]
	s_waitcnt vmcnt(47)
; DI unsigned pk2(float lo, float hi) { f32x2 v = {lo, hi}; bf16x2_t b = __builtin_convertvector(v, bf16x2_t); return __builtin_bit_cast(unsigned, b); }
; DI float bflo(unsigned u) { return __uint_as_float(u << 16); }
; DI float bfhi(unsigned u) { return __uint_as_float(u & 0xffff0000u); }
; DI void phase_m_comb(int wv, const ArgP a, LAS unsigned char* lds, int dry) {
;     ...
;             for (int c = 0; c < 256; c += 64) { unsigned d[64];
; #pragma unroll
;                 for (int k = 0; k < 64; ++k) d[k] = p[(size_t)(c + k) * 65536];
; #pragma unroll
;                 for (int k = 0; k < 64; ++k) { if (!dry) p[(size_t)(c + k) * 65536] = pk2(C0, C1); const float a_ = ga[(c + k) * 4 + h], b_ = gb[(c + k) * 4 + h]; C0 = a_ * C0 + b_ * bflo(d[k]); C1 = a_ * C1 + b_ * bfhi(d[k]); } }
	v_cvt_pk_bf16_f32 v123, v8, v9
	v_lshlrev_b32_e32 v120, 16, v155
	v_and_b32_e32 v121, 0xffff0000, v155
	global_store_dword v116, v123, s[16:17]
	s_add_u32 s16, s16, 0x40000
	s_addc_u32 s17, s17, 0
	v_pk_mul_f32 v[120:121], v[214:215], v[120:121] op_sel:[1,0] op_sel_hi:[1,1]
	v_pk_fma_f32 v[8:9], v[8:9], v[58:59], v[120:121] op_sel:[0,1,0] op_sel_hi:[1,1,1]
	global_load_dword v172, v116, s[14:15]
	s_add_u32 s14, s14, 0x40000
	s_addc_u32 s15, s15, 0
	global_load_dword v173, v116, s[14:15]
	s_add_u32 s14, s14, 0x40000
	s_addc_u32 s15, s15, 0
	global_load_dword v174, v116, s[14:15]
	s_add_u32 s14, s14, 0x40000
	s_addc_u32 s15, s15, 0
	global_load_dword v175, v116, s[14:15]
	s_add_u32 s14, s14, 0x40000
	s_addc_u32 s15, s15, 0
	global_load_dword v176, v116, s[14:15]
	s_add_u32 s14, s14, 0x40000
	s_addc_u32 s15, s15, 0
	global_load_dword v177, v116, s[14:15]
	s_add_u32 s14, s14, 0x40000
	s_addc_u32 s15, s15, 0
	global_load_dword v178, v116, s[14:15]
	s_add_u32 s14, s14, 0x40000
	s_addc_u32 s15, s15, 0
	global_load_dword v179, v116, s[14:15]
	s_add_u32 s14, s14, 0x40000
	s_addc_u32 s15, s15, 0
	global_load_dword v180, v116, s[14:15]
	s_add_u32 s14, s14, 0x40000
	s_addc_u32 s15, s15, 0
	global_load_dword v181, v116, s[14:15]
	s_add_u32 s14, s14, 0x40000
	s_addc_u32 s15, s15, 0
	global_load_dword v182, v116, s[14:15]
	s_add_u32 s14, s14, 0x40000
	s_addc_u32 s15, s15, 0
	global_load_dword v183, v116, s[14:15]
	s_add_u32 s14, s14, 0x40000
	s_addc_u32 s15, s15, 0
	global_load_dword v184, v116, s[14:15]
	s_add_u32 s14, s14, 0x40000
	s_addc_u32 s15, s15, 0
	global_load_dword v185, v116, s[14:15]
	s_add_u32 s14, s14, 0x40000
	s_addc_u32 s15, s15, 0
	global_load_dword v186, v116, s[14:15]
	s_add_u32 s14, s14, 0x40000
	s_addc_u32 s15, s15, 0
	global_load_dword v187, v116, s[14:15]
	s_add_u32 s14, s14, 0x40000
	s_addc_u32 s15, s15, 0
	s_waitcnt vmcnt(47)
	v_cvt_pk_bf16_f32 v122, v8, v9
	v_lshlrev_b32_e32 v120, 16, v156
	v_and_b32_e32 v121, 0xffff0000, v156
	global_store_dword v116, v122, s[16:17]
	s_add_u32 s16, s16, 0x40000
	s_addc_u32 s17, s17, 0
	v_pk_mul_f32 v[120:121], v[216:217], v[120:121] op_sel_hi:[0,1]
	v_pk_fma_f32 v[8:9], v[8:9], v[60:61], v[120:121] op_sel_hi:[1,0,1]
	s_waitcnt vmcnt(47)
	v_cvt_pk_bf16_f32 v123, v8, v9
	v_lshlrev_b32_e32 v120, 16, v157
	v_and_b32_e32 v121, 0xffff0000, v157
	global_store_dword v116, v123, s[16:17]
	s_add_u32 s16, s16, 0x40000
	s_addc_u32 s17, s17, 0
	v_pk_mul_f32 v[120:121], v[216:217], v[120:121] op_sel:[1,0] op_sel_hi:[1,1]
	v_pk_fma_f32 v[8:9], v[8:9], v[60:61], v[120:121] op_sel:[0,1,0] op_sel_hi:[1,1,1]
	s_waitcnt vmcnt(47)
	v_cvt_pk_bf16_f32 v122, v8, v9
	v_lshlrev_b32_e32 v120, 16, v158
	v_and_b32_e32 v121, 0xffff0000, v158
	global_store_dword v116, v122, s[16:17]
	s_add_u32 s16, s16, 0x40000
	s_addc_u32 s17, s17, 0
	v_pk_mul_f32 v[120:121], v[218:219], v[120:121] op_sel_hi:[0,1]
	v_pk_fma_f32 v[8:9], v[8:9], v[62:63], v[120:121] op_sel_hi:[1,0,1]
	s_waitcnt vmcnt(47)
	v_cvt_pk_bf16_f32 v123, v8, v9
	v_lshlrev_b32_e32 v120, 16, v159
	v_and_b32_e32 v121, 0xffff0000, v159
	global_store_dword v116, v123, s[16:17]
	s_add_u32 s16, s16, 0x40000
	s_addc_u32 s17, s17, 0
	v_pk_mul_f32 v[120:121], v[218:219], v[120:121] op_sel:[1,0] op_sel_hi:[1,1]
	v_pk_fma_f32 v[8:9], v[8:9], v[62:63], v[120:121] op_sel:[0,1,0] op_sel_hi:[1,1,1]
	s_waitcnt vmcnt(47)
	v_cvt_pk_bf16_f32 v122, v8, v9
	v_lshlrev_b32_e32 v120, 16, v160
	v_and_b32_e32 v121, 0xffff0000, v160
	global_store_dword v116, v122, s[16:17]
	s_add_u32 s16, s16, 0x40000
	s_addc_u32 s17, s17, 0
	v_pk_mul_f32 v[120:121], v[220:221], v[120:121] op_sel_hi:[0,1]
	v_pk_fma_f32 v[8:9], v[8:9], v[64:65], v[120:121] op_sel_hi:[1,0,1]
	s_waitcnt vmcnt(47)
	v_cvt_pk_bf16_f32 v123, v8, v9
	v_lshlrev_b32_e32 v120, 16, v161
	v_and_b32_e32 v121, 0xffff0000, v161
	global_store_dword v116, v123, s[16:17]
	s_add_u32 s16, s16, 0x40000
	s_addc_u32 s17, s17, 0
	v_pk_mul_f32 v[120:121], v[220:221], v[120:121] op_sel:[1,0] op_sel_hi:[1,1]
	v_pk_fma_f32 v[8:9], v[8:9], v[64:65], v[120:121] op_sel:[0,1,0] op_sel_hi:[1,1,1]
	s_waitcnt vmcnt(47)
	v_cvt_pk_bf16_f32 v122, v8, v9
	v_lshlrev_b32_e32 v120, 16, v162
	v_and_b32_e32 v121, 0xffff0000, v162
	global_store_dword v116, v122, s[16:17]
	s_add_u32 s16, s16, 0x40000
	s_addc_u32 s17, s17, 0
	v_pk_mul_f32 v[120:121], v[222:223], v[120:121] op_sel_hi:[0,1]
	v_pk_fma_f32 v[8:9], v[8:9], v[66:67], v[120:121] op_sel_hi:[1,0,1]
	s_waitcnt vmcnt(47)
	v_cvt_pk_bf16_f32 v123, v8, v9
	v_lshlrev_b32_e32 v120, 16, v163
	v_and_b32_e32 v121, 0xffff0000, v163
	global_store_dword v116, v123, s[16:17]
	s_add_u32 s16, s16, 0x40000
	s_addc_u32 s17, s17, 0
	v_pk_mul_f32 v[120:121], v[222:223], v[120:121] op_sel:[1,0] op_sel_hi:[1,1]
	v_pk_fma_f32 v[8:9], v[8:9], v[66:67], v[120:121] op_sel:[0,1,0] op_sel_hi:[1,1,1]
	s_waitcnt vmcnt(47)
	v_cvt_pk_bf16_f32 v122, v8, v9
	v_lshlrev_b32_e32 v120, 16, v164
	v_and_b32_e32 v121, 0xffff0000, v164
	global_store_dword v116, v122, s[16:17]
	s_add_u32 s16, s16, 0x40000
	s_addc_u32 s17, s17, 0
	v_pk_mul_f32 v[120:121], v[224:225], v[120:121] op_sel_hi:[0,1]
	v_pk_fma_f32 v[8:9], v[8:9], v[68:69], v[120:121] op_sel_hi:[1,0,1]
	s_waitcnt vmcnt(47)
	v_cvt_pk_bf16_f32 v123, v8, v9
	v_lshlrev_b32_e32 v120, 16, v165
	v_and_b32_e32 v121, 0xffff0000, v165
	global_store_dword v116, v123, s[16:17]
	s_add_u32 s16, s16, 0x40000
	s_addc_u32 s17, s17, 0
	v_pk_mul_f32 v[120:121], v[224:225], v[120:121] op_sel:[1,0] op_sel_hi:[1,1]
	v_pk_fma_f32 v[8:9], v[8:9], v[68:69], v[120:121] op_sel:[0,1,0] op_sel_hi:[1,1,1]
	s_waitcnt vmcnt(47)
; DI unsigned pk2(float lo, float hi) { f32x2 v = {lo, hi}; bf16x2_t b = __builtin_convertvector(v, bf16x2_t); return __builtin_bit_cast(unsigned, b); }
; DI float bflo(unsigned u) { return __uint_as_float(u << 16); }
; DI float bfhi(unsigned u) { return __uint_as_float(u & 0xffff0000u); }
; DI void phase_m_comb(int wv, const ArgP a, LAS unsigned char* lds, int dry) {
;     ...
;             for (int c = 0; c < 256; c += 64) { unsigned d[64];
; #pragma unroll
;                 for (int k = 0; k < 64; ++k) d[k] = p[(size_t)(c + k) * 65536];
; #pragma unroll
;                 for (int k = 0; k < 64; ++k) { if (!dry) p[(size_t)(c + k) * 65536] = pk2(C0, C1); const float a_ = ga[(c + k) * 4 + h], b_ = gb[(c + k) * 4 + h]; C0 = a_ * C0 + b_ * bflo(d[k]); C1 = a_ * C1 + b_ * bfhi(d[k]); } }
	v_cvt_pk_bf16_f32 v122, v8, v9
	v_lshlrev_b32_e32 v120, 16, v166
	v_and_b32_e32 v121, 0xffff0000, v166
	global_store_dword v116, v122, s[16:17]
	s_add_u32 s16, s16, 0x40000
	s_addc_u32 s17, s17, 0
	v_pk_mul_f32 v[120:121], v[226:227], v[120:121] op_sel_hi:[0,1]
	v_pk_fma_f32 v[8:9], v[8:9], v[70:71], v[120:121] op_sel_hi:[1,0,1]
	s_waitcnt vmcnt(47)
	v_cvt_pk_bf16_f32 v123, v8, v9
	v_lshlrev_b32_e32 v120, 16, v167
	v_and_b32_e32 v121, 0xffff0000, v167
	global_store_dword v116, v123, s[16:17]
	s_add_u32 s16, s16, 0x40000
	s_addc_u32 s17, s17, 0
	v_pk_mul_f32 v[120:121], v[226:227], v[120:121] op_sel:[1,0] op_sel_hi:[1,1]
	v_pk_fma_f32 v[8:9], v[8:9], v[70:71], v[120:121] op_sel:[0,1,0] op_sel_hi:[1,1,1]
	s_waitcnt vmcnt(47)
	v_cvt_pk_bf16_f32 v122, v8, v9
	v_lshlrev_b32_e32 v120, 16, v168
	v_and_b32_e32 v121, 0xffff0000, v168
	global_store_dword v116, v122, s[16:17]
	s_add_u32 s16, s16, 0x40000
	s_addc_u32 s17, s17, 0
	v_pk_mul_f32 v[120:121], v[228:229], v[120:121] op_sel_hi:[0,1]
	v_pk_fma_f32 v[8:9], v[8:9], v[72:73], v[120:121] op_sel_hi:[1,0,1]
	s_waitcnt vmcnt(47)
	v_cvt_pk_bf16_f32 v123, v8, v9
	v_lshlrev_b32_e32 v120, 16, v169
	v_and_b32_e32 v121, 0xffff0000, v169
	global_store_dword v116, v123, s[16:17]
	s_add_u32 s16, s16, 0x40000
	s_addc_u32 s17, s17, 0
	v_pk_mul_f32 v[120:121], v[228:229], v[120:121] op_sel:[1,0] op_sel_hi:[1,1]
	v_pk_fma_f32 v[8:9], v[8:9], v[72:73], v[120:121] op_sel:[0,1,0] op_sel_hi:[1,1,1]
	s_waitcnt vmcnt(47)
	v_cvt_pk_bf16_f32 v122, v8, v9
	v_lshlrev_b32_e32 v120, 16, v170
	v_and_b32_e32 v121, 0xffff0000, v170
	global_store_dword v116, v122, s[16:17]
	s_add_u32 s16, s16, 0x40000
	s_addc_u32 s17, s17, 0
	v_pk_mul_f32 v[120:121], v[230:231], v[120:121] op_sel_hi:[0,1]
	v_pk_fma_f32 v[8:9], v[8:9], v[74:75], v[120:121] op_sel_hi:[1,0,1]
	s_waitcnt vmcnt(47)
	v_cvt_pk_bf16_f32 v123, v8, v9
	v_lshlrev_b32_e32 v120, 16, v171
	v_and_b32_e32 v121, 0xffff0000, v171
	global_store_dword v116, v123, s[16:17]
	s_add_u32 s16, s16, 0x40000
	s_addc_u32 s17, s17, 0
	v_pk_mul_f32 v[120:121], v[230:231], v[120:121] op_sel:[1,0] op_sel_hi:[1,1]
	v_pk_fma_f32 v[8:9], v[8:9], v[74:75], v[120:121] op_sel:[0,1,0] op_sel_hi:[1,1,1]
	global_load_dword v140, v116, s[14:15]
	s_add_u32 s14, s14, 0x40000
	s_addc_u32 s15, s15, 0
	global_load_dword v141, v116, s[14:15]
	s_add_u32 s14, s14, 0x40000
	s_addc_u32 s15, s15, 0
	global_load_dword v142, v116, s[14:15]
	s_add_u32 s14, s14, 0x40000
	s_addc_u32 s15, s15, 0
	global_load_dword v143, v116, s[14:15]
	s_add_u32 s14, s14, 0x40000
	s_addc_u32 s15, s15, 0
	global_load_dword v144, v116, s[14:15]
	s_add_u32 s14, s14, 0x40000
	s_addc_u32 s15, s15, 0
	global_load_dword v145, v116, s[14:15]
	s_add_u32 s14, s14, 0x40000
	s_addc_u32 s15, s15, 0
	global_load_dword v146, v116, s[14:15]
	s_add_u32 s14, s14, 0x40000
	s_addc_u32 s15, s15, 0
	global_load_dword v147, v116, s[14:15]
	s_add_u32 s14, s14, 0x40000
	s_addc_u32 s15, s15, 0
	global_load_dword v148, v116, s[14:15]
	s_add_u32 s14, s14, 0x40000
	s_addc_u32 s15, s15, 0
	global_load_dword v149, v116, s[14:15]
	s_add_u32 s14, s14, 0x40000
	s_addc_u32 s15, s15, 0
	global_load_dword v150, v116, s[14:15]
	s_add_u32 s14, s14, 0x40000
	s_addc_u32 s15, s15, 0
	global_load_dword v151, v116, s[14:15]
	s_add_u32 s14, s14, 0x40000
	s_addc_u32 s15, s15, 0
	global_load_dword v152, v116, s[14:15]
	s_add_u32 s14, s14, 0x40000
	s_addc_u32 s15, s15, 0
	global_load_dword v153, v116, s[14:15]
	s_add_u32 s14, s14, 0x40000
	s_addc_u32 s15, s15, 0
	global_load_dword v154, v116, s[14:15]
	s_add_u32 s14, s14, 0x40000
	s_addc_u32 s15, s15, 0
	global_load_dword v155, v116, s[14:15]
	s_add_u32 s14, s14, 0x40000
	s_addc_u32 s15, s15, 0
	v_add_u32_e32 v118, 0x400, v118
	v_add_u32_e32 v119, 0x400, v119
	ds_read2_b32 v[12:13], v118 offset0:0 offset1:4
	ds_read2_b32 v[76:77], v119 offset0:0 offset1:4
	ds_read2_b32 v[14:15], v118 offset0:8 offset1:12
	ds_read2_b32 v[78:79], v119 offset0:8 offset1:12
	ds_read2_b32 v[16:17], v118 offset0:16 offset1:20
	ds_read2_b32 v[80:81], v119 offset0:16 offset1:20
	ds_read2_b32 v[18:19], v118 offset0:24 offset1:28
	ds_read2_b32 v[82:83], v119 offset0:24 offset1:28
	s_waitcnt lgkmcnt(0)
	ds_read2_b32 v[20:21], v118 offset0:32 offset1:36
	ds_read2_b32 v[84:85], v119 offset0:32 offset1:36
	ds_read2_b32 v[22:23], v118 offset0:40 offset1:44
	ds_read2_b32 v[86:87], v119 offset0:40 offset1:44
	ds_read2_b32 v[24:25], v118 offset0:48 offset1:52
	ds_read2_b32 v[88:89], v119 offset0:48 offset1:52
	ds_read2_b32 v[26:27], v118 offset0:56 offset1:60
	ds_read2_b32 v[90:91], v119 offset0:56 offset1:60
	s_waitcnt lgkmcnt(0)
	ds_read2_b32 v[28:29], v118 offset0:64 offset1:68
	ds_read2_b32 v[92:93], v119 offset0:64 offset1:68
	ds_read2_b32 v[30:31], v118 offset0:72 offset1:76
	ds_read2_b32 v[94:95], v119 offset0:72 offset1:76
	ds_read2_b32 v[32:33], v118 offset0:80 offset1:84
	ds_read2_b32 v[96:97], v119 offset0:80 offset1:84
	ds_read2_b32 v[34:35], v118 offset0:88 offset1:92
	ds_read2_b32 v[98:99], v119 offset0:88 offset1:92
	s_waitcnt lgkmcnt(0)
	ds_read2_b32 v[36:37], v118 offset0:96 offset1:100
	ds_read2_b32 v[100:101], v119 offset0:96 offset1:100
	ds_read2_b32 v[38:39], v118 offset0:104 offset1:108
	ds_read2_b32 v[102:103], v119 offset0:104 offset1:108
	ds_read2_b32 v[40:41], v118 offset0:112 offset1:116
	ds_read2_b32 v[104:105], v119 offset0:112 offset1:116
	ds_read2_b32 v[42:43], v118 offset0:120 offset1:124
	ds_read2_b32 v[106:107], v119 offset0:120 offset1:124
	s_waitcnt lgkmcnt(0)
; DI unsigned pk2(float lo, float hi) { f32x2 v = {lo, hi}; bf16x2_t b = __builtin_convertvector(v, bf16x2_t); return __builtin_bit_cast(unsigned, b); }
; DI float bflo(unsigned u) { return __uint_as_float(u << 16); }
; DI float bfhi(unsigned u) { return __uint_as_float(u & 0xffff0000u); }
; DI void phase_m_comb(int wv, const ArgP a, LAS unsigned char* lds, int dry) {
;     ...
;             for (int c = 0; c < 256; c += 64) { unsigned d[64];
; #pragma unroll
;                 for (int k = 0; k < 64; ++k) d[k] = p[(size_t)(c + k) * 65536];
; #pragma unroll
;                 for (int k = 0; k < 64; ++k) { if (!dry) p[(size_t)(c + k) * 65536] = pk2(C0, C1); const float a_ = ga[(c + k) * 4 + h], b_ = gb[(c + k) * 4 + h]; C0 = a_ * C0 + b_ * bflo(d[k]); C1 = a_ * C1 + b_ * bfhi(d[k]); } }
	ds_read2_b32 v[44:45], v118 offset0:128 offset1:132
	ds_read2_b32 v[108:109], v119 offset0:128 offset1:132
	ds_read2_b32 v[46:47], v118 offset0:136 offset1:140
	ds_read2_b32 v[110:111], v119 offset0:136 offset1:140
	ds_read2_b32 v[48:49], v118 offset0:144 offset1:148
	ds_read2_b32 v[112:113], v119 offset0:144 offset1:148
	ds_read2_b32 v[50:51], v118 offset0:152 offset1:156
	ds_read2_b32 v[114:115], v119 offset0:152 offset1:156
	s_waitcnt lgkmcnt(0)
	ds_read2_b32 v[52:53], v118 offset0:160 offset1:164
	ds_read2_b32 v[208:209], v119 offset0:160 offset1:164
	ds_read2_b32 v[54:55], v118 offset0:168 offset1:172
	ds_read2_b32 v[210:211], v119 offset0:168 offset1:172
	ds_read2_b32 v[56:57], v118 offset0:176 offset1:180
	ds_read2_b32 v[212:213], v119 offset0:176 offset1:180
	ds_read2_b32 v[58:59], v118 offset0:184 offset1:188
	ds_read2_b32 v[214:215], v119 offset0:184 offset1:188
	s_waitcnt lgkmcnt(0)
	ds_read2_b32 v[60:61], v118 offset0:192 offset1:196
	ds_read2_b32 v[216:217], v119 offset0:192 offset1:196
	ds_read2_b32 v[62:63], v118 offset0:200 offset1:204
	ds_read2_b32 v[218:219], v119 offset0:200 offset1:204
	ds_read2_b32 v[64:65], v118 offset0:208 offset1:212
	ds_read2_b32 v[220:221], v119 offset0:208 offset1:212
	ds_read2_b32 v[66:67], v118 offset0:216 offset1:220
	ds_read2_b32 v[222:223], v119 offset0:216 offset1:220
	s_waitcnt lgkmcnt(0)
	ds_read2_b32 v[68:69], v118 offset0:224 offset1:228
	ds_read2_b32 v[224:225], v119 offset0:224 offset1:228
	ds_read2_b32 v[70:71], v118 offset0:232 offset1:236
	ds_read2_b32 v[226:227], v119 offset0:232 offset1:236
	ds_read2_b32 v[72:73], v118 offset0:240 offset1:244
	ds_read2_b32 v[228:229], v119 offset0:240 offset1:244
	ds_read2_b32 v[74:75], v118 offset0:248 offset1:252
	ds_read2_b32 v[230:231], v119 offset0:248 offset1:252
	s_waitcnt lgkmcnt(0)
	s_waitcnt vmcnt(47)
	v_cvt_pk_bf16_f32 v122, v8, v9
	v_lshlrev_b32_e32 v120, 16, v172
	v_and_b32_e32 v121, 0xffff0000, v172
	global_store_dword v116, v122, s[16:17]
	s_add_u32 s16, s16, 0x40000
	s_addc_u32 s17, s17, 0
	v_pk_mul_f32 v[120:121], v[76:77], v[120:121] op_sel_hi:[0,1]
	v_pk_fma_f32 v[8:9], v[8:9], v[12:13], v[120:121] op_sel_hi:[1,0,1]
	s_waitcnt vmcnt(47)
	v_cvt_pk_bf16_f32 v123, v8, v9
	v_lshlrev_b32_e32 v120, 16, v173
	v_and_b32_e32 v121, 0xffff0000, v173
	global_store_dword v116, v123, s[16:17]
	s_add_u32 s16, s16, 0x40000
	s_addc_u32 s17, s17, 0
	v_pk_mul_f32 v[120:121], v[76:77], v[120:121] op_sel:[1,0] op_sel_hi:[1,1]
	v_pk_fma_f32 v[8:9], v[8:9], v[12:13], v[120:121] op_sel:[0,1,0] op_sel_hi:[1,1,1]
	s_waitcnt vmcnt(47)
	v_cvt_pk_bf16_f32 v122, v8, v9
	v_lshlrev_b32_e32 v120, 16, v174
	v_and_b32_e32 v121, 0xffff0000, v174
	global_store_dword v116, v122, s[16:17]
	s_add_u32 s16, s16, 0x40000
	s_addc_u32 s17, s17, 0
	v_pk_mul_f32 v[120:121], v[78:79], v[120:121] op_sel_hi:[0,1]
	v_pk_fma_f32 v[8:9], v[8:9], v[14:15], v[120:121] op_sel_hi:[1,0,1]
	s_waitcnt vmcnt(47)
	v_cvt_pk_bf16_f32 v123, v8, v9
	v_lshlrev_b32_e32 v120, 16, v175
	v_and_b32_e32 v121, 0xffff0000, v175
	global_store_dword v116, v123, s[16:17]
	s_add_u32 s16, s16, 0x40000
	s_addc_u32 s17, s17, 0
	v_pk_mul_f32 v[120:121], v[78:79], v[120:121] op_sel:[1,0] op_sel_hi:[1,1]
	v_pk_fma_f32 v[8:9], v[8:9], v[14:15], v[120:121] op_sel:[0,1,0] op_sel_hi:[1,1,1]
	s_waitcnt vmcnt(47)
	v_cvt_pk_bf16_f32 v122, v8, v9
	v_lshlrev_b32_e32 v120, 16, v176
	v_and_b32_e32 v121, 0xffff0000, v176
	global_store_dword v116, v122, s[16:17]
	s_add_u32 s16, s16, 0x40000
	s_addc_u32 s17, s17, 0
	v_pk_mul_f32 v[120:121], v[80:81], v[120:121] op_sel_hi:[0,1]
	v_pk_fma_f32 v[8:9], v[8:9], v[16:17], v[120:121] op_sel_hi:[1,0,1]
	s_waitcnt vmcnt(47)
	v_cvt_pk_bf16_f32 v123, v8, v9
	v_lshlrev_b32_e32 v120, 16, v177
	v_and_b32_e32 v121, 0xffff0000, v177
	global_store_dword v116, v123, s[16:17]
	s_add_u32 s16, s16, 0x40000
	s_addc_u32 s17, s17, 0
	v_pk_mul_f32 v[120:121], v[80:81], v[120:121] op_sel:[1,0] op_sel_hi:[1,1]
	v_pk_fma_f32 v[8:9], v[8:9], v[16:17], v[120:121] op_sel:[0,1,0] op_sel_hi:[1,1,1]
	s_waitcnt vmcnt(47)
	v_cvt_pk_bf16_f32 v122, v8, v9
	v_lshlrev_b32_e32 v120, 16, v178
	v_and_b32_e32 v121, 0xffff0000, v178
	global_store_dword v116, v122, s[16:17]
	s_add_u32 s16, s16, 0x40000
	s_addc_u32 s17, s17, 0
	v_pk_mul_f32 v[120:121], v[82:83], v[120:121] op_sel_hi:[0,1]
	v_pk_fma_f32 v[8:9], v[8:9], v[18:19], v[120:121] op_sel_hi:[1,0,1]
	s_waitcnt vmcnt(47)
	v_cvt_pk_bf16_f32 v123, v8, v9
	v_lshlrev_b32_e32 v120, 16, v179
	v_and_b32_e32 v121, 0xffff0000, v179
	global_store_dword v116, v123, s[16:17]
	s_add_u32 s16, s16, 0x40000
	s_addc_u32 s17, s17, 0
	v_pk_mul_f32 v[120:121], v[82:83], v[120:121] op_sel:[1,0] op_sel_hi:[1,1]
	v_pk_fma_f32 v[8:9], v[8:9], v[18:19], v[120:121] op_sel:[0,1,0] op_sel_hi:[1,1,1]
	s_waitcnt vmcnt(47)
	v_cvt_pk_bf16_f32 v122, v8, v9
	v_lshlrev_b32_e32 v120, 16, v180
	v_and_b32_e32 v121, 0xffff0000, v180
	global_store_dword v116, v122, s[16:17]
	s_add_u32 s16, s16, 0x40000
	s_addc_u32 s17, s17, 0
	v_pk_mul_f32 v[120:121], v[84:85], v[120:121] op_sel_hi:[0,1]
	v_pk_fma_f32 v[8:9], v[8:9], v[20:21], v[120:121] op_sel_hi:[1,0,1]
	s_waitcnt vmcnt(47)
	v_cvt_pk_bf16_f32 v123, v8, v9
	v_lshlrev_b32_e32 v120, 16, v181
	v_and_b32_e32 v121, 0xffff0000, v181
	global_store_dword v116, v123, s[16:17]
	s_add_u32 s16, s16, 0x40000
	s_addc_u32 s17, s17, 0
	v_pk_mul_f32 v[120:121], v[84:85], v[120:121] op_sel:[1,0] op_sel_hi:[1,1]
	v_pk_fma_f32 v[8:9], v[8:9], v[20:21], v[120:121] op_sel:[0,1,0] op_sel_hi:[1,1,1]
	s_waitcnt vmcnt(47)
; DI unsigned pk2(float lo, float hi) { f32x2 v = {lo, hi}; bf16x2_t b = __builtin_convertvector(v, bf16x2_t); return __builtin_bit_cast(unsigned, b); }
; DI float bflo(unsigned u) { return __uint_as_float(u << 16); }
; DI float bfhi(unsigned u) { return __uint_as_float(u & 0xffff0000u); }
; DI void phase_m_comb(int wv, const ArgP a, LAS unsigned char* lds, int dry) {
;     ...
;             for (int c = 0; c < 256; c += 64) { unsigned d[64];
; #pragma unroll
;                 for (int k = 0; k < 64; ++k) d[k] = p[(size_t)(c + k) * 65536];
; #pragma unroll
;                 for (int k = 0; k < 64; ++k) { if (!dry) p[(size_t)(c + k) * 65536] = pk2(C0, C1); const float a_ = ga[(c + k) * 4 + h], b_ = gb[(c + k) * 4 + h]; C0 = a_ * C0 + b_ * bflo(d[k]); C1 = a_ * C1 + b_ * bfhi(d[k]); } }
	v_cvt_pk_bf16_f32 v122, v8, v9
	v_lshlrev_b32_e32 v120, 16, v182
	v_and_b32_e32 v121, 0xffff0000, v182
	global_store_dword v116, v122, s[16:17]
	s_add_u32 s16, s16, 0x40000
	s_addc_u32 s17, s17, 0
	v_pk_mul_f32 v[120:121], v[86:87], v[120:121] op_sel_hi:[0,1]
	v_pk_fma_f32 v[8:9], v[8:9], v[22:23], v[120:121] op_sel_hi:[1,0,1]
	s_waitcnt vmcnt(47)
	v_cvt_pk_bf16_f32 v123, v8, v9
	v_lshlrev_b32_e32 v120, 16, v183
	v_and_b32_e32 v121, 0xffff0000, v183
	global_store_dword v116, v123, s[16:17]
	s_add_u32 s16, s16, 0x40000
	s_addc_u32 s17, s17, 0
	v_pk_mul_f32 v[120:121], v[86:87], v[120:121] op_sel:[1,0] op_sel_hi:[1,1]
	v_pk_fma_f32 v[8:9], v[8:9], v[22:23], v[120:121] op_sel:[0,1,0] op_sel_hi:[1,1,1]
	s_waitcnt vmcnt(47)
	v_cvt_pk_bf16_f32 v122, v8, v9
	v_lshlrev_b32_e32 v120, 16, v184
	v_and_b32_e32 v121, 0xffff0000, v184
	global_store_dword v116, v122, s[16:17]
	s_add_u32 s16, s16, 0x40000
	s_addc_u32 s17, s17, 0
	v_pk_mul_f32 v[120:121], v[88:89], v[120:121] op_sel_hi:[0,1]
	v_pk_fma_f32 v[8:9], v[8:9], v[24:25], v[120:121] op_sel_hi:[1,0,1]
	s_waitcnt vmcnt(47)
	v_cvt_pk_bf16_f32 v123, v8, v9
	v_lshlrev_b32_e32 v120, 16, v185
	v_and_b32_e32 v121, 0xffff0000, v185
	global_store_dword v116, v123, s[16:17]
	s_add_u32 s16, s16, 0x40000
	s_addc_u32 s17, s17, 0
	v_pk_mul_f32 v[120:121], v[88:89], v[120:121] op_sel:[1,0] op_sel_hi:[1,1]
	v_pk_fma_f32 v[8:9], v[8:9], v[24:25], v[120:121] op_sel:[0,1,0] op_sel_hi:[1,1,1]
	s_waitcnt vmcnt(47)
	v_cvt_pk_bf16_f32 v122, v8, v9
	v_lshlrev_b32_e32 v120, 16, v186
	v_and_b32_e32 v121, 0xffff0000, v186
	global_store_dword v116, v122, s[16:17]
	s_add_u32 s16, s16, 0x40000
	s_addc_u32 s17, s17, 0
	v_pk_mul_f32 v[120:121], v[90:91], v[120:121] op_sel_hi:[0,1]
	v_pk_fma_f32 v[8:9], v[8:9], v[26:27], v[120:121] op_sel_hi:[1,0,1]
	s_waitcnt vmcnt(47)
	v_cvt_pk_bf16_f32 v123, v8, v9
	v_lshlrev_b32_e32 v120, 16, v187
	v_and_b32_e32 v121, 0xffff0000, v187
	global_store_dword v116, v123, s[16:17]
	s_add_u32 s16, s16, 0x40000
	s_addc_u32 s17, s17, 0
	v_pk_mul_f32 v[120:121], v[90:91], v[120:121] op_sel:[1,0] op_sel_hi:[1,1]
	v_pk_fma_f32 v[8:9], v[8:9], v[26:27], v[120:121] op_sel:[0,1,0] op_sel_hi:[1,1,1]
	global_load_dword v156, v116, s[14:15]
	s_add_u32 s14, s14, 0x40000
	s_addc_u32 s15, s15, 0
	global_load_dword v157, v116, s[14:15]
	s_add_u32 s14, s14, 0x40000
	s_addc_u32 s15, s15, 0
	global_load_dword v158, v116, s[14:15]
	s_add_u32 s14, s14, 0x40000
	s_addc_u32 s15, s15, 0
	global_load_dword v159, v116, s[14:15]
	s_add_u32 s14, s14, 0x40000
	s_addc_u32 s15, s15, 0
	global_load_dword v160, v116, s[14:15]
	s_add_u32 s14, s14, 0x40000
	s_addc_u32 s15, s15, 0
	global_load_dword v161, v116, s[14:15]
	s_add_u32 s14, s14, 0x40000
	s_addc_u32 s15, s15, 0
	global_load_dword v162, v116, s[14:15]
	s_add_u32 s14, s14, 0x40000
	s_addc_u32 s15, s15, 0
	global_load_dword v163, v116, s[14:15]
	s_add_u32 s14, s14, 0x40000
	s_addc_u32 s15, s15, 0
	global_load_dword v164, v116, s[14:15]
	s_add_u32 s14, s14, 0x40000
	s_addc_u32 s15, s15, 0
	global_load_dword v165, v116, s[14:15]
	s_add_u32 s14, s14, 0x40000
	s_addc_u32 s15, s15, 0
	global_load_dword v166, v116, s[14:15]
	s_add_u32 s14, s14, 0x40000
	s_addc_u32 s15, s15, 0
	global_load_dword v167, v116, s[14:15]
	s_add_u32 s14, s14, 0x40000
	s_addc_u32 s15, s15, 0
	global_load_dword v168, v116, s[14:15]
	s_add_u32 s14, s14, 0x40000
	s_addc_u32 s15, s15, 0
	global_load_dword v169, v116, s[14:15]
	s_add_u32 s14, s14, 0x40000
	s_addc_u32 s15, s15, 0
	global_load_dword v170, v116, s[14:15]
	s_add_u32 s14, s14, 0x40000
	s_addc_u32 s15, s15, 0
	global_load_dword v171, v116, s[14:15]
	s_add_u32 s14, s14, 0x40000
	s_addc_u32 s15, s15, 0
	s_waitcnt vmcnt(47)
	v_cvt_pk_bf16_f32 v122, v8, v9
	v_lshlrev_b32_e32 v120, 16, v140
	v_and_b32_e32 v121, 0xffff0000, v140
	global_store_dword v116, v122, s[16:17]
	s_add_u32 s16, s16, 0x40000
	s_addc_u32 s17, s17, 0
	v_pk_mul_f32 v[120:121], v[92:93], v[120:121] op_sel_hi:[0,1]
	v_pk_fma_f32 v[8:9], v[8:9], v[28:29], v[120:121] op_sel_hi:[1,0,1]
	s_waitcnt vmcnt(47)
	v_cvt_pk_bf16_f32 v123, v8, v9
	v_lshlrev_b32_e32 v120, 16, v141
	v_and_b32_e32 v121, 0xffff0000, v141
	global_store_dword v116, v123, s[16:17]
	s_add_u32 s16, s16, 0x40000
	s_addc_u32 s17, s17, 0
	v_pk_mul_f32 v[120:121], v[92:93], v[120:121] op_sel:[1,0] op_sel_hi:[1,1]
	v_pk_fma_f32 v[8:9], v[8:9], v[28:29], v[120:121] op_sel:[0,1,0] op_sel_hi:[1,1,1]
	s_waitcnt vmcnt(47)
	v_cvt_pk_bf16_f32 v122, v8, v9
	v_lshlrev_b32_e32 v120, 16, v142
	v_and_b32_e32 v121, 0xffff0000, v142
	global_store_dword v116, v122, s[16:17]
	s_add_u32 s16, s16, 0x40000
	s_addc_u32 s17, s17, 0
	v_pk_mul_f32 v[120:121], v[94:95], v[120:121] op_sel_hi:[0,1]
	v_pk_fma_f32 v[8:9], v[8:9], v[30:31], v[120:121] op_sel_hi:[1,0,1]
	s_waitcnt vmcnt(47)
	v_cvt_pk_bf16_f32 v123, v8, v9
	v_lshlrev_b32_e32 v120, 16, v143
	v_and_b32_e32 v121, 0xffff0000, v143
	global_store_dword v116, v123, s[16:17]
	s_add_u32 s16, s16, 0x40000
	s_addc_u32 s17, s17, 0
	v_pk_mul_f32 v[120:121], v[94:95], v[120:121] op_sel:[1,0] op_sel_hi:[1,1]
	v_pk_fma_f32 v[8:9], v[8:9], v[30:31], v[120:121] op_sel:[0,1,0] op_sel_hi:[1,1,1]
	s_waitcnt vmcnt(47)
	v_cvt_pk_bf16_f32 v122, v8, v9
	v_lshlrev_b32_e32 v120, 16, v144
	v_and_b32_e32 v121, 0xffff0000, v144
	global_store_dword v116, v122, s[16:17]
	s_add_u32 s16, s16, 0x40000
	s_addc_u32 s17, s17, 0
	v_pk_mul_f32 v[120:121], v[96:97], v[120:121] op_sel_hi:[0,1]
	v_pk_fma_f32 v[8:9], v[8:9], v[32:33], v[120:121] op_sel_hi:[1,0,1]
	s_waitcnt vmcnt(47)
; DI unsigned pk2(float lo, float hi) { f32x2 v = {lo, hi}; bf16x2_t b = __builtin_convertvector(v, bf16x2_t); return __builtin_bit_cast(unsigned, b); }
; DI float bflo(unsigned u) { return __uint_as_float(u << 16); }
; DI float bfhi(unsigned u) { return __uint_as_float(u & 0xffff0000u); }
; DI void phase_m_comb(int wv, const ArgP a, LAS unsigned char* lds, int dry) {
;     ...
;             for (int c = 0; c < 256; c += 64) { unsigned d[64];
; #pragma unroll
;                 for (int k = 0; k < 64; ++k) d[k] = p[(size_t)(c + k) * 65536];
; #pragma unroll
;                 for (int k = 0; k < 64; ++k) { if (!dry) p[(size_t)(c + k) * 65536] = pk2(C0, C1); const float a_ = ga[(c + k) * 4 + h], b_ = gb[(c + k) * 4 + h]; C0 = a_ * C0 + b_ * bflo(d[k]); C1 = a_ * C1 + b_ * bfhi(d[k]); } }
	v_cvt_pk_bf16_f32 v123, v8, v9
	v_lshlrev_b32_e32 v120, 16, v145
	v_and_b32_e32 v121, 0xffff0000, v145
	global_store_dword v116, v123, s[16:17]
	s_add_u32 s16, s16, 0x40000
	s_addc_u32 s17, s17, 0
	v_pk_mul_f32 v[120:121], v[96:97], v[120:121] op_sel:[1,0] op_sel_hi:[1,1]
	v_pk_fma_f32 v[8:9], v[8:9], v[32:33], v[120:121] op_sel:[0,1,0] op_sel_hi:[1,1,1]
	s_waitcnt vmcnt(47)
	v_cvt_pk_bf16_f32 v122, v8, v9
	v_lshlrev_b32_e32 v120, 16, v146
	v_and_b32_e32 v121, 0xffff0000, v146
	global_store_dword v116, v122, s[16:17]
	s_add_u32 s16, s16, 0x40000
	s_addc_u32 s17, s17, 0
	v_pk_mul_f32 v[120:121], v[98:99], v[120:121] op_sel_hi:[0,1]
	v_pk_fma_f32 v[8:9], v[8:9], v[34:35], v[120:121] op_sel_hi:[1,0,1]
	s_waitcnt vmcnt(47)
	v_cvt_pk_bf16_f32 v123, v8, v9
	v_lshlrev_b32_e32 v120, 16, v147
	v_and_b32_e32 v121, 0xffff0000, v147
	global_store_dword v116, v123, s[16:17]
	s_add_u32 s16, s16, 0x40000
	s_addc_u32 s17, s17, 0
	v_pk_mul_f32 v[120:121], v[98:99], v[120:121] op_sel:[1,0] op_sel_hi:[1,1]
	v_pk_fma_f32 v[8:9], v[8:9], v[34:35], v[120:121] op_sel:[0,1,0] op_sel_hi:[1,1,1]
	s_waitcnt vmcnt(47)
	v_cvt_pk_bf16_f32 v122, v8, v9
	v_lshlrev_b32_e32 v120, 16, v148
	v_and_b32_e32 v121, 0xffff0000, v148
	global_store_dword v116, v122, s[16:17]
	s_add_u32 s16, s16, 0x40000
	s_addc_u32 s17, s17, 0
	v_pk_mul_f32 v[120:121], v[100:101], v[120:121] op_sel_hi:[0,1]
	v_pk_fma_f32 v[8:9], v[8:9], v[36:37], v[120:121] op_sel_hi:[1,0,1]
	s_waitcnt vmcnt(47)
	v_cvt_pk_bf16_f32 v123, v8, v9
	v_lshlrev_b32_e32 v120, 16, v149
	v_and_b32_e32 v121, 0xffff0000, v149
	global_store_dword v116, v123, s[16:17]
	s_add_u32 s16, s16, 0x40000
	s_addc_u32 s17, s17, 0
	v_pk_mul_f32 v[120:121], v[100:101], v[120:121] op_sel:[1,0] op_sel_hi:[1,1]
	v_pk_fma_f32 v[8:9], v[8:9], v[36:37], v[120:121] op_sel:[0,1,0] op_sel_hi:[1,1,1]
	s_waitcnt vmcnt(47)
	v_cvt_pk_bf16_f32 v122, v8, v9
	v_lshlrev_b32_e32 v120, 16, v150
	v_and_b32_e32 v121, 0xffff0000, v150
	global_store_dword v116, v122, s[16:17]
	s_add_u32 s16, s16, 0x40000
	s_addc_u32 s17, s17, 0
	v_pk_mul_f32 v[120:121], v[102:103], v[120:121] op_sel_hi:[0,1]
	v_pk_fma_f32 v[8:9], v[8:9], v[38:39], v[120:121] op_sel_hi:[1,0,1]
	s_waitcnt vmcnt(47)
	v_cvt_pk_bf16_f32 v123, v8, v9
	v_lshlrev_b32_e32 v120, 16, v151
	v_and_b32_e32 v121, 0xffff0000, v151
	global_store_dword v116, v123, s[16:17]
	s_add_u32 s16, s16, 0x40000
	s_addc_u32 s17, s17, 0
	v_pk_mul_f32 v[120:121], v[102:103], v[120:121] op_sel:[1,0] op_sel_hi:[1,1]
	v_pk_fma_f32 v[8:9], v[8:9], v[38:39], v[120:121] op_sel:[0,1,0] op_sel_hi:[1,1,1]
	s_waitcnt vmcnt(47)
	v_cvt_pk_bf16_f32 v122, v8, v9
	v_lshlrev_b32_e32 v120, 16, v152
	v_and_b32_e32 v121, 0xffff0000, v152
	global_store_dword v116, v122, s[16:17]
	s_add_u32 s16, s16, 0x40000
	s_addc_u32 s17, s17, 0
	v_pk_mul_f32 v[120:121], v[104:105], v[120:121] op_sel_hi:[0,1]
	v_pk_fma_f32 v[8:9], v[8:9], v[40:41], v[120:121] op_sel_hi:[1,0,1]
	s_waitcnt vmcnt(47)
	v_cvt_pk_bf16_f32 v123, v8, v9
	v_lshlrev_b32_e32 v120, 16, v153
	v_and_b32_e32 v121, 0xffff0000, v153
	global_store_dword v116, v123, s[16:17]
	s_add_u32 s16, s16, 0x40000
	s_addc_u32 s17, s17, 0
	v_pk_mul_f32 v[120:121], v[104:105], v[120:121] op_sel:[1,0] op_sel_hi:[1,1]
	v_pk_fma_f32 v[8:9], v[8:9], v[40:41], v[120:121] op_sel:[0,1,0] op_sel_hi:[1,1,1]
	s_waitcnt vmcnt(47)
	v_cvt_pk_bf16_f32 v122, v8, v9
	v_lshlrev_b32_e32 v120, 16, v154
	v_and_b32_e32 v121, 0xffff0000, v154
	global_store_dword v116, v122, s[16:17]
	s_add_u32 s16, s16, 0x40000
	s_addc_u32 s17, s17, 0
	v_pk_mul_f32 v[120:121], v[106:107], v[120:121] op_sel_hi:[0,1]
	v_pk_fma_f32 v[8:9], v[8:9], v[42:43], v[120:121] op_sel_hi:[1,0,1]
	s_waitcnt vmcnt(47)
	v_cvt_pk_bf16_f32 v123, v8, v9
	v_lshlrev_b32_e32 v120, 16, v155
	v_and_b32_e32 v121, 0xffff0000, v155
	global_store_dword v116, v123, s[16:17]
	s_add_u32 s16, s16, 0x40000
	s_addc_u32 s17, s17, 0
	v_pk_mul_f32 v[120:121], v[106:107], v[120:121] op_sel:[1,0] op_sel_hi:[1,1]
	v_pk_fma_f32 v[8:9], v[8:9], v[42:43], v[120:121] op_sel:[0,1,0] op_sel_hi:[1,1,1]
	global_load_dword v172, v116, s[14:15]
	s_add_u32 s14, s14, 0x40000
	s_addc_u32 s15, s15, 0
	global_load_dword v173, v116, s[14:15]
	s_add_u32 s14, s14, 0x40000
	s_addc_u32 s15, s15, 0
	global_load_dword v174, v116, s[14:15]
	s_add_u32 s14, s14, 0x40000
	s_addc_u32 s15, s15, 0
	global_load_dword v175, v116, s[14:15]
	s_add_u32 s14, s14, 0x40000
	s_addc_u32 s15, s15, 0
	global_load_dword v176, v116, s[14:15]
	s_add_u32 s14, s14, 0x40000
	s_addc_u32 s15, s15, 0
	global_load_dword v177, v116, s[14:15]
	s_add_u32 s14, s14, 0x40000
	s_addc_u32 s15, s15, 0
	global_load_dword v178, v116, s[14:15]
	s_add_u32 s14, s14, 0x40000
	s_addc_u32 s15, s15, 0
	global_load_dword v179, v116, s[14:15]
	s_add_u32 s14, s14, 0x40000
	s_addc_u32 s15, s15, 0
	global_load_dword v180, v116, s[14:15]
	s_add_u32 s14, s14, 0x40000
	s_addc_u32 s15, s15, 0
	global_load_dword v181, v116, s[14:15]
	s_add_u32 s14, s14, 0x40000
	s_addc_u32 s15, s15, 0
	global_load_dword v182, v116, s[14:15]
	s_add_u32 s14, s14, 0x40000
	s_addc_u32 s15, s15, 0
	global_load_dword v183, v116, s[14:15]
	s_add_u32 s14, s14, 0x40000
	s_addc_u32 s15, s15, 0
	global_load_dword v184, v116, s[14:15]
	s_add_u32 s14, s14, 0x40000
	s_addc_u32 s15, s15, 0
	global_load_dword v185, v116, s[14:15]
	s_add_u32 s14, s14, 0x40000
	s_addc_u32 s15, s15, 0
	global_load_dword v186, v116, s[14:15]
	s_add_u32 s14, s14, 0x40000
	s_addc_u32 s15, s15, 0
	global_load_dword v187, v116, s[14:15]
	s_add_u32 s14, s14, 0x40000
	s_addc_u32 s15, s15, 0
	s_waitcnt vmcnt(47)
; DI unsigned pk2(float lo, float hi) { f32x2 v = {lo, hi}; bf16x2_t b = __builtin_convertvector(v, bf16x2_t); return __builtin_bit_cast(unsigned, b); }
; DI float bflo(unsigned u) { return __uint_as_float(u << 16); }
; DI float bfhi(unsigned u) { return __uint_as_float(u & 0xffff0000u); }
; DI void phase_m_comb(int wv, const ArgP a, LAS unsigned char* lds, int dry) {
;     ...
;             for (int c = 0; c < 256; c += 64) { unsigned d[64];
; #pragma unroll
;                 for (int k = 0; k < 64; ++k) d[k] = p[(size_t)(c + k) * 65536];
; #pragma unroll
;                 for (int k = 0; k < 64; ++k) { if (!dry) p[(size_t)(c + k) * 65536] = pk2(C0, C1); const float a_ = ga[(c + k) * 4 + h], b_ = gb[(c + k) * 4 + h]; C0 = a_ * C0 + b_ * bflo(d[k]); C1 = a_ * C1 + b_ * bfhi(d[k]); } }
	v_cvt_pk_bf16_f32 v122, v8, v9
	v_lshlrev_b32_e32 v120, 16, v156
	v_and_b32_e32 v121, 0xffff0000, v156
	global_store_dword v116, v122, s[16:17]
	s_add_u32 s16, s16, 0x40000
	s_addc_u32 s17, s17, 0
	v_pk_mul_f32 v[120:121], v[108:109], v[120:121] op_sel_hi:[0,1]
	v_pk_fma_f32 v[8:9], v[8:9], v[44:45], v[120:121] op_sel_hi:[1,0,1]
	s_waitcnt vmcnt(47)
	v_cvt_pk_bf16_f32 v123, v8, v9
	v_lshlrev_b32_e32 v120, 16, v157
	v_and_b32_e32 v121, 0xffff0000, v157
	global_store_dword v116, v123, s[16:17]
	s_add_u32 s16, s16, 0x40000
	s_addc_u32 s17, s17, 0
	v_pk_mul_f32 v[120:121], v[108:109], v[120:121] op_sel:[1,0] op_sel_hi:[1,1]
	v_pk_fma_f32 v[8:9], v[8:9], v[44:45], v[120:121] op_sel:[0,1,0] op_sel_hi:[1,1,1]
	s_waitcnt vmcnt(47)
	v_cvt_pk_bf16_f32 v122, v8, v9
	v_lshlrev_b32_e32 v120, 16, v158
	v_and_b32_e32 v121, 0xffff0000, v158
	global_store_dword v116, v122, s[16:17]
	s_add_u32 s16, s16, 0x40000
	s_addc_u32 s17, s17, 0
	v_pk_mul_f32 v[120:121], v[110:111], v[120:121] op_sel_hi:[0,1]
	v_pk_fma_f32 v[8:9], v[8:9], v[46:47], v[120:121] op_sel_hi:[1,0,1]
	s_waitcnt vmcnt(47)
	v_cvt_pk_bf16_f32 v123, v8, v9
	v_lshlrev_b32_e32 v120, 16, v159
	v_and_b32_e32 v121, 0xffff0000, v159
	global_store_dword v116, v123, s[16:17]
	s_add_u32 s16, s16, 0x40000
	s_addc_u32 s17, s17, 0
	v_pk_mul_f32 v[120:121], v[110:111], v[120:121] op_sel:[1,0] op_sel_hi:[1,1]
	v_pk_fma_f32 v[8:9], v[8:9], v[46:47], v[120:121] op_sel:[0,1,0] op_sel_hi:[1,1,1]
	s_waitcnt vmcnt(47)
	v_cvt_pk_bf16_f32 v122, v8, v9
	v_lshlrev_b32_e32 v120, 16, v160
	v_and_b32_e32 v121, 0xffff0000, v160
	global_store_dword v116, v122, s[16:17]
	s_add_u32 s16, s16, 0x40000
	s_addc_u32 s17, s17, 0
	v_pk_mul_f32 v[120:121], v[112:113], v[120:121] op_sel_hi:[0,1]
	v_pk_fma_f32 v[8:9], v[8:9], v[48:49], v[120:121] op_sel_hi:[1,0,1]
	s_waitcnt vmcnt(47)
	v_cvt_pk_bf16_f32 v123, v8, v9
	v_lshlrev_b32_e32 v120, 16, v161
	v_and_b32_e32 v121, 0xffff0000, v161
	global_store_dword v116, v123, s[16:17]
	s_add_u32 s16, s16, 0x40000
	s_addc_u32 s17, s17, 0
	v_pk_mul_f32 v[120:121], v[112:113], v[120:121] op_sel:[1,0] op_sel_hi:[1,1]
	v_pk_fma_f32 v[8:9], v[8:9], v[48:49], v[120:121] op_sel:[0,1,0] op_sel_hi:[1,1,1]
	s_waitcnt vmcnt(47)
	v_cvt_pk_bf16_f32 v122, v8, v9
	v_lshlrev_b32_e32 v120, 16, v162
	v_and_b32_e32 v121, 0xffff0000, v162
	global_store_dword v116, v122, s[16:17]
	s_add_u32 s16, s16, 0x40000
	s_addc_u32 s17, s17, 0
	v_pk_mul_f32 v[120:121], v[114:115], v[120:121] op_sel_hi:[0,1]
	v_pk_fma_f32 v[8:9], v[8:9], v[50:51], v[120:121] op_sel_hi:[1,0,1]
	s_waitcnt vmcnt(47)
	v_cvt_pk_bf16_f32 v123, v8, v9
	v_lshlrev_b32_e32 v120, 16, v163
	v_and_b32_e32 v121, 0xffff0000, v163
	global_store_dword v116, v123, s[16:17]
	s_add_u32 s16, s16, 0x40000
	s_addc_u32 s17, s17, 0
	v_pk_mul_f32 v[120:121], v[114:115], v[120:121] op_sel:[1,0] op_sel_hi:[1,1]
	v_pk_fma_f32 v[8:9], v[8:9], v[50:51], v[120:121] op_sel:[0,1,0] op_sel_hi:[1,1,1]
	s_waitcnt vmcnt(47)
	v_cvt_pk_bf16_f32 v122, v8, v9
	v_lshlrev_b32_e32 v120, 16, v164
	v_and_b32_e32 v121, 0xffff0000, v164
	global_store_dword v116, v122, s[16:17]
	s_add_u32 s16, s16, 0x40000
	s_addc_u32 s17, s17, 0
	v_pk_mul_f32 v[120:121], v[208:209], v[120:121] op_sel_hi:[0,1]
	v_pk_fma_f32 v[8:9], v[8:9], v[52:53], v[120:121] op_sel_hi:[1,0,1]
	s_waitcnt vmcnt(47)
	v_cvt_pk_bf16_f32 v123, v8, v9
	v_lshlrev_b32_e32 v120, 16, v165
	v_and_b32_e32 v121, 0xffff0000, v165
	global_store_dword v116, v123, s[16:17]
	s_add_u32 s16, s16, 0x40000
	s_addc_u32 s17, s17, 0
	v_pk_mul_f32 v[120:121], v[208:209], v[120:121] op_sel:[1,0] op_sel_hi:[1,1]
	v_pk_fma_f32 v[8:9], v[8:9], v[52:53], v[120:121] op_sel:[0,1,0] op_sel_hi:[1,1,1]
	s_waitcnt vmcnt(47)
	v_cvt_pk_bf16_f32 v122, v8, v9
	v_lshlrev_b32_e32 v120, 16, v166
	v_and_b32_e32 v121, 0xffff0000, v166
	global_store_dword v116, v122, s[16:17]
	s_add_u32 s16, s16, 0x40000
	s_addc_u32 s17, s17, 0
	v_pk_mul_f32 v[120:121], v[210:211], v[120:121] op_sel_hi:[0,1]
	v_pk_fma_f32 v[8:9], v[8:9], v[54:55], v[120:121] op_sel_hi:[1,0,1]
	s_waitcnt vmcnt(47)
	v_cvt_pk_bf16_f32 v123, v8, v9
	v_lshlrev_b32_e32 v120, 16, v167
	v_and_b32_e32 v121, 0xffff0000, v167
	global_store_dword v116, v123, s[16:17]
	s_add_u32 s16, s16, 0x40000
	s_addc_u32 s17, s17, 0
	v_pk_mul_f32 v[120:121], v[210:211], v[120:121] op_sel:[1,0] op_sel_hi:[1,1]
	v_pk_fma_f32 v[8:9], v[8:9], v[54:55], v[120:121] op_sel:[0,1,0] op_sel_hi:[1,1,1]
	s_waitcnt vmcnt(47)
	v_cvt_pk_bf16_f32 v122, v8, v9
	v_lshlrev_b32_e32 v120, 16, v168
	v_and_b32_e32 v121, 0xffff0000, v168
	global_store_dword v116, v122, s[16:17]
	s_add_u32 s16, s16, 0x40000
	s_addc_u32 s17, s17, 0
	v_pk_mul_f32 v[120:121], v[212:213], v[120:121] op_sel_hi:[0,1]
	v_pk_fma_f32 v[8:9], v[8:9], v[56:57], v[120:121] op_sel_hi:[1,0,1]
	s_waitcnt vmcnt(47)
	v_cvt_pk_bf16_f32 v123, v8, v9
	v_lshlrev_b32_e32 v120, 16, v169
	v_and_b32_e32 v121, 0xffff0000, v169
	global_store_dword v116, v123, s[16:17]
	s_add_u32 s16, s16, 0x40000
	s_addc_u32 s17, s17, 0
	v_pk_mul_f32 v[120:121], v[212:213], v[120:121] op_sel:[1,0] op_sel_hi:[1,1]
	v_pk_fma_f32 v[8:9], v[8:9], v[56:57], v[120:121] op_sel:[0,1,0] op_sel_hi:[1,1,1]
	s_waitcnt vmcnt(47)
	v_cvt_pk_bf16_f32 v122, v8, v9
	v_lshlrev_b32_e32 v120, 16, v170
	v_and_b32_e32 v121, 0xffff0000, v170
	global_store_dword v116, v122, s[16:17]
	s_add_u32 s16, s16, 0x40000
	s_addc_u32 s17, s17, 0
	v_pk_mul_f32 v[120:121], v[214:215], v[120:121] op_sel_hi:[0,1]
	v_pk_fma_f32 v[8:9], v[8:9], v[58:59], v[120:121] op_sel_hi:[1,0,1]
	s_waitcnt vmcnt(47)
; DI unsigned pk2(float lo, float hi) { f32x2 v = {lo, hi}; bf16x2_t b = __builtin_convertvector(v, bf16x2_t); return __builtin_bit_cast(unsigned, b); }
; DI float bflo(unsigned u) { return __uint_as_float(u << 16); }
; DI float bfhi(unsigned u) { return __uint_as_float(u & 0xffff0000u); }
; DI void phase_m_comb(int wv, const ArgP a, LAS unsigned char* lds, int dry) {
;     ...
;             for (int c = 0; c < 256; c += 64) { unsigned d[64];
; #pragma unroll
;                 for (int k = 0; k < 64; ++k) d[k] = p[(size_t)(c + k) * 65536];
; #pragma unroll
;                 for (int k = 0; k < 64; ++k) { if (!dry) p[(size_t)(c + k) * 65536] = pk2(C0, C1); const float a_ = ga[(c + k) * 4 + h], b_ = gb[(c + k) * 4 + h]; C0 = a_ * C0 + b_ * bflo(d[k]); C1 = a_ * C1 + b_ * bfhi(d[k]); } }
	v_cvt_pk_bf16_f32 v123, v8, v9
	v_lshlrev_b32_e32 v120, 16, v171
	v_and_b32_e32 v121, 0xffff0000, v171
	global_store_dword v116, v123, s[16:17]
	s_add_u32 s16, s16, 0x40000
	s_addc_u32 s17, s17, 0
	v_pk_mul_f32 v[120:121], v[214:215], v[120:121] op_sel:[1,0] op_sel_hi:[1,1]
	v_pk_fma_f32 v[8:9], v[8:9], v[58:59], v[120:121] op_sel:[0,1,0] op_sel_hi:[1,1,1]
	global_load_dword v140, v116, s[14:15]
	s_add_u32 s14, s14, 0x40000
	s_addc_u32 s15, s15, 0
	global_load_dword v141, v116, s[14:15]
	s_add_u32 s14, s14, 0x40000
	s_addc_u32 s15, s15, 0
	global_load_dword v142, v116, s[14:15]
	s_add_u32 s14, s14, 0x40000
	s_addc_u32 s15, s15, 0
	global_load_dword v143, v116, s[14:15]
	s_add_u32 s14, s14, 0x40000
	s_addc_u32 s15, s15, 0
	global_load_dword v144, v116, s[14:15]
	s_add_u32 s14, s14, 0x40000
	s_addc_u32 s15, s15, 0
	global_load_dword v145, v116, s[14:15]
	s_add_u32 s14, s14, 0x40000
	s_addc_u32 s15, s15, 0
	global_load_dword v146, v116, s[14:15]
	s_add_u32 s14, s14, 0x40000
	s_addc_u32 s15, s15, 0
	global_load_dword v147, v116, s[14:15]
	s_add_u32 s14, s14, 0x40000
	s_addc_u32 s15, s15, 0
	global_load_dword v148, v116, s[14:15]
	s_add_u32 s14, s14, 0x40000
	s_addc_u32 s15, s15, 0
	global_load_dword v149, v116, s[14:15]
	s_add_u32 s14, s14, 0x40000
	s_addc_u32 s15, s15, 0
	global_load_dword v150, v116, s[14:15]
	s_add_u32 s14, s14, 0x40000
	s_addc_u32 s15, s15, 0
	global_load_dword v151, v116, s[14:15]
	s_add_u32 s14, s14, 0x40000
	s_addc_u32 s15, s15, 0
	global_load_dword v152, v116, s[14:15]
	s_add_u32 s14, s14, 0x40000
	s_addc_u32 s15, s15, 0
	global_load_dword v153, v116, s[14:15]
	s_add_u32 s14, s14, 0x40000
	s_addc_u32 s15, s15, 0
	global_load_dword v154, v116, s[14:15]
	s_add_u32 s14, s14, 0x40000
	s_addc_u32 s15, s15, 0
	global_load_dword v155, v116, s[14:15]
	s_add_u32 s14, s14, 0x40000
	s_addc_u32 s15, s15, 0
	s_waitcnt vmcnt(47)
	v_cvt_pk_bf16_f32 v122, v8, v9
	v_lshlrev_b32_e32 v120, 16, v172
	v_and_b32_e32 v121, 0xffff0000, v172
	global_store_dword v116, v122, s[16:17]
	s_add_u32 s16, s16, 0x40000
	s_addc_u32 s17, s17, 0
	v_pk_mul_f32 v[120:121], v[216:217], v[120:121] op_sel_hi:[0,1]
	v_pk_fma_f32 v[8:9], v[8:9], v[60:61], v[120:121] op_sel_hi:[1,0,1]
	s_waitcnt vmcnt(47)
	v_cvt_pk_bf16_f32 v123, v8, v9
	v_lshlrev_b32_e32 v120, 16, v173
	v_and_b32_e32 v121, 0xffff0000, v173
	global_store_dword v116, v123, s[16:17]
	s_add_u32 s16, s16, 0x40000
	s_addc_u32 s17, s17, 0
	v_pk_mul_f32 v[120:121], v[216:217], v[120:121] op_sel:[1,0] op_sel_hi:[1,1]
	v_pk_fma_f32 v[8:9], v[8:9], v[60:61], v[120:121] op_sel:[0,1,0] op_sel_hi:[1,1,1]
	s_waitcnt vmcnt(47)
	v_cvt_pk_bf16_f32 v122, v8, v9
	v_lshlrev_b32_e32 v120, 16, v174
	v_and_b32_e32 v121, 0xffff0000, v174
	global_store_dword v116, v122, s[16:17]
	s_add_u32 s16, s16, 0x40000
	s_addc_u32 s17, s17, 0
	v_pk_mul_f32 v[120:121], v[218:219], v[120:121] op_sel_hi:[0,1]
	v_pk_fma_f32 v[8:9], v[8:9], v[62:63], v[120:121] op_sel_hi:[1,0,1]
	s_waitcnt vmcnt(47)
	v_cvt_pk_bf16_f32 v123, v8, v9
	v_lshlrev_b32_e32 v120, 16, v175
	v_and_b32_e32 v121, 0xffff0000, v175
	global_store_dword v116, v123, s[16:17]
	s_add_u32 s16, s16, 0x40000
	s_addc_u32 s17, s17, 0
	v_pk_mul_f32 v[120:121], v[218:219], v[120:121] op_sel:[1,0] op_sel_hi:[1,1]
	v_pk_fma_f32 v[8:9], v[8:9], v[62:63], v[120:121] op_sel:[0,1,0] op_sel_hi:[1,1,1]
	s_waitcnt vmcnt(47)
	v_cvt_pk_bf16_f32 v122, v8, v9
	v_lshlrev_b32_e32 v120, 16, v176
	v_and_b32_e32 v121, 0xffff0000, v176
	global_store_dword v116, v122, s[16:17]
	s_add_u32 s16, s16, 0x40000
	s_addc_u32 s17, s17, 0
	v_pk_mul_f32 v[120:121], v[220:221], v[120:121] op_sel_hi:[0,1]
	v_pk_fma_f32 v[8:9], v[8:9], v[64:65], v[120:121] op_sel_hi:[1,0,1]
	s_waitcnt vmcnt(47)
	v_cvt_pk_bf16_f32 v123, v8, v9
	v_lshlrev_b32_e32 v120, 16, v177
	v_and_b32_e32 v121, 0xffff0000, v177
	global_store_dword v116, v123, s[16:17]
	s_add_u32 s16, s16, 0x40000
	s_addc_u32 s17, s17, 0
	v_pk_mul_f32 v[120:121], v[220:221], v[120:121] op_sel:[1,0] op_sel_hi:[1,1]
	v_pk_fma_f32 v[8:9], v[8:9], v[64:65], v[120:121] op_sel:[0,1,0] op_sel_hi:[1,1,1]
	s_waitcnt vmcnt(47)
	v_cvt_pk_bf16_f32 v122, v8, v9
	v_lshlrev_b32_e32 v120, 16, v178
	v_and_b32_e32 v121, 0xffff0000, v178
	global_store_dword v116, v122, s[16:17]
	s_add_u32 s16, s16, 0x40000
	s_addc_u32 s17, s17, 0
	v_pk_mul_f32 v[120:121], v[222:223], v[120:121] op_sel_hi:[0,1]
	v_pk_fma_f32 v[8:9], v[8:9], v[66:67], v[120:121] op_sel_hi:[1,0,1]
	s_waitcnt vmcnt(47)
	v_cvt_pk_bf16_f32 v123, v8, v9
	v_lshlrev_b32_e32 v120, 16, v179
	v_and_b32_e32 v121, 0xffff0000, v179
	global_store_dword v116, v123, s[16:17]
	s_add_u32 s16, s16, 0x40000
	s_addc_u32 s17, s17, 0
	v_pk_mul_f32 v[120:121], v[222:223], v[120:121] op_sel:[1,0] op_sel_hi:[1,1]
	v_pk_fma_f32 v[8:9], v[8:9], v[66:67], v[120:121] op_sel:[0,1,0] op_sel_hi:[1,1,1]
	s_waitcnt vmcnt(47)
	v_cvt_pk_bf16_f32 v122, v8, v9
	v_lshlrev_b32_e32 v120, 16, v180
	v_and_b32_e32 v121, 0xffff0000, v180
	global_store_dword v116, v122, s[16:17]
	s_add_u32 s16, s16, 0x40000
	s_addc_u32 s17, s17, 0
	v_pk_mul_f32 v[120:121], v[224:225], v[120:121] op_sel_hi:[0,1]
	v_pk_fma_f32 v[8:9], v[8:9], v[68:69], v[120:121] op_sel_hi:[1,0,1]
	s_waitcnt vmcnt(47)
	v_cvt_pk_bf16_f32 v123, v8, v9
	v_lshlrev_b32_e32 v120, 16, v181
	v_and_b32_e32 v121, 0xffff0000, v181
	global_store_dword v116, v123, s[16:17]
	s_add_u32 s16, s16, 0x40000
	s_addc_u32 s17, s17, 0
	v_pk_mul_f32 v[120:121], v[224:225], v[120:121] op_sel:[1,0] op_sel_hi:[1,1]
	v_pk_fma_f32 v[8:9], v[8:9], v[68:69], v[120:121] op_sel:[0,1,0] op_sel_hi:[1,1,1]
	s_waitcnt vmcnt(47)
; DI unsigned pk2(float lo, float hi) { f32x2 v = {lo, hi}; bf16x2_t b = __builtin_convertvector(v, bf16x2_t); return __builtin_bit_cast(unsigned, b); }
; DI float bflo(unsigned u) { return __uint_as_float(u << 16); }
; DI float bfhi(unsigned u) { return __uint_as_float(u & 0xffff0000u); }
; DI void phase_m_comb(int wv, const ArgP a, LAS unsigned char* lds, int dry) {
;     ...
;             for (int c = 0; c < 256; c += 64) { unsigned d[64];
; #pragma unroll
;                 for (int k = 0; k < 64; ++k) d[k] = p[(size_t)(c + k) * 65536];
; #pragma unroll
;                 for (int k = 0; k < 64; ++k) { if (!dry) p[(size_t)(c + k) * 65536] = pk2(C0, C1); const float a_ = ga[(c + k) * 4 + h], b_ = gb[(c + k) * 4 + h]; C0 = a_ * C0 + b_ * bflo(d[k]); C1 = a_ * C1 + b_ * bfhi(d[k]); } }
	v_cvt_pk_bf16_f32 v122, v8, v9
	v_lshlrev_b32_e32 v120, 16, v182
	v_and_b32_e32 v121, 0xffff0000, v182
	global_store_dword v116, v122, s[16:17]
	s_add_u32 s16, s16, 0x40000
	s_addc_u32 s17, s17, 0
	v_pk_mul_f32 v[120:121], v[226:227], v[120:121] op_sel_hi:[0,1]
	v_pk_fma_f32 v[8:9], v[8:9], v[70:71], v[120:121] op_sel_hi:[1,0,1]
	s_waitcnt vmcnt(47)
	v_cvt_pk_bf16_f32 v123, v8, v9
	v_lshlrev_b32_e32 v120, 16, v183
	v_and_b32_e32 v121, 0xffff0000, v183
	global_store_dword v116, v123, s[16:17]
	s_add_u32 s16, s16, 0x40000
	s_addc_u32 s17, s17, 0
	v_pk_mul_f32 v[120:121], v[226:227], v[120:121] op_sel:[1,0] op_sel_hi:[1,1]
	v_pk_fma_f32 v[8:9], v[8:9], v[70:71], v[120:121] op_sel:[0,1,0] op_sel_hi:[1,1,1]
	s_waitcnt vmcnt(47)
	v_cvt_pk_bf16_f32 v122, v8, v9
	v_lshlrev_b32_e32 v120, 16, v184
	v_and_b32_e32 v121, 0xffff0000, v184
	global_store_dword v116, v122, s[16:17]
	s_add_u32 s16, s16, 0x40000
	s_addc_u32 s17, s17, 0
	v_pk_mul_f32 v[120:121], v[228:229], v[120:121] op_sel_hi:[0,1]
	v_pk_fma_f32 v[8:9], v[8:9], v[72:73], v[120:121] op_sel_hi:[1,0,1]
	s_waitcnt vmcnt(47)
	v_cvt_pk_bf16_f32 v123, v8, v9
	v_lshlrev_b32_e32 v120, 16, v185
	v_and_b32_e32 v121, 0xffff0000, v185
	global_store_dword v116, v123, s[16:17]
	s_add_u32 s16, s16, 0x40000
	s_addc_u32 s17, s17, 0
	v_pk_mul_f32 v[120:121], v[228:229], v[120:121] op_sel:[1,0] op_sel_hi:[1,1]
	v_pk_fma_f32 v[8:9], v[8:9], v[72:73], v[120:121] op_sel:[0,1,0] op_sel_hi:[1,1,1]
	s_waitcnt vmcnt(47)
	v_cvt_pk_bf16_f32 v122, v8, v9
	v_lshlrev_b32_e32 v120, 16, v186
	v_and_b32_e32 v121, 0xffff0000, v186
	global_store_dword v116, v122, s[16:17]
	s_add_u32 s16, s16, 0x40000
	s_addc_u32 s17, s17, 0
	v_pk_mul_f32 v[120:121], v[230:231], v[120:121] op_sel_hi:[0,1]
	v_pk_fma_f32 v[8:9], v[8:9], v[74:75], v[120:121] op_sel_hi:[1,0,1]
	s_waitcnt vmcnt(47)
	v_cvt_pk_bf16_f32 v123, v8, v9
	v_lshlrev_b32_e32 v120, 16, v187
	v_and_b32_e32 v121, 0xffff0000, v187
	global_store_dword v116, v123, s[16:17]
	s_add_u32 s16, s16, 0x40000
	s_addc_u32 s17, s17, 0
	v_pk_mul_f32 v[120:121], v[230:231], v[120:121] op_sel:[1,0] op_sel_hi:[1,1]
	v_pk_fma_f32 v[8:9], v[8:9], v[74:75], v[120:121] op_sel:[0,1,0] op_sel_hi:[1,1,1]
	global_load_dword v156, v116, s[14:15]
	s_add_u32 s14, s14, 0x40000
	s_addc_u32 s15, s15, 0
	global_load_dword v157, v116, s[14:15]
	s_add_u32 s14, s14, 0x40000
	s_addc_u32 s15, s15, 0
	global_load_dword v158, v116, s[14:15]
	s_add_u32 s14, s14, 0x40000
	s_addc_u32 s15, s15, 0
	global_load_dword v159, v116, s[14:15]
	s_add_u32 s14, s14, 0x40000
	s_addc_u32 s15, s15, 0
	global_load_dword v160, v116, s[14:15]
	s_add_u32 s14, s14, 0x40000
	s_addc_u32 s15, s15, 0
	global_load_dword v161, v116, s[14:15]
	s_add_u32 s14, s14, 0x40000
	s_addc_u32 s15, s15, 0
	global_load_dword v162, v116, s[14:15]
	s_add_u32 s14, s14, 0x40000
	s_addc_u32 s15, s15, 0
	global_load_dword v163, v116, s[14:15]
	s_add_u32 s14, s14, 0x40000
	s_addc_u32 s15, s15, 0
	global_load_dword v164, v116, s[14:15]
	s_add_u32 s14, s14, 0x40000
	s_addc_u32 s15, s15, 0
	global_load_dword v165, v116, s[14:15]
	s_add_u32 s14, s14, 0x40000
	s_addc_u32 s15, s15, 0
	global_load_dword v166, v116, s[14:15]
	s_add_u32 s14, s14, 0x40000
	s_addc_u32 s15, s15, 0
	global_load_dword v167, v116, s[14:15]
	s_add_u32 s14, s14, 0x40000
	s_addc_u32 s15, s15, 0
	global_load_dword v168, v116, s[14:15]
	s_add_u32 s14, s14, 0x40000
	s_addc_u32 s15, s15, 0
	global_load_dword v169, v116, s[14:15]
	s_add_u32 s14, s14, 0x40000
	s_addc_u32 s15, s15, 0
	global_load_dword v170, v116, s[14:15]
	s_add_u32 s14, s14, 0x40000
	s_addc_u32 s15, s15, 0
	global_load_dword v171, v116, s[14:15]
	s_add_u32 s14, s14, 0x40000
	s_addc_u32 s15, s15, 0
	v_add_u32_e32 v118, 0x400, v118
	v_add_u32_e32 v119, 0x400, v119
	ds_read2_b32 v[12:13], v118 offset0:0 offset1:4
	ds_read2_b32 v[76:77], v119 offset0:0 offset1:4
	ds_read2_b32 v[14:15], v118 offset0:8 offset1:12
	ds_read2_b32 v[78:79], v119 offset0:8 offset1:12
	ds_read2_b32 v[16:17], v118 offset0:16 offset1:20
	ds_read2_b32 v[80:81], v119 offset0:16 offset1:20
	ds_read2_b32 v[18:19], v118 offset0:24 offset1:28
	ds_read2_b32 v[82:83], v119 offset0:24 offset1:28
	s_waitcnt lgkmcnt(0)
	ds_read2_b32 v[20:21], v118 offset0:32 offset1:36
	ds_read2_b32 v[84:85], v119 offset0:32 offset1:36
	ds_read2_b32 v[22:23], v118 offset0:40 offset1:44
	ds_read2_b32 v[86:87], v119 offset0:40 offset1:44
	ds_read2_b32 v[24:25], v118 offset0:48 offset1:52
	ds_read2_b32 v[88:89], v119 offset0:48 offset1:52
	ds_read2_b32 v[26:27], v118 offset0:56 offset1:60
	ds_read2_b32 v[90:91], v119 offset0:56 offset1:60
	s_waitcnt lgkmcnt(0)
	ds_read2_b32 v[28:29], v118 offset0:64 offset1:68
	ds_read2_b32 v[92:93], v119 offset0:64 offset1:68
	ds_read2_b32 v[30:31], v118 offset0:72 offset1:76
	ds_read2_b32 v[94:95], v119 offset0:72 offset1:76
	ds_read2_b32 v[32:33], v118 offset0:80 offset1:84
	ds_read2_b32 v[96:97], v119 offset0:80 offset1:84
	ds_read2_b32 v[34:35], v118 offset0:88 offset1:92
	ds_read2_b32 v[98:99], v119 offset0:88 offset1:92
	s_waitcnt lgkmcnt(0)
	ds_read2_b32 v[36:37], v118 offset0:96 offset1:100
	ds_read2_b32 v[100:101], v119 offset0:96 offset1:100
	ds_read2_b32 v[38:39], v118 offset0:104 offset1:108
	ds_read2_b32 v[102:103], v119 offset0:104 offset1:108
	ds_read2_b32 v[40:41], v118 offset0:112 offset1:116
	ds_read2_b32 v[104:105], v119 offset0:112 offset1:116
	ds_read2_b32 v[42:43], v118 offset0:120 offset1:124
	ds_read2_b32 v[106:107], v119 offset0:120 offset1:124
	s_waitcnt lgkmcnt(0)
; DI unsigned pk2(float lo, float hi) { f32x2 v = {lo, hi}; bf16x2_t b = __builtin_convertvector(v, bf16x2_t); return __builtin_bit_cast(unsigned, b); }
; DI float bflo(unsigned u) { return __uint_as_float(u << 16); }
; DI float bfhi(unsigned u) { return __uint_as_float(u & 0xffff0000u); }
; DI void phase_m_comb(int wv, const ArgP a, LAS unsigned char* lds, int dry) {
;     ...
;             for (int c = 0; c < 256; c += 64) { unsigned d[64];
; #pragma unroll
;                 for (int k = 0; k < 64; ++k) d[k] = p[(size_t)(c + k) * 65536];
; #pragma unroll
;                 for (int k = 0; k < 64; ++k) { if (!dry) p[(size_t)(c + k) * 65536] = pk2(C0, C1); const float a_ = ga[(c + k) * 4 + h], b_ = gb[(c + k) * 4 + h]; C0 = a_ * C0 + b_ * bflo(d[k]); C1 = a_ * C1 + b_ * bfhi(d[k]); } }
	ds_read2_b32 v[44:45], v118 offset0:128 offset1:132
	ds_read2_b32 v[108:109], v119 offset0:128 offset1:132
	ds_read2_b32 v[46:47], v118 offset0:136 offset1:140
	ds_read2_b32 v[110:111], v119 offset0:136 offset1:140
	ds_read2_b32 v[48:49], v118 offset0:144 offset1:148
	ds_read2_b32 v[112:113], v119 offset0:144 offset1:148
	ds_read2_b32 v[50:51], v118 offset0:152 offset1:156
	ds_read2_b32 v[114:115], v119 offset0:152 offset1:156
	s_waitcnt lgkmcnt(0)
	ds_read2_b32 v[52:53], v118 offset0:160 offset1:164
	ds_read2_b32 v[208:209], v119 offset0:160 offset1:164
	ds_read2_b32 v[54:55], v118 offset0:168 offset1:172
	ds_read2_b32 v[210:211], v119 offset0:168 offset1:172
	ds_read2_b32 v[56:57], v118 offset0:176 offset1:180
	ds_read2_b32 v[212:213], v119 offset0:176 offset1:180
	ds_read2_b32 v[58:59], v118 offset0:184 offset1:188
	ds_read2_b32 v[214:215], v119 offset0:184 offset1:188
	s_waitcnt lgkmcnt(0)
	ds_read2_b32 v[60:61], v118 offset0:192 offset1:196
	ds_read2_b32 v[216:217], v119 offset0:192 offset1:196
	ds_read2_b32 v[62:63], v118 offset0:200 offset1:204
	ds_read2_b32 v[218:219], v119 offset0:200 offset1:204
	ds_read2_b32 v[64:65], v118 offset0:208 offset1:212
	ds_read2_b32 v[220:221], v119 offset0:208 offset1:212
	ds_read2_b32 v[66:67], v118 offset0:216 offset1:220
	ds_read2_b32 v[222:223], v119 offset0:216 offset1:220
	s_waitcnt lgkmcnt(0)
	ds_read2_b32 v[68:69], v118 offset0:224 offset1:228
	ds_read2_b32 v[224:225], v119 offset0:224 offset1:228
	ds_read2_b32 v[70:71], v118 offset0:232 offset1:236
	ds_read2_b32 v[226:227], v119 offset0:232 offset1:236
	ds_read2_b32 v[72:73], v118 offset0:240 offset1:244
	ds_read2_b32 v[228:229], v119 offset0:240 offset1:244
	ds_read2_b32 v[74:75], v118 offset0:248 offset1:252
	ds_read2_b32 v[230:231], v119 offset0:248 offset1:252
	s_waitcnt lgkmcnt(0)
	s_waitcnt vmcnt(47)
	v_cvt_pk_bf16_f32 v122, v8, v9
	v_lshlrev_b32_e32 v120, 16, v140
	v_and_b32_e32 v121, 0xffff0000, v140
	global_store_dword v116, v122, s[16:17]
	s_add_u32 s16, s16, 0x40000
	s_addc_u32 s17, s17, 0
	v_pk_mul_f32 v[120:121], v[76:77], v[120:121] op_sel_hi:[0,1]
	v_pk_fma_f32 v[8:9], v[8:9], v[12:13], v[120:121] op_sel_hi:[1,0,1]
	s_waitcnt vmcnt(47)
	v_cvt_pk_bf16_f32 v123, v8, v9
	v_lshlrev_b32_e32 v120, 16, v141
	v_and_b32_e32 v121, 0xffff0000, v141
	global_store_dword v116, v123, s[16:17]
	s_add_u32 s16, s16, 0x40000
	s_addc_u32 s17, s17, 0
	v_pk_mul_f32 v[120:121], v[76:77], v[120:121] op_sel:[1,0] op_sel_hi:[1,1]
	v_pk_fma_f32 v[8:9], v[8:9], v[12:13], v[120:121] op_sel:[0,1,0] op_sel_hi:[1,1,1]
	s_waitcnt vmcnt(47)
	v_cvt_pk_bf16_f32 v122, v8, v9
	v_lshlrev_b32_e32 v120, 16, v142
	v_and_b32_e32 v121, 0xffff0000, v142
	global_store_dword v116, v122, s[16:17]
	s_add_u32 s16, s16, 0x40000
	s_addc_u32 s17, s17, 0
	v_pk_mul_f32 v[120:121], v[78:79], v[120:121] op_sel_hi:[0,1]
	v_pk_fma_f32 v[8:9], v[8:9], v[14:15], v[120:121] op_sel_hi:[1,0,1]
	s_waitcnt vmcnt(47)
	v_cvt_pk_bf16_f32 v123, v8, v9
	v_lshlrev_b32_e32 v120, 16, v143
	v_and_b32_e32 v121, 0xffff0000, v143
	global_store_dword v116, v123, s[16:17]
	s_add_u32 s16, s16, 0x40000
	s_addc_u32 s17, s17, 0
	v_pk_mul_f32 v[120:121], v[78:79], v[120:121] op_sel:[1,0] op_sel_hi:[1,1]
	v_pk_fma_f32 v[8:9], v[8:9], v[14:15], v[120:121] op_sel:[0,1,0] op_sel_hi:[1,1,1]
	s_waitcnt vmcnt(47)
	v_cvt_pk_bf16_f32 v122, v8, v9
	v_lshlrev_b32_e32 v120, 16, v144
	v_and_b32_e32 v121, 0xffff0000, v144
	global_store_dword v116, v122, s[16:17]
	s_add_u32 s16, s16, 0x40000
	s_addc_u32 s17, s17, 0
	v_pk_mul_f32 v[120:121], v[80:81], v[120:121] op_sel_hi:[0,1]
	v_pk_fma_f32 v[8:9], v[8:9], v[16:17], v[120:121] op_sel_hi:[1,0,1]
	s_waitcnt vmcnt(47)
	v_cvt_pk_bf16_f32 v123, v8, v9
	v_lshlrev_b32_e32 v120, 16, v145
	v_and_b32_e32 v121, 0xffff0000, v145
	global_store_dword v116, v123, s[16:17]
	s_add_u32 s16, s16, 0x40000
	s_addc_u32 s17, s17, 0
	v_pk_mul_f32 v[120:121], v[80:81], v[120:121] op_sel:[1,0] op_sel_hi:[1,1]
	v_pk_fma_f32 v[8:9], v[8:9], v[16:17], v[120:121] op_sel:[0,1,0] op_sel_hi:[1,1,1]
	s_waitcnt vmcnt(47)
	v_cvt_pk_bf16_f32 v122, v8, v9
	v_lshlrev_b32_e32 v120, 16, v146
	v_and_b32_e32 v121, 0xffff0000, v146
	global_store_dword v116, v122, s[16:17]
	s_add_u32 s16, s16, 0x40000
	s_addc_u32 s17, s17, 0
	v_pk_mul_f32 v[120:121], v[82:83], v[120:121] op_sel_hi:[0,1]
	v_pk_fma_f32 v[8:9], v[8:9], v[18:19], v[120:121] op_sel_hi:[1,0,1]
	s_waitcnt vmcnt(47)
	v_cvt_pk_bf16_f32 v123, v8, v9
	v_lshlrev_b32_e32 v120, 16, v147
	v_and_b32_e32 v121, 0xffff0000, v147
	global_store_dword v116, v123, s[16:17]
	s_add_u32 s16, s16, 0x40000
	s_addc_u32 s17, s17, 0
	v_pk_mul_f32 v[120:121], v[82:83], v[120:121] op_sel:[1,0] op_sel_hi:[1,1]
	v_pk_fma_f32 v[8:9], v[8:9], v[18:19], v[120:121] op_sel:[0,1,0] op_sel_hi:[1,1,1]
	s_waitcnt vmcnt(47)
	v_cvt_pk_bf16_f32 v122, v8, v9
	v_lshlrev_b32_e32 v120, 16, v148
	v_and_b32_e32 v121, 0xffff0000, v148
	global_store_dword v116, v122, s[16:17]
	s_add_u32 s16, s16, 0x40000
	s_addc_u32 s17, s17, 0
	v_pk_mul_f32 v[120:121], v[84:85], v[120:121] op_sel_hi:[0,1]
	v_pk_fma_f32 v[8:9], v[8:9], v[20:21], v[120:121] op_sel_hi:[1,0,1]
	s_waitcnt vmcnt(47)
	v_cvt_pk_bf16_f32 v123, v8, v9
	v_lshlrev_b32_e32 v120, 16, v149
	v_and_b32_e32 v121, 0xffff0000, v149
	global_store_dword v116, v123, s[16:17]
	s_add_u32 s16, s16, 0x40000
	s_addc_u32 s17, s17, 0
	v_pk_mul_f32 v[120:121], v[84:85], v[120:121] op_sel:[1,0] op_sel_hi:[1,1]
	v_pk_fma_f32 v[8:9], v[8:9], v[20:21], v[120:121] op_sel:[0,1,0] op_sel_hi:[1,1,1]
	s_waitcnt vmcnt(47)
; DI unsigned pk2(float lo, float hi) { f32x2 v = {lo, hi}; bf16x2_t b = __builtin_convertvector(v, bf16x2_t); return __builtin_bit_cast(unsigned, b); }
; DI float bflo(unsigned u) { return __uint_as_float(u << 16); }
; DI float bfhi(unsigned u) { return __uint_as_float(u & 0xffff0000u); }
; DI void phase_m_comb(int wv, const ArgP a, LAS unsigned char* lds, int dry) {
;     ...
;             for (int c = 0; c < 256; c += 64) { unsigned d[64];
; #pragma unroll
;                 for (int k = 0; k < 64; ++k) d[k] = p[(size_t)(c + k) * 65536];
; #pragma unroll
;                 for (int k = 0; k < 64; ++k) { if (!dry) p[(size_t)(c + k) * 65536] = pk2(C0, C1); const float a_ = ga[(c + k) * 4 + h], b_ = gb[(c + k) * 4 + h]; C0 = a_ * C0 + b_ * bflo(d[k]); C1 = a_ * C1 + b_ * bfhi(d[k]); } }
	v_cvt_pk_bf16_f32 v122, v8, v9
	v_lshlrev_b32_e32 v120, 16, v150
	v_and_b32_e32 v121, 0xffff0000, v150
	global_store_dword v116, v122, s[16:17]
	s_add_u32 s16, s16, 0x40000
	s_addc_u32 s17, s17, 0
	v_pk_mul_f32 v[120:121], v[86:87], v[120:121] op_sel_hi:[0,1]
	v_pk_fma_f32 v[8:9], v[8:9], v[22:23], v[120:121] op_sel_hi:[1,0,1]
	s_waitcnt vmcnt(47)
	v_cvt_pk_bf16_f32 v123, v8, v9
	v_lshlrev_b32_e32 v120, 16, v151
	v_and_b32_e32 v121, 0xffff0000, v151
	global_store_dword v116, v123, s[16:17]
	s_add_u32 s16, s16, 0x40000
	s_addc_u32 s17, s17, 0
	v_pk_mul_f32 v[120:121], v[86:87], v[120:121] op_sel:[1,0] op_sel_hi:[1,1]
	v_pk_fma_f32 v[8:9], v[8:9], v[22:23], v[120:121] op_sel:[0,1,0] op_sel_hi:[1,1,1]
	s_waitcnt vmcnt(47)
	v_cvt_pk_bf16_f32 v122, v8, v9
	v_lshlrev_b32_e32 v120, 16, v152
	v_and_b32_e32 v121, 0xffff0000, v152
	global_store_dword v116, v122, s[16:17]
	s_add_u32 s16, s16, 0x40000
	s_addc_u32 s17, s17, 0
	v_pk_mul_f32 v[120:121], v[88:89], v[120:121] op_sel_hi:[0,1]
	v_pk_fma_f32 v[8:9], v[8:9], v[24:25], v[120:121] op_sel_hi:[1,0,1]
	s_waitcnt vmcnt(47)
	v_cvt_pk_bf16_f32 v123, v8, v9
	v_lshlrev_b32_e32 v120, 16, v153
	v_and_b32_e32 v121, 0xffff0000, v153
	global_store_dword v116, v123, s[16:17]
	s_add_u32 s16, s16, 0x40000
	s_addc_u32 s17, s17, 0
	v_pk_mul_f32 v[120:121], v[88:89], v[120:121] op_sel:[1,0] op_sel_hi:[1,1]
	v_pk_fma_f32 v[8:9], v[8:9], v[24:25], v[120:121] op_sel:[0,1,0] op_sel_hi:[1,1,1]
	s_waitcnt vmcnt(47)
	v_cvt_pk_bf16_f32 v122, v8, v9
	v_lshlrev_b32_e32 v120, 16, v154
	v_and_b32_e32 v121, 0xffff0000, v154
	global_store_dword v116, v122, s[16:17]
	s_add_u32 s16, s16, 0x40000
	s_addc_u32 s17, s17, 0
	v_pk_mul_f32 v[120:121], v[90:91], v[120:121] op_sel_hi:[0,1]
	v_pk_fma_f32 v[8:9], v[8:9], v[26:27], v[120:121] op_sel_hi:[1,0,1]
	s_waitcnt vmcnt(47)
	v_cvt_pk_bf16_f32 v123, v8, v9
	v_lshlrev_b32_e32 v120, 16, v155
	v_and_b32_e32 v121, 0xffff0000, v155
	global_store_dword v116, v123, s[16:17]
	s_add_u32 s16, s16, 0x40000
	s_addc_u32 s17, s17, 0
	v_pk_mul_f32 v[120:121], v[90:91], v[120:121] op_sel:[1,0] op_sel_hi:[1,1]
	v_pk_fma_f32 v[8:9], v[8:9], v[26:27], v[120:121] op_sel:[0,1,0] op_sel_hi:[1,1,1]
	global_load_dword v172, v116, s[14:15]
	s_add_u32 s14, s14, 0x40000
	s_addc_u32 s15, s15, 0
	global_load_dword v173, v116, s[14:15]
	s_add_u32 s14, s14, 0x40000
	s_addc_u32 s15, s15, 0
	global_load_dword v174, v116, s[14:15]
	s_add_u32 s14, s14, 0x40000
	s_addc_u32 s15, s15, 0
	global_load_dword v175, v116, s[14:15]
	s_add_u32 s14, s14, 0x40000
	s_addc_u32 s15, s15, 0
	global_load_dword v176, v116, s[14:15]
	s_add_u32 s14, s14, 0x40000
	s_addc_u32 s15, s15, 0
	global_load_dword v177, v116, s[14:15]
	s_add_u32 s14, s14, 0x40000
	s_addc_u32 s15, s15, 0
	global_load_dword v178, v116, s[14:15]
	s_add_u32 s14, s14, 0x40000
	s_addc_u32 s15, s15, 0
	global_load_dword v179, v116, s[14:15]
	s_add_u32 s14, s14, 0x40000
	s_addc_u32 s15, s15, 0
	global_load_dword v180, v116, s[14:15]
	s_add_u32 s14, s14, 0x40000
	s_addc_u32 s15, s15, 0
	global_load_dword v181, v116, s[14:15]
	s_add_u32 s14, s14, 0x40000
	s_addc_u32 s15, s15, 0
	global_load_dword v182, v116, s[14:15]
	s_add_u32 s14, s14, 0x40000
	s_addc_u32 s15, s15, 0
	global_load_dword v183, v116, s[14:15]
	s_add_u32 s14, s14, 0x40000
	s_addc_u32 s15, s15, 0
	global_load_dword v184, v116, s[14:15]
	s_add_u32 s14, s14, 0x40000
	s_addc_u32 s15, s15, 0
	global_load_dword v185, v116, s[14:15]
	s_add_u32 s14, s14, 0x40000
	s_addc_u32 s15, s15, 0
	global_load_dword v186, v116, s[14:15]
	s_add_u32 s14, s14, 0x40000
	s_addc_u32 s15, s15, 0
	global_load_dword v187, v116, s[14:15]
	s_add_u32 s14, s14, 0x40000
	s_addc_u32 s15, s15, 0
	s_waitcnt vmcnt(47)
	v_cvt_pk_bf16_f32 v122, v8, v9
	v_lshlrev_b32_e32 v120, 16, v156
	v_and_b32_e32 v121, 0xffff0000, v156
	global_store_dword v116, v122, s[16:17]
	s_add_u32 s16, s16, 0x40000
	s_addc_u32 s17, s17, 0
	v_pk_mul_f32 v[120:121], v[92:93], v[120:121] op_sel_hi:[0,1]
	v_pk_fma_f32 v[8:9], v[8:9], v[28:29], v[120:121] op_sel_hi:[1,0,1]
	s_waitcnt vmcnt(47)
	v_cvt_pk_bf16_f32 v123, v8, v9
	v_lshlrev_b32_e32 v120, 16, v157
	v_and_b32_e32 v121, 0xffff0000, v157
	global_store_dword v116, v123, s[16:17]
	s_add_u32 s16, s16, 0x40000
	s_addc_u32 s17, s17, 0
	v_pk_mul_f32 v[120:121], v[92:93], v[120:121] op_sel:[1,0] op_sel_hi:[1,1]
	v_pk_fma_f32 v[8:9], v[8:9], v[28:29], v[120:121] op_sel:[0,1,0] op_sel_hi:[1,1,1]
	s_waitcnt vmcnt(47)
	v_cvt_pk_bf16_f32 v122, v8, v9
	v_lshlrev_b32_e32 v120, 16, v158
	v_and_b32_e32 v121, 0xffff0000, v158
	global_store_dword v116, v122, s[16:17]
	s_add_u32 s16, s16, 0x40000
	s_addc_u32 s17, s17, 0
	v_pk_mul_f32 v[120:121], v[94:95], v[120:121] op_sel_hi:[0,1]
	v_pk_fma_f32 v[8:9], v[8:9], v[30:31], v[120:121] op_sel_hi:[1,0,1]
	s_waitcnt vmcnt(47)
	v_cvt_pk_bf16_f32 v123, v8, v9
	v_lshlrev_b32_e32 v120, 16, v159
	v_and_b32_e32 v121, 0xffff0000, v159
	global_store_dword v116, v123, s[16:17]
	s_add_u32 s16, s16, 0x40000
	s_addc_u32 s17, s17, 0
	v_pk_mul_f32 v[120:121], v[94:95], v[120:121] op_sel:[1,0] op_sel_hi:[1,1]
	v_pk_fma_f32 v[8:9], v[8:9], v[30:31], v[120:121] op_sel:[0,1,0] op_sel_hi:[1,1,1]
	s_waitcnt vmcnt(47)
	v_cvt_pk_bf16_f32 v122, v8, v9
	v_lshlrev_b32_e32 v120, 16, v160
	v_and_b32_e32 v121, 0xffff0000, v160
	global_store_dword v116, v122, s[16:17]
	s_add_u32 s16, s16, 0x40000
	s_addc_u32 s17, s17, 0
	v_pk_mul_f32 v[120:121], v[96:97], v[120:121] op_sel_hi:[0,1]
	v_pk_fma_f32 v[8:9], v[8:9], v[32:33], v[120:121] op_sel_hi:[1,0,1]
	s_waitcnt vmcnt(47)
; DI unsigned pk2(float lo, float hi) { f32x2 v = {lo, hi}; bf16x2_t b = __builtin_convertvector(v, bf16x2_t); return __builtin_bit_cast(unsigned, b); }
; DI float bflo(unsigned u) { return __uint_as_float(u << 16); }
; DI float bfhi(unsigned u) { return __uint_as_float(u & 0xffff0000u); }
; DI void phase_m_comb(int wv, const ArgP a, LAS unsigned char* lds, int dry) {
;     ...
;             for (int c = 0; c < 256; c += 64) { unsigned d[64];
; #pragma unroll
;                 for (int k = 0; k < 64; ++k) d[k] = p[(size_t)(c + k) * 65536];
; #pragma unroll
;                 for (int k = 0; k < 64; ++k) { if (!dry) p[(size_t)(c + k) * 65536] = pk2(C0, C1); const float a_ = ga[(c + k) * 4 + h], b_ = gb[(c + k) * 4 + h]; C0 = a_ * C0 + b_ * bflo(d[k]); C1 = a_ * C1 + b_ * bfhi(d[k]); } }
	v_cvt_pk_bf16_f32 v123, v8, v9
	v_lshlrev_b32_e32 v120, 16, v161
	v_and_b32_e32 v121, 0xffff0000, v161
	global_store_dword v116, v123, s[16:17]
	s_add_u32 s16, s16, 0x40000
	s_addc_u32 s17, s17, 0
	v_pk_mul_f32 v[120:121], v[96:97], v[120:121] op_sel:[1,0] op_sel_hi:[1,1]
	v_pk_fma_f32 v[8:9], v[8:9], v[32:33], v[120:121] op_sel:[0,1,0] op_sel_hi:[1,1,1]
	s_waitcnt vmcnt(47)
	v_cvt_pk_bf16_f32 v122, v8, v9
	v_lshlrev_b32_e32 v120, 16, v162
	v_and_b32_e32 v121, 0xffff0000, v162
	global_store_dword v116, v122, s[16:17]
	s_add_u32 s16, s16, 0x40000
	s_addc_u32 s17, s17, 0
	v_pk_mul_f32 v[120:121], v[98:99], v[120:121] op_sel_hi:[0,1]
	v_pk_fma_f32 v[8:9], v[8:9], v[34:35], v[120:121] op_sel_hi:[1,0,1]
	s_waitcnt vmcnt(47)
	v_cvt_pk_bf16_f32 v123, v8, v9
	v_lshlrev_b32_e32 v120, 16, v163
	v_and_b32_e32 v121, 0xffff0000, v163
	global_store_dword v116, v123, s[16:17]
	s_add_u32 s16, s16, 0x40000
	s_addc_u32 s17, s17, 0
	v_pk_mul_f32 v[120:121], v[98:99], v[120:121] op_sel:[1,0] op_sel_hi:[1,1]
	v_pk_fma_f32 v[8:9], v[8:9], v[34:35], v[120:121] op_sel:[0,1,0] op_sel_hi:[1,1,1]
	s_waitcnt vmcnt(47)
	v_cvt_pk_bf16_f32 v122, v8, v9
	v_lshlrev_b32_e32 v120, 16, v164
	v_and_b32_e32 v121, 0xffff0000, v164
	global_store_dword v116, v122, s[16:17]
	s_add_u32 s16, s16, 0x40000
	s_addc_u32 s17, s17, 0
	v_pk_mul_f32 v[120:121], v[100:101], v[120:121] op_sel_hi:[0,1]
	v_pk_fma_f32 v[8:9], v[8:9], v[36:37], v[120:121] op_sel_hi:[1,0,1]
	s_waitcnt vmcnt(47)
	v_cvt_pk_bf16_f32 v123, v8, v9
	v_lshlrev_b32_e32 v120, 16, v165
	v_and_b32_e32 v121, 0xffff0000, v165
	global_store_dword v116, v123, s[16:17]
	s_add_u32 s16, s16, 0x40000
	s_addc_u32 s17, s17, 0
	v_pk_mul_f32 v[120:121], v[100:101], v[120:121] op_sel:[1,0] op_sel_hi:[1,1]
	v_pk_fma_f32 v[8:9], v[8:9], v[36:37], v[120:121] op_sel:[0,1,0] op_sel_hi:[1,1,1]
	s_waitcnt vmcnt(47)
	v_cvt_pk_bf16_f32 v122, v8, v9
	v_lshlrev_b32_e32 v120, 16, v166
	v_and_b32_e32 v121, 0xffff0000, v166
	global_store_dword v116, v122, s[16:17]
	s_add_u32 s16, s16, 0x40000
	s_addc_u32 s17, s17, 0
	v_pk_mul_f32 v[120:121], v[102:103], v[120:121] op_sel_hi:[0,1]
	v_pk_fma_f32 v[8:9], v[8:9], v[38:39], v[120:121] op_sel_hi:[1,0,1]
	s_waitcnt vmcnt(47)
	v_cvt_pk_bf16_f32 v123, v8, v9
	v_lshlrev_b32_e32 v120, 16, v167
	v_and_b32_e32 v121, 0xffff0000, v167
	global_store_dword v116, v123, s[16:17]
	s_add_u32 s16, s16, 0x40000
	s_addc_u32 s17, s17, 0
	v_pk_mul_f32 v[120:121], v[102:103], v[120:121] op_sel:[1,0] op_sel_hi:[1,1]
	v_pk_fma_f32 v[8:9], v[8:9], v[38:39], v[120:121] op_sel:[0,1,0] op_sel_hi:[1,1,1]
	s_waitcnt vmcnt(47)
	v_cvt_pk_bf16_f32 v122, v8, v9
	v_lshlrev_b32_e32 v120, 16, v168
	v_and_b32_e32 v121, 0xffff0000, v168
	global_store_dword v116, v122, s[16:17]
	s_add_u32 s16, s16, 0x40000
	s_addc_u32 s17, s17, 0
	v_pk_mul_f32 v[120:121], v[104:105], v[120:121] op_sel_hi:[0,1]
	v_pk_fma_f32 v[8:9], v[8:9], v[40:41], v[120:121] op_sel_hi:[1,0,1]
	s_waitcnt vmcnt(47)
	v_cvt_pk_bf16_f32 v123, v8, v9
	v_lshlrev_b32_e32 v120, 16, v169
	v_and_b32_e32 v121, 0xffff0000, v169
	global_store_dword v116, v123, s[16:17]
	s_add_u32 s16, s16, 0x40000
	s_addc_u32 s17, s17, 0
	v_pk_mul_f32 v[120:121], v[104:105], v[120:121] op_sel:[1,0] op_sel_hi:[1,1]
	v_pk_fma_f32 v[8:9], v[8:9], v[40:41], v[120:121] op_sel:[0,1,0] op_sel_hi:[1,1,1]
	s_waitcnt vmcnt(47)
	v_cvt_pk_bf16_f32 v122, v8, v9
	v_lshlrev_b32_e32 v120, 16, v170
	v_and_b32_e32 v121, 0xffff0000, v170
	global_store_dword v116, v122, s[16:17]
	s_add_u32 s16, s16, 0x40000
	s_addc_u32 s17, s17, 0
	v_pk_mul_f32 v[120:121], v[106:107], v[120:121] op_sel_hi:[0,1]
	v_pk_fma_f32 v[8:9], v[8:9], v[42:43], v[120:121] op_sel_hi:[1,0,1]
	s_waitcnt vmcnt(47)
	v_cvt_pk_bf16_f32 v123, v8, v9
	v_lshlrev_b32_e32 v120, 16, v171
	v_and_b32_e32 v121, 0xffff0000, v171
	global_store_dword v116, v123, s[16:17]
	s_add_u32 s16, s16, 0x40000
	s_addc_u32 s17, s17, 0
	v_pk_mul_f32 v[120:121], v[106:107], v[120:121] op_sel:[1,0] op_sel_hi:[1,1]
	v_pk_fma_f32 v[8:9], v[8:9], v[42:43], v[120:121] op_sel:[0,1,0] op_sel_hi:[1,1,1]
	global_load_dword v140, v116, s[14:15]
	s_add_u32 s14, s14, 0x40000
	s_addc_u32 s15, s15, 0
	global_load_dword v141, v116, s[14:15]
	s_add_u32 s14, s14, 0x40000
	s_addc_u32 s15, s15, 0
	global_load_dword v142, v116, s[14:15]
	s_add_u32 s14, s14, 0x40000
	s_addc_u32 s15, s15, 0
	global_load_dword v143, v116, s[14:15]
	s_add_u32 s14, s14, 0x40000
	s_addc_u32 s15, s15, 0
	global_load_dword v144, v116, s[14:15]
	s_add_u32 s14, s14, 0x40000
	s_addc_u32 s15, s15, 0
	global_load_dword v145, v116, s[14:15]
	s_add_u32 s14, s14, 0x40000
	s_addc_u32 s15, s15, 0
	global_load_dword v146, v116, s[14:15]
	s_add_u32 s14, s14, 0x40000
	s_addc_u32 s15, s15, 0
	global_load_dword v147, v116, s[14:15]
	s_add_u32 s14, s14, 0x40000
	s_addc_u32 s15, s15, 0
	global_load_dword v148, v116, s[14:15]
	s_add_u32 s14, s14, 0x40000
	s_addc_u32 s15, s15, 0
	global_load_dword v149, v116, s[14:15]
	s_add_u32 s14, s14, 0x40000
	s_addc_u32 s15, s15, 0
	global_load_dword v150, v116, s[14:15]
	s_add_u32 s14, s14, 0x40000
	s_addc_u32 s15, s15, 0
	global_load_dword v151, v116, s[14:15]
	s_add_u32 s14, s14, 0x40000
	s_addc_u32 s15, s15, 0
	global_load_dword v152, v116, s[14:15]
	s_add_u32 s14, s14, 0x40000
	s_addc_u32 s15, s15, 0
	global_load_dword v153, v116, s[14:15]
	s_add_u32 s14, s14, 0x40000
	s_addc_u32 s15, s15, 0
	global_load_dword v154, v116, s[14:15]
	s_add_u32 s14, s14, 0x40000
	s_addc_u32 s15, s15, 0
	global_load_dword v155, v116, s[14:15]
	s_add_u32 s14, s14, 0x40000
	s_addc_u32 s15, s15, 0
	s_waitcnt vmcnt(47)
; DI unsigned pk2(float lo, float hi) { f32x2 v = {lo, hi}; bf16x2_t b = __builtin_convertvector(v, bf16x2_t); return __builtin_bit_cast(unsigned, b); }
; DI float bflo(unsigned u) { return __uint_as_float(u << 16); }
; DI float bfhi(unsigned u) { return __uint_as_float(u & 0xffff0000u); }
; DI void phase_m_comb(int wv, const ArgP a, LAS unsigned char* lds, int dry) {
;     ...
;             for (int c = 0; c < 256; c += 64) { unsigned d[64];
; #pragma unroll
;                 for (int k = 0; k < 64; ++k) d[k] = p[(size_t)(c + k) * 65536];
; #pragma unroll
;                 for (int k = 0; k < 64; ++k) { if (!dry) p[(size_t)(c + k) * 65536] = pk2(C0, C1); const float a_ = ga[(c + k) * 4 + h], b_ = gb[(c + k) * 4 + h]; C0 = a_ * C0 + b_ * bflo(d[k]); C1 = a_ * C1 + b_ * bfhi(d[k]); } }
	v_cvt_pk_bf16_f32 v122, v8, v9
	v_lshlrev_b32_e32 v120, 16, v172
	v_and_b32_e32 v121, 0xffff0000, v172
	global_store_dword v116, v122, s[16:17]
	s_add_u32 s16, s16, 0x40000
	s_addc_u32 s17, s17, 0
	v_pk_mul_f32 v[120:121], v[108:109], v[120:121] op_sel_hi:[0,1]
	v_pk_fma_f32 v[8:9], v[8:9], v[44:45], v[120:121] op_sel_hi:[1,0,1]
	s_waitcnt vmcnt(47)
	v_cvt_pk_bf16_f32 v123, v8, v9
	v_lshlrev_b32_e32 v120, 16, v173
	v_and_b32_e32 v121, 0xffff0000, v173
	global_store_dword v116, v123, s[16:17]
	s_add_u32 s16, s16, 0x40000
	s_addc_u32 s17, s17, 0
	v_pk_mul_f32 v[120:121], v[108:109], v[120:121] op_sel:[1,0] op_sel_hi:[1,1]
	v_pk_fma_f32 v[8:9], v[8:9], v[44:45], v[120:121] op_sel:[0,1,0] op_sel_hi:[1,1,1]
	s_waitcnt vmcnt(47)
	v_cvt_pk_bf16_f32 v122, v8, v9
	v_lshlrev_b32_e32 v120, 16, v174
	v_and_b32_e32 v121, 0xffff0000, v174
	global_store_dword v116, v122, s[16:17]
	s_add_u32 s16, s16, 0x40000
	s_addc_u32 s17, s17, 0
	v_pk_mul_f32 v[120:121], v[110:111], v[120:121] op_sel_hi:[0,1]
	v_pk_fma_f32 v[8:9], v[8:9], v[46:47], v[120:121] op_sel_hi:[1,0,1]
	s_waitcnt vmcnt(47)
	v_cvt_pk_bf16_f32 v123, v8, v9
	v_lshlrev_b32_e32 v120, 16, v175
	v_and_b32_e32 v121, 0xffff0000, v175
	global_store_dword v116, v123, s[16:17]
	s_add_u32 s16, s16, 0x40000
	s_addc_u32 s17, s17, 0
	v_pk_mul_f32 v[120:121], v[110:111], v[120:121] op_sel:[1,0] op_sel_hi:[1,1]
	v_pk_fma_f32 v[8:9], v[8:9], v[46:47], v[120:121] op_sel:[0,1,0] op_sel_hi:[1,1,1]
	s_waitcnt vmcnt(47)
	v_cvt_pk_bf16_f32 v122, v8, v9
	v_lshlrev_b32_e32 v120, 16, v176
	v_and_b32_e32 v121, 0xffff0000, v176
	global_store_dword v116, v122, s[16:17]
	s_add_u32 s16, s16, 0x40000
	s_addc_u32 s17, s17, 0
	v_pk_mul_f32 v[120:121], v[112:113], v[120:121] op_sel_hi:[0,1]
	v_pk_fma_f32 v[8:9], v[8:9], v[48:49], v[120:121] op_sel_hi:[1,0,1]
	s_waitcnt vmcnt(47)
	v_cvt_pk_bf16_f32 v123, v8, v9
	v_lshlrev_b32_e32 v120, 16, v177
	v_and_b32_e32 v121, 0xffff0000, v177
	global_store_dword v116, v123, s[16:17]
	s_add_u32 s16, s16, 0x40000
	s_addc_u32 s17, s17, 0
	v_pk_mul_f32 v[120:121], v[112:113], v[120:121] op_sel:[1,0] op_sel_hi:[1,1]
	v_pk_fma_f32 v[8:9], v[8:9], v[48:49], v[120:121] op_sel:[0,1,0] op_sel_hi:[1,1,1]
	s_waitcnt vmcnt(47)
	v_cvt_pk_bf16_f32 v122, v8, v9
	v_lshlrev_b32_e32 v120, 16, v178
	v_and_b32_e32 v121, 0xffff0000, v178
	global_store_dword v116, v122, s[16:17]
	s_add_u32 s16, s16, 0x40000
	s_addc_u32 s17, s17, 0
	v_pk_mul_f32 v[120:121], v[114:115], v[120:121] op_sel_hi:[0,1]
	v_pk_fma_f32 v[8:9], v[8:9], v[50:51], v[120:121] op_sel_hi:[1,0,1]
	s_waitcnt vmcnt(47)
	v_cvt_pk_bf16_f32 v123, v8, v9
	v_lshlrev_b32_e32 v120, 16, v179
	v_and_b32_e32 v121, 0xffff0000, v179
	global_store_dword v116, v123, s[16:17]
	s_add_u32 s16, s16, 0x40000
	s_addc_u32 s17, s17, 0
	v_pk_mul_f32 v[120:121], v[114:115], v[120:121] op_sel:[1,0] op_sel_hi:[1,1]
	v_pk_fma_f32 v[8:9], v[8:9], v[50:51], v[120:121] op_sel:[0,1,0] op_sel_hi:[1,1,1]
	s_waitcnt vmcnt(47)
	v_cvt_pk_bf16_f32 v122, v8, v9
	v_lshlrev_b32_e32 v120, 16, v180
	v_and_b32_e32 v121, 0xffff0000, v180
	global_store_dword v116, v122, s[16:17]
	s_add_u32 s16, s16, 0x40000
	s_addc_u32 s17, s17, 0
	v_pk_mul_f32 v[120:121], v[208:209], v[120:121] op_sel_hi:[0,1]
	v_pk_fma_f32 v[8:9], v[8:9], v[52:53], v[120:121] op_sel_hi:[1,0,1]
	s_waitcnt vmcnt(47)
	v_cvt_pk_bf16_f32 v123, v8, v9
	v_lshlrev_b32_e32 v120, 16, v181
	v_and_b32_e32 v121, 0xffff0000, v181
	global_store_dword v116, v123, s[16:17]
	s_add_u32 s16, s16, 0x40000
	s_addc_u32 s17, s17, 0
	v_pk_mul_f32 v[120:121], v[208:209], v[120:121] op_sel:[1,0] op_sel_hi:[1,1]
	v_pk_fma_f32 v[8:9], v[8:9], v[52:53], v[120:121] op_sel:[0,1,0] op_sel_hi:[1,1,1]
	s_waitcnt vmcnt(47)
	v_cvt_pk_bf16_f32 v122, v8, v9
	v_lshlrev_b32_e32 v120, 16, v182
	v_and_b32_e32 v121, 0xffff0000, v182
	global_store_dword v116, v122, s[16:17]
	s_add_u32 s16, s16, 0x40000
	s_addc_u32 s17, s17, 0
	v_pk_mul_f32 v[120:121], v[210:211], v[120:121] op_sel_hi:[0,1]
	v_pk_fma_f32 v[8:9], v[8:9], v[54:55], v[120:121] op_sel_hi:[1,0,1]
	s_waitcnt vmcnt(47)
	v_cvt_pk_bf16_f32 v123, v8, v9
	v_lshlrev_b32_e32 v120, 16, v183
	v_and_b32_e32 v121, 0xffff0000, v183
	global_store_dword v116, v123, s[16:17]
	s_add_u32 s16, s16, 0x40000
	s_addc_u32 s17, s17, 0
	v_pk_mul_f32 v[120:121], v[210:211], v[120:121] op_sel:[1,0] op_sel_hi:[1,1]
	v_pk_fma_f32 v[8:9], v[8:9], v[54:55], v[120:121] op_sel:[0,1,0] op_sel_hi:[1,1,1]
	s_waitcnt vmcnt(47)
	v_cvt_pk_bf16_f32 v122, v8, v9
	v_lshlrev_b32_e32 v120, 16, v184
	v_and_b32_e32 v121, 0xffff0000, v184
	global_store_dword v116, v122, s[16:17]
	s_add_u32 s16, s16, 0x40000
	s_addc_u32 s17, s17, 0
	v_pk_mul_f32 v[120:121], v[212:213], v[120:121] op_sel_hi:[0,1]
	v_pk_fma_f32 v[8:9], v[8:9], v[56:57], v[120:121] op_sel_hi:[1,0,1]
	s_waitcnt vmcnt(47)
	v_cvt_pk_bf16_f32 v123, v8, v9
	v_lshlrev_b32_e32 v120, 16, v185
	v_and_b32_e32 v121, 0xffff0000, v185
	global_store_dword v116, v123, s[16:17]
	s_add_u32 s16, s16, 0x40000
	s_addc_u32 s17, s17, 0
	v_pk_mul_f32 v[120:121], v[212:213], v[120:121] op_sel:[1,0] op_sel_hi:[1,1]
	v_pk_fma_f32 v[8:9], v[8:9], v[56:57], v[120:121] op_sel:[0,1,0] op_sel_hi:[1,1,1]
	s_waitcnt vmcnt(47)
	v_cvt_pk_bf16_f32 v122, v8, v9
	v_lshlrev_b32_e32 v120, 16, v186
	v_and_b32_e32 v121, 0xffff0000, v186
	global_store_dword v116, v122, s[16:17]
	s_add_u32 s16, s16, 0x40000
	s_addc_u32 s17, s17, 0
	v_pk_mul_f32 v[120:121], v[214:215], v[120:121] op_sel_hi:[0,1]
	v_pk_fma_f32 v[8:9], v[8:9], v[58:59], v[120:121] op_sel_hi:[1,0,1]
	s_waitcnt vmcnt(47)
; DI unsigned pk2(float lo, float hi) { f32x2 v = {lo, hi}; bf16x2_t b = __builtin_convertvector(v, bf16x2_t); return __builtin_bit_cast(unsigned, b); }
; DI float bflo(unsigned u) { return __uint_as_float(u << 16); }
; DI float bfhi(unsigned u) { return __uint_as_float(u & 0xffff0000u); }
; DI void phase_m_comb(int wv, const ArgP a, LAS unsigned char* lds, int dry) {
;     ...
;             for (int c = 0; c < 256; c += 64) { unsigned d[64];
; #pragma unroll
;                 for (int k = 0; k < 64; ++k) d[k] = p[(size_t)(c + k) * 65536];
; #pragma unroll
;                 for (int k = 0; k < 64; ++k) { if (!dry) p[(size_t)(c + k) * 65536] = pk2(C0, C1); const float a_ = ga[(c + k) * 4 + h], b_ = gb[(c + k) * 4 + h]; C0 = a_ * C0 + b_ * bflo(d[k]); C1 = a_ * C1 + b_ * bfhi(d[k]); } }
	v_cvt_pk_bf16_f32 v123, v8, v9
	v_lshlrev_b32_e32 v120, 16, v187
	v_and_b32_e32 v121, 0xffff0000, v187
	global_store_dword v116, v123, s[16:17]
	s_add_u32 s16, s16, 0x40000
	s_addc_u32 s17, s17, 0
	v_pk_mul_f32 v[120:121], v[214:215], v[120:121] op_sel:[1,0] op_sel_hi:[1,1]
	v_pk_fma_f32 v[8:9], v[8:9], v[58:59], v[120:121] op_sel:[0,1,0] op_sel_hi:[1,1,1]
	s_waitcnt vmcnt(31)
	v_cvt_pk_bf16_f32 v122, v8, v9
	v_lshlrev_b32_e32 v120, 16, v140
	v_and_b32_e32 v121, 0xffff0000, v140
	global_store_dword v116, v122, s[16:17]
	s_add_u32 s16, s16, 0x40000
	s_addc_u32 s17, s17, 0
	v_pk_mul_f32 v[120:121], v[216:217], v[120:121] op_sel_hi:[0,1]
	v_pk_fma_f32 v[8:9], v[8:9], v[60:61], v[120:121] op_sel_hi:[1,0,1]
	s_waitcnt vmcnt(31)
	v_cvt_pk_bf16_f32 v123, v8, v9
	v_lshlrev_b32_e32 v120, 16, v141
	v_and_b32_e32 v121, 0xffff0000, v141
	global_store_dword v116, v123, s[16:17]
	s_add_u32 s16, s16, 0x40000
	s_addc_u32 s17, s17, 0
	v_pk_mul_f32 v[120:121], v[216:217], v[120:121] op_sel:[1,0] op_sel_hi:[1,1]
	v_pk_fma_f32 v[8:9], v[8:9], v[60:61], v[120:121] op_sel:[0,1,0] op_sel_hi:[1,1,1]
	s_waitcnt vmcnt(31)
	v_cvt_pk_bf16_f32 v122, v8, v9
	v_lshlrev_b32_e32 v120, 16, v142
	v_and_b32_e32 v121, 0xffff0000, v142
	global_store_dword v116, v122, s[16:17]
	s_add_u32 s16, s16, 0x40000
	s_addc_u32 s17, s17, 0
	v_pk_mul_f32 v[120:121], v[218:219], v[120:121] op_sel_hi:[0,1]
	v_pk_fma_f32 v[8:9], v[8:9], v[62:63], v[120:121] op_sel_hi:[1,0,1]
	s_waitcnt vmcnt(31)
	v_cvt_pk_bf16_f32 v123, v8, v9
	v_lshlrev_b32_e32 v120, 16, v143
	v_and_b32_e32 v121, 0xffff0000, v143
	global_store_dword v116, v123, s[16:17]
	s_add_u32 s16, s16, 0x40000
	s_addc_u32 s17, s17, 0
	v_pk_mul_f32 v[120:121], v[218:219], v[120:121] op_sel:[1,0] op_sel_hi:[1,1]
	v_pk_fma_f32 v[8:9], v[8:9], v[62:63], v[120:121] op_sel:[0,1,0] op_sel_hi:[1,1,1]
	s_waitcnt vmcnt(31)
	v_cvt_pk_bf16_f32 v122, v8, v9
	v_lshlrev_b32_e32 v120, 16, v144
	v_and_b32_e32 v121, 0xffff0000, v144
	global_store_dword v116, v122, s[16:17]
	s_add_u32 s16, s16, 0x40000
	s_addc_u32 s17, s17, 0
	v_pk_mul_f32 v[120:121], v[220:221], v[120:121] op_sel_hi:[0,1]
	v_pk_fma_f32 v[8:9], v[8:9], v[64:65], v[120:121] op_sel_hi:[1,0,1]
	s_waitcnt vmcnt(31)
	v_cvt_pk_bf16_f32 v123, v8, v9
	v_lshlrev_b32_e32 v120, 16, v145
	v_and_b32_e32 v121, 0xffff0000, v145
	global_store_dword v116, v123, s[16:17]
	s_add_u32 s16, s16, 0x40000
	s_addc_u32 s17, s17, 0
	v_pk_mul_f32 v[120:121], v[220:221], v[120:121] op_sel:[1,0] op_sel_hi:[1,1]
	v_pk_fma_f32 v[8:9], v[8:9], v[64:65], v[120:121] op_sel:[0,1,0] op_sel_hi:[1,1,1]
	s_waitcnt vmcnt(31)
	v_cvt_pk_bf16_f32 v122, v8, v9
	v_lshlrev_b32_e32 v120, 16, v146
	v_and_b32_e32 v121, 0xffff0000, v146
	global_store_dword v116, v122, s[16:17]
	s_add_u32 s16, s16, 0x40000
	s_addc_u32 s17, s17, 0
	v_pk_mul_f32 v[120:121], v[222:223], v[120:121] op_sel_hi:[0,1]
	v_pk_fma_f32 v[8:9], v[8:9], v[66:67], v[120:121] op_sel_hi:[1,0,1]
	s_waitcnt vmcnt(31)
	v_cvt_pk_bf16_f32 v123, v8, v9
	v_lshlrev_b32_e32 v120, 16, v147
	v_and_b32_e32 v121, 0xffff0000, v147
	global_store_dword v116, v123, s[16:17]
	s_add_u32 s16, s16, 0x40000
	s_addc_u32 s17, s17, 0
	v_pk_mul_f32 v[120:121], v[222:223], v[120:121] op_sel:[1,0] op_sel_hi:[1,1]
	v_pk_fma_f32 v[8:9], v[8:9], v[66:67], v[120:121] op_sel:[0,1,0] op_sel_hi:[1,1,1]
	s_waitcnt vmcnt(31)
	v_cvt_pk_bf16_f32 v122, v8, v9
	v_lshlrev_b32_e32 v120, 16, v148
	v_and_b32_e32 v121, 0xffff0000, v148
	global_store_dword v116, v122, s[16:17]
	s_add_u32 s16, s16, 0x40000
	s_addc_u32 s17, s17, 0
	v_pk_mul_f32 v[120:121], v[224:225], v[120:121] op_sel_hi:[0,1]
	v_pk_fma_f32 v[8:9], v[8:9], v[68:69], v[120:121] op_sel_hi:[1,0,1]
	s_waitcnt vmcnt(31)
	v_cvt_pk_bf16_f32 v123, v8, v9
	v_lshlrev_b32_e32 v120, 16, v149
	v_and_b32_e32 v121, 0xffff0000, v149
	global_store_dword v116, v123, s[16:17]
	s_add_u32 s16, s16, 0x40000
	s_addc_u32 s17, s17, 0
	v_pk_mul_f32 v[120:121], v[224:225], v[120:121] op_sel:[1,0] op_sel_hi:[1,1]
	v_pk_fma_f32 v[8:9], v[8:9], v[68:69], v[120:121] op_sel:[0,1,0] op_sel_hi:[1,1,1]
	s_waitcnt vmcnt(31)
	v_cvt_pk_bf16_f32 v122, v8, v9
	v_lshlrev_b32_e32 v120, 16, v150
	v_and_b32_e32 v121, 0xffff0000, v150
	global_store_dword v116, v122, s[16:17]
	s_add_u32 s16, s16, 0x40000
	s_addc_u32 s17, s17, 0
	v_pk_mul_f32 v[120:121], v[226:227], v[120:121] op_sel_hi:[0,1]
	v_pk_fma_f32 v[8:9], v[8:9], v[70:71], v[120:121] op_sel_hi:[1,0,1]
	s_waitcnt vmcnt(31)
	v_cvt_pk_bf16_f32 v123, v8, v9
	v_lshlrev_b32_e32 v120, 16, v151
	v_and_b32_e32 v121, 0xffff0000, v151
	global_store_dword v116, v123, s[16:17]
	s_add_u32 s16, s16, 0x40000
	s_addc_u32 s17, s17, 0
	v_pk_mul_f32 v[120:121], v[226:227], v[120:121] op_sel:[1,0] op_sel_hi:[1,1]
	v_pk_fma_f32 v[8:9], v[8:9], v[70:71], v[120:121] op_sel:[0,1,0] op_sel_hi:[1,1,1]
	s_waitcnt vmcnt(31)
	v_cvt_pk_bf16_f32 v122, v8, v9
	v_lshlrev_b32_e32 v120, 16, v152
	v_and_b32_e32 v121, 0xffff0000, v152
	global_store_dword v116, v122, s[16:17]
	s_add_u32 s16, s16, 0x40000
	s_addc_u32 s17, s17, 0
	v_pk_mul_f32 v[120:121], v[228:229], v[120:121] op_sel_hi:[0,1]
	v_pk_fma_f32 v[8:9], v[8:9], v[72:73], v[120:121] op_sel_hi:[1,0,1]
	s_waitcnt vmcnt(31)
	v_cvt_pk_bf16_f32 v123, v8, v9
	v_lshlrev_b32_e32 v120, 16, v153
	v_and_b32_e32 v121, 0xffff0000, v153
	global_store_dword v116, v123, s[16:17]
	s_add_u32 s16, s16, 0x40000
	s_addc_u32 s17, s17, 0
	v_pk_mul_f32 v[120:121], v[228:229], v[120:121] op_sel:[1,0] op_sel_hi:[1,1]
	v_pk_fma_f32 v[8:9], v[8:9], v[72:73], v[120:121] op_sel:[0,1,0] op_sel_hi:[1,1,1]
	s_waitcnt vmcnt(31)
	v_cvt_pk_bf16_f32 v122, v8, v9
	v_lshlrev_b32_e32 v120, 16, v154
	v_and_b32_e32 v121, 0xffff0000, v154
	global_store_dword v116, v122, s[16:17]
	s_add_u32 s16, s16, 0x40000
	s_addc_u32 s17, s17, 0
	v_pk_mul_f32 v[120:121], v[230:231], v[120:121] op_sel_hi:[0,1]
	v_pk_fma_f32 v[8:9], v[8:9], v[74:75], v[120:121] op_sel_hi:[1,0,1]
	s_waitcnt vmcnt(31)
	v_cvt_pk_bf16_f32 v123, v8, v9
	v_lshlrev_b32_e32 v120, 16, v155
	v_and_b32_e32 v121, 0xffff0000, v155
	global_store_dword v116, v123, s[16:17]
	s_add_u32 s16, s16, 0x40000
	s_addc_u32 s17, s17, 0
	v_pk_mul_f32 v[120:121], v[230:231], v[120:121] op_sel:[1,0] op_sel_hi:[1,1]
	v_pk_fma_f32 v[8:9], v[8:9], v[74:75], v[120:121] op_sel:[0,1,0] op_sel_hi:[1,1,1]
	s_mov_b64 s[0:1], 0
